# plus redundant post-barrier lgkmcnt(0) removed in GEMM MMA blocks
# baseline (speedup 1.0000x reference)
.LBB0_49:
	ds_read_b128 v[152:155], v148
	ds_read_b128 v[156:159], v148 offset:1024
	ds_read_b128 v[160:163], v148 offset:2048
	ds_read_b128 v[164:167], v148 offset:3072
	ds_read_b128 v[168:171], v149
	ds_read_b128 v[172:175], v149 offset:1024
	ds_read_b128 v[176:179], v149 offset:2048
	ds_read_b128 v[180:183], v149 offset:3072
	s_add_u32 s33, s34, 0xfff80080
	s_addc_u32 s36, s35, -1
	s_cmp_eq_u32 s58, 28
	s_cselect_b32 s39, s17, s36
	s_cselect_b32 s38, s54, s33
	s_cselect_b32 s37, s15, s57
	s_cselect_b32 s36, s55, s56
	v_lshl_add_u64 v[216:217], s[34:35], 0, v[138:139]
	s_add_i32 m0, s31, 0xc000
	ds_read_b128 v[184:187], v150
	ds_read_b128 v[188:191], v150 offset:1024
	ds_read_b128 v[192:195], v150 offset:2048
	ds_read_b128 v[196:199], v150 offset:3072
	ds_read_b128 v[200:203], v150 offset:4096
	ds_read_b128 v[204:207], v150 offset:5120
	ds_read_b128 v[208:211], v150 offset:6144
	ds_read_b128 v[212:215], v150 offset:7168
	global_load_lds_dwordx4 v[216:217], off
	v_lshl_add_u64 v[216:217], s[34:35], 0, v[140:141]
	s_add_i32 m0, s31, 0xe000
	s_nop 0
	global_load_lds_dwordx4 v[216:217], off
	s_waitcnt vmcnt(8)
	s_waitcnt lgkmcnt(0)
	s_barrier
	v_mfma_f32_16x16x32_bf16 v[124:127], v[152:155], v[184:187], v[124:127]
	v_mfma_f32_16x16x32_bf16 v[120:123], v[160:163], v[184:187], v[120:123]
	v_mfma_f32_16x16x32_bf16 v[108:111], v[152:155], v[192:195], v[108:111]
	v_mfma_f32_16x16x32_bf16 v[104:107], v[160:163], v[192:195], v[104:107]
	v_mfma_f32_16x16x32_bf16 v[92:95], v[152:155], v[200:203], v[92:95]
	v_mfma_f32_16x16x32_bf16 v[88:91], v[160:163], v[200:203], v[88:91]
	v_mfma_f32_16x16x32_bf16 v[76:79], v[152:155], v[208:211], v[76:79]
	v_mfma_f32_16x16x32_bf16 v[72:75], v[160:163], v[208:211], v[72:75]
	v_mfma_f32_16x16x32_bf16 v[124:127], v[156:159], v[188:191], v[124:127]
	v_mfma_f32_16x16x32_bf16 v[120:123], v[164:167], v[188:191], v[120:123]
	v_mfma_f32_16x16x32_bf16 v[108:111], v[156:159], v[196:199], v[108:111]
	v_mfma_f32_16x16x32_bf16 v[104:107], v[164:167], v[196:199], v[104:107]
	v_mfma_f32_16x16x32_bf16 v[92:95], v[156:159], v[204:207], v[92:95]
	v_mfma_f32_16x16x32_bf16 v[88:91], v[164:167], v[204:207], v[88:91]
	v_mfma_f32_16x16x32_bf16 v[76:79], v[156:159], v[212:215], v[76:79]
	v_mfma_f32_16x16x32_bf16 v[72:75], v[164:167], v[212:215], v[72:75]
	v_mfma_f32_16x16x32_bf16 v[116:119], v[168:171], v[184:187], v[116:119]
	v_mfma_f32_16x16x32_bf16 v[112:115], v[176:179], v[184:187], v[112:115]
	v_mfma_f32_16x16x32_bf16 v[100:103], v[168:171], v[192:195], v[100:103]
	v_mfma_f32_16x16x32_bf16 v[96:99], v[176:179], v[192:195], v[96:99]
	v_mfma_f32_16x16x32_bf16 v[84:87], v[168:171], v[200:203], v[84:87]
	v_mfma_f32_16x16x32_bf16 v[80:83], v[176:179], v[200:203], v[80:83]
	v_mfma_f32_16x16x32_bf16 v[68:71], v[168:171], v[208:211], v[68:71]
	v_mfma_f32_16x16x32_bf16 v[64:67], v[176:179], v[208:211], v[64:67]
	v_mfma_f32_16x16x32_bf16 v[116:119], v[172:175], v[188:191], v[116:119]
	v_mfma_f32_16x16x32_bf16 v[112:115], v[180:183], v[188:191], v[112:115]
	v_mfma_f32_16x16x32_bf16 v[100:103], v[172:175], v[196:199], v[100:103]
	v_mfma_f32_16x16x32_bf16 v[96:99], v[180:183], v[196:199], v[96:99]
	v_mfma_f32_16x16x32_bf16 v[84:87], v[172:175], v[204:207], v[84:87]
	v_mfma_f32_16x16x32_bf16 v[80:83], v[180:183], v[204:207], v[80:83]
	v_mfma_f32_16x16x32_bf16 v[68:71], v[172:175], v[212:215], v[68:71]
	v_mfma_f32_16x16x32_bf16 v[64:67], v[180:183], v[212:215], v[64:67]
	s_barrier
	s_add_i32 s33, s50, s40
	v_lshl_add_u64 v[216:217], s[36:37], 0, v[132:133]
	s_mov_b32 m0, s33
	ds_read_b128 v[184:187], v150 offset:16384
	ds_read_b128 v[188:191], v150 offset:17408
	ds_read_b128 v[192:195], v150 offset:18432
	ds_read_b128 v[196:199], v150 offset:19456
	ds_read_b128 v[200:203], v150 offset:20480
	ds_read_b128 v[204:207], v150 offset:21504
	ds_read_b128 v[208:211], v150 offset:22528
	ds_read_b128 v[212:215], v150 offset:23552
	global_load_lds_dwordx4 v[216:217], off
	s_add_i32 m0, s33, 0x2000
	s_add_u32 s60, s36, 0x80000
	v_lshl_add_u64 v[218:219], s[36:37], 0, v[136:137]
	s_addc_u32 s61, s37, 0
	s_add_i32 s33, s51, s40
	global_load_lds_dwordx4 v[218:219], off
	v_lshl_add_u64 v[222:223], s[60:61], 0, v[132:133]
	s_mov_b32 m0, s33
	v_lshl_add_u64 v[224:225], s[38:39], 0, v[134:135]
	global_load_lds_dwordx4 v[222:223], off
	v_lshl_add_u64 v[222:223], s[60:61], 0, v[136:137]
	s_add_i32 m0, s33, 0x2000
	s_nop 0
	global_load_lds_dwordx4 v[222:223], off
	v_lshl_add_u64 v[222:223], s[38:39], 0, v[130:131]
	s_mov_b32 m0, s31
	s_nop 0
	global_load_lds_dwordx4 v[222:223], off
	s_mov_b32 m0, s43
	s_nop 0
	global_load_lds_dwordx4 v[224:225], off
	s_waitcnt vmcnt(8)
	s_waitcnt lgkmcnt(0)
	s_barrier
	v_mfma_f32_16x16x32_bf16 v[60:63], v[152:155], v[184:187], v[60:63]
	v_mfma_f32_16x16x32_bf16 v[56:59], v[160:163], v[184:187], v[56:59]
	v_mfma_f32_16x16x32_bf16 v[44:47], v[152:155], v[192:195], v[44:47]
	v_mfma_f32_16x16x32_bf16 v[40:43], v[160:163], v[192:195], v[40:43]
	v_mfma_f32_16x16x32_bf16 v[28:31], v[152:155], v[200:203], v[28:31]
	v_mfma_f32_16x16x32_bf16 v[24:27], v[160:163], v[200:203], v[24:27]
	v_mfma_f32_16x16x32_bf16 v[12:15], v[152:155], v[208:211], v[12:15]
	v_mfma_f32_16x16x32_bf16 v[8:11], v[160:163], v[208:211], v[8:11]
	v_mfma_f32_16x16x32_bf16 v[60:63], v[156:159], v[188:191], v[60:63]
	v_mfma_f32_16x16x32_bf16 v[56:59], v[164:167], v[188:191], v[56:59]
	v_mfma_f32_16x16x32_bf16 v[44:47], v[156:159], v[196:199], v[44:47]
	v_mfma_f32_16x16x32_bf16 v[40:43], v[164:167], v[196:199], v[40:43]
	v_mfma_f32_16x16x32_bf16 v[28:31], v[156:159], v[204:207], v[28:31]
	v_mfma_f32_16x16x32_bf16 v[24:27], v[164:167], v[204:207], v[24:27]
	v_mfma_f32_16x16x32_bf16 v[12:15], v[156:159], v[212:215], v[12:15]
	v_mfma_f32_16x16x32_bf16 v[8:11], v[164:167], v[212:215], v[8:11]
	v_mfma_f32_16x16x32_bf16 v[52:55], v[168:171], v[184:187], v[52:55]
	v_mfma_f32_16x16x32_bf16 v[48:51], v[176:179], v[184:187], v[48:51]
	v_mfma_f32_16x16x32_bf16 v[36:39], v[168:171], v[192:195], v[36:39]
	v_mfma_f32_16x16x32_bf16 v[32:35], v[176:179], v[192:195], v[32:35]
	v_mfma_f32_16x16x32_bf16 v[20:23], v[168:171], v[200:203], v[20:23]
	v_mfma_f32_16x16x32_bf16 v[16:19], v[176:179], v[200:203], v[16:19]
	v_mfma_f32_16x16x32_bf16 v[4:7], v[168:171], v[208:211], v[4:7]
	v_mfma_f32_16x16x32_bf16 v[0:3], v[176:179], v[208:211], v[0:3]
	v_mfma_f32_16x16x32_bf16 v[52:55], v[172:175], v[188:191], v[52:55]
	v_mfma_f32_16x16x32_bf16 v[48:51], v[180:183], v[188:191], v[48:51]
	v_mfma_f32_16x16x32_bf16 v[36:39], v[172:175], v[196:199], v[36:39]
	v_mfma_f32_16x16x32_bf16 v[32:35], v[180:183], v[196:199], v[32:35]
	v_mfma_f32_16x16x32_bf16 v[20:23], v[172:175], v[204:207], v[20:23]
	v_mfma_f32_16x16x32_bf16 v[16:19], v[180:183], v[204:207], v[16:19]
	v_mfma_f32_16x16x32_bf16 v[4:7], v[172:175], v[212:215], v[4:7]
	v_mfma_f32_16x16x32_bf16 v[0:3], v[180:183], v[212:215], v[0:3]
	s_barrier
	s_add_i32 s33, 0, 0x18000
	v_add_u32_e32 v151, s33, v146
	s_add_i32 s59, 0, 0x1c000
	ds_read_b128 v[152:155], v151
	ds_read_b128 v[156:159], v151 offset:1024
	ds_read_b128 v[160:163], v151 offset:2048
	ds_read_b128 v[164:167], v151 offset:3072
	v_add_u32_e32 v151, s59, v146
	ds_read_b128 v[168:171], v151
	ds_read_b128 v[172:175], v151 offset:1024
	ds_read_b128 v[176:179], v151 offset:2048
	ds_read_b128 v[180:183], v151 offset:3072
	s_add_u32 s38, s38, 0x80000
	s_addc_u32 s39, s39, 0
	s_mov_b32 m0, s44
	v_lshl_add_u64 v[226:227], s[38:39], 0, v[130:131]
	ds_read_b128 v[184:187], v150 offset:32768
	ds_read_b128 v[188:191], v150 offset:33792
	ds_read_b128 v[192:195], v150 offset:34816
	ds_read_b128 v[196:199], v150 offset:35840
	ds_read_b128 v[200:203], v150 offset:36864
	ds_read_b128 v[204:207], v150 offset:37888
	ds_read_b128 v[208:211], v150 offset:38912
	ds_read_b128 v[212:215], v150 offset:39936
	global_load_lds_dwordx4 v[226:227], off
	v_lshl_add_u64 v[226:227], s[38:39], 0, v[134:135]
	s_mov_b32 m0, s45
	s_nop 0
	global_load_lds_dwordx4 v[226:227], off
	s_waitcnt vmcnt(8)
	s_waitcnt lgkmcnt(0)
	s_barrier
	v_mfma_f32_16x16x32_bf16 v[124:127], v[152:155], v[184:187], v[124:127]
	v_mfma_f32_16x16x32_bf16 v[120:123], v[160:163], v[184:187], v[120:123]
	v_mfma_f32_16x16x32_bf16 v[108:111], v[152:155], v[192:195], v[108:111]
	v_mfma_f32_16x16x32_bf16 v[104:107], v[160:163], v[192:195], v[104:107]
	v_mfma_f32_16x16x32_bf16 v[92:95], v[152:155], v[200:203], v[92:95]
	v_mfma_f32_16x16x32_bf16 v[88:91], v[160:163], v[200:203], v[88:91]
	v_mfma_f32_16x16x32_bf16 v[76:79], v[152:155], v[208:211], v[76:79]
	v_mfma_f32_16x16x32_bf16 v[72:75], v[160:163], v[208:211], v[72:75]
	v_mfma_f32_16x16x32_bf16 v[124:127], v[156:159], v[188:191], v[124:127]
	v_mfma_f32_16x16x32_bf16 v[120:123], v[164:167], v[188:191], v[120:123]
	v_mfma_f32_16x16x32_bf16 v[108:111], v[156:159], v[196:199], v[108:111]
	v_mfma_f32_16x16x32_bf16 v[104:107], v[164:167], v[196:199], v[104:107]
	v_mfma_f32_16x16x32_bf16 v[92:95], v[156:159], v[204:207], v[92:95]
	v_mfma_f32_16x16x32_bf16 v[88:91], v[164:167], v[204:207], v[88:91]
	v_mfma_f32_16x16x32_bf16 v[76:79], v[156:159], v[212:215], v[76:79]
	v_mfma_f32_16x16x32_bf16 v[72:75], v[164:167], v[212:215], v[72:75]
	v_mfma_f32_16x16x32_bf16 v[116:119], v[168:171], v[184:187], v[116:119]
	v_mfma_f32_16x16x32_bf16 v[112:115], v[176:179], v[184:187], v[112:115]
	v_mfma_f32_16x16x32_bf16 v[100:103], v[168:171], v[192:195], v[100:103]
	v_mfma_f32_16x16x32_bf16 v[96:99], v[176:179], v[192:195], v[96:99]
	v_mfma_f32_16x16x32_bf16 v[84:87], v[168:171], v[200:203], v[84:87]
	v_mfma_f32_16x16x32_bf16 v[80:83], v[176:179], v[200:203], v[80:83]
	v_mfma_f32_16x16x32_bf16 v[68:71], v[168:171], v[208:211], v[68:71]
	v_mfma_f32_16x16x32_bf16 v[64:67], v[176:179], v[208:211], v[64:67]
	v_mfma_f32_16x16x32_bf16 v[116:119], v[172:175], v[188:191], v[116:119]
	v_mfma_f32_16x16x32_bf16 v[112:115], v[180:183], v[188:191], v[112:115]
	v_mfma_f32_16x16x32_bf16 v[100:103], v[172:175], v[196:199], v[100:103]
	v_mfma_f32_16x16x32_bf16 v[96:99], v[180:183], v[196:199], v[96:99]
	v_mfma_f32_16x16x32_bf16 v[84:87], v[172:175], v[204:207], v[84:87]
	v_mfma_f32_16x16x32_bf16 v[80:83], v[180:183], v[204:207], v[80:83]
	v_mfma_f32_16x16x32_bf16 v[68:71], v[172:175], v[212:215], v[68:71]
	v_mfma_f32_16x16x32_bf16 v[64:67], v[180:183], v[212:215], v[64:67]
	s_barrier
	s_add_i32 s33, s33, s40
	v_lshl_add_u64 v[216:217], v[216:217], 0, s[8:9]
	s_mov_b32 m0, s33
	ds_read_b128 v[184:187], v150 offset:49152
	ds_read_b128 v[188:191], v150 offset:50176
	ds_read_b128 v[192:195], v150 offset:51200
	ds_read_b128 v[196:199], v150 offset:52224
	ds_read_b128 v[200:203], v150 offset:53248
	ds_read_b128 v[204:207], v150 offset:54272
	ds_read_b128 v[208:211], v150 offset:55296
	ds_read_b128 v[212:215], v150 offset:56320
	global_load_lds_dwordx4 v[216:217], off
	s_add_i32 m0, s33, 0x2000
	s_add_u32 s36, s36, 0x80080
	v_lshl_add_u64 v[216:217], v[218:219], 0, s[8:9]
	s_addc_u32 s37, s37, 0
	s_add_i32 s33, s59, s40
	global_load_lds_dwordx4 v[216:217], off
	v_lshl_add_u64 v[216:217], s[36:37], 0, v[132:133]
	s_mov_b32 m0, s33
	s_nop 0
	global_load_lds_dwordx4 v[216:217], off
	v_lshl_add_u64 v[216:217], s[36:37], 0, v[136:137]
	s_add_i32 m0, s33, 0x2000
	s_nop 0
	global_load_lds_dwordx4 v[216:217], off
	v_lshl_add_u64 v[216:217], v[222:223], 0, s[8:9]
	s_mov_b32 m0, s48
	s_nop 0
	global_load_lds_dwordx4 v[216:217], off
	v_lshl_add_u64 v[216:217], v[224:225], 0, s[8:9]
	s_mov_b32 m0, s49
	s_nop 0
	global_load_lds_dwordx4 v[216:217], off
	s_waitcnt vmcnt(8)
	s_waitcnt lgkmcnt(0)
	s_barrier
	v_mfma_f32_16x16x32_bf16 v[60:63], v[152:155], v[184:187], v[60:63]
	v_mfma_f32_16x16x32_bf16 v[56:59], v[160:163], v[184:187], v[56:59]
	v_mfma_f32_16x16x32_bf16 v[44:47], v[152:155], v[192:195], v[44:47]
	v_mfma_f32_16x16x32_bf16 v[40:43], v[160:163], v[192:195], v[40:43]
	v_mfma_f32_16x16x32_bf16 v[28:31], v[152:155], v[200:203], v[28:31]
	v_mfma_f32_16x16x32_bf16 v[24:27], v[160:163], v[200:203], v[24:27]
	v_mfma_f32_16x16x32_bf16 v[12:15], v[152:155], v[208:211], v[12:15]
	v_mfma_f32_16x16x32_bf16 v[8:11], v[160:163], v[208:211], v[8:11]
	v_mfma_f32_16x16x32_bf16 v[60:63], v[156:159], v[188:191], v[60:63]
	v_mfma_f32_16x16x32_bf16 v[56:59], v[164:167], v[188:191], v[56:59]
	v_mfma_f32_16x16x32_bf16 v[44:47], v[156:159], v[196:199], v[44:47]
	v_mfma_f32_16x16x32_bf16 v[40:43], v[164:167], v[196:199], v[40:43]
	v_mfma_f32_16x16x32_bf16 v[28:31], v[156:159], v[204:207], v[28:31]
	v_mfma_f32_16x16x32_bf16 v[24:27], v[164:167], v[204:207], v[24:27]
	v_mfma_f32_16x16x32_bf16 v[12:15], v[156:159], v[212:215], v[12:15]
	v_mfma_f32_16x16x32_bf16 v[8:11], v[164:167], v[212:215], v[8:11]
	v_mfma_f32_16x16x32_bf16 v[52:55], v[168:171], v[184:187], v[52:55]
	v_mfma_f32_16x16x32_bf16 v[48:51], v[176:179], v[184:187], v[48:51]
	v_mfma_f32_16x16x32_bf16 v[36:39], v[168:171], v[192:195], v[36:39]
	v_mfma_f32_16x16x32_bf16 v[32:35], v[176:179], v[192:195], v[32:35]
	v_mfma_f32_16x16x32_bf16 v[20:23], v[168:171], v[200:203], v[20:23]
	v_mfma_f32_16x16x32_bf16 v[16:19], v[176:179], v[200:203], v[16:19]
	v_mfma_f32_16x16x32_bf16 v[4:7], v[168:171], v[208:211], v[4:7]
	v_mfma_f32_16x16x32_bf16 v[0:3], v[176:179], v[208:211], v[0:3]
	v_mfma_f32_16x16x32_bf16 v[52:55], v[172:175], v[188:191], v[52:55]
	v_mfma_f32_16x16x32_bf16 v[48:51], v[180:183], v[188:191], v[48:51]
	v_mfma_f32_16x16x32_bf16 v[36:39], v[172:175], v[196:199], v[36:39]
	v_mfma_f32_16x16x32_bf16 v[32:35], v[180:183], v[196:199], v[32:35]
	v_mfma_f32_16x16x32_bf16 v[20:23], v[172:175], v[204:207], v[20:23]
	v_mfma_f32_16x16x32_bf16 v[16:19], v[180:183], v[204:207], v[16:19]
	v_mfma_f32_16x16x32_bf16 v[4:7], v[172:175], v[212:215], v[4:7]
	v_mfma_f32_16x16x32_bf16 v[0:3], v[180:183], v[212:215], v[0:3]
	s_barrier
	s_add_i32 s58, s58, 2
	s_add_u32 s34, s34, 0x100
	s_addc_u32 s35, s35, 0
	s_add_u32 s56, s56, 0x100
	s_addc_u32 s57, s57, 0
	s_cmp_gt_u32 s58, 29
	s_cbranch_scc0 .LBB0_49
	s_and_b64 vcc, exec, s[10:11]
	s_cbranch_vccz .LBB0_52
	s_barrier

.LBB0_111:
	ds_read_b128 v[140:143], v149
	ds_read_b128 v[152:155], v149 offset:1024
	ds_read_b128 v[156:159], v149 offset:2048
	ds_read_b128 v[160:163], v149 offset:3072
	ds_read_b128 v[164:167], v150
	ds_read_b128 v[168:171], v150 offset:1024
	ds_read_b128 v[172:175], v150 offset:2048
	ds_read_b128 v[176:179], v150 offset:3072
	s_add_u32 s28, s24, 0xffea0080
	s_addc_u32 s29, s25, -1
	s_cmpk_eq_i32 s52, 0x54
	s_cselect_b32 s31, s3, s29
	s_cselect_b32 s30, s2, s28
	s_cselect_b32 s29, s19, s51
	s_cselect_b32 s28, s18, s50
	v_lshl_add_u64 v[144:145], s[24:25], 0, v[132:133]
	s_add_i32 m0, s36, 0xc000
	ds_read_b128 v[180:183], v151
	ds_read_b128 v[184:187], v151 offset:1024
	ds_read_b128 v[188:191], v151 offset:2048
	ds_read_b128 v[192:195], v151 offset:3072
	ds_read_b128 v[196:199], v151 offset:4096
	ds_read_b128 v[200:203], v151 offset:5120
	ds_read_b128 v[204:207], v151 offset:6144
	ds_read_b128 v[208:211], v151 offset:7168
	global_load_lds_dwordx4 v[144:145], off
	v_lshl_add_u64 v[144:145], s[24:25], 0, v[134:135]
	s_add_i32 m0, s36, 0xe000
	s_nop 0
	global_load_lds_dwordx4 v[144:145], off
	s_waitcnt vmcnt(8)
	s_waitcnt lgkmcnt(0)
	s_barrier
	v_mfma_f32_16x16x32_bf16 v[124:127], v[140:143], v[180:183], v[124:127]
	v_mfma_f32_16x16x32_bf16 v[120:123], v[156:159], v[180:183], v[120:123]
	v_mfma_f32_16x16x32_bf16 v[108:111], v[140:143], v[188:191], v[108:111]
	v_mfma_f32_16x16x32_bf16 v[104:107], v[156:159], v[188:191], v[104:107]
	v_mfma_f32_16x16x32_bf16 v[92:95], v[140:143], v[196:199], v[92:95]
	v_mfma_f32_16x16x32_bf16 v[88:91], v[156:159], v[196:199], v[88:91]
	v_mfma_f32_16x16x32_bf16 v[76:79], v[140:143], v[204:207], v[76:79]
	v_mfma_f32_16x16x32_bf16 v[72:75], v[156:159], v[204:207], v[72:75]
	v_mfma_f32_16x16x32_bf16 v[124:127], v[152:155], v[184:187], v[124:127]
	v_mfma_f32_16x16x32_bf16 v[120:123], v[160:163], v[184:187], v[120:123]
	v_mfma_f32_16x16x32_bf16 v[108:111], v[152:155], v[192:195], v[108:111]
	v_mfma_f32_16x16x32_bf16 v[104:107], v[160:163], v[192:195], v[104:107]
	v_mfma_f32_16x16x32_bf16 v[92:95], v[152:155], v[200:203], v[92:95]
	v_mfma_f32_16x16x32_bf16 v[88:91], v[160:163], v[200:203], v[88:91]
	v_mfma_f32_16x16x32_bf16 v[76:79], v[152:155], v[208:211], v[76:79]
	v_mfma_f32_16x16x32_bf16 v[72:75], v[160:163], v[208:211], v[72:75]
	v_mfma_f32_16x16x32_bf16 v[116:119], v[164:167], v[180:183], v[116:119]
	v_mfma_f32_16x16x32_bf16 v[112:115], v[172:175], v[180:183], v[112:115]
	v_mfma_f32_16x16x32_bf16 v[100:103], v[164:167], v[188:191], v[100:103]
	v_mfma_f32_16x16x32_bf16 v[96:99], v[172:175], v[188:191], v[96:99]
	v_mfma_f32_16x16x32_bf16 v[84:87], v[164:167], v[196:199], v[84:87]
	v_mfma_f32_16x16x32_bf16 v[80:83], v[172:175], v[196:199], v[80:83]
	v_mfma_f32_16x16x32_bf16 v[68:71], v[164:167], v[204:207], v[68:71]
	v_mfma_f32_16x16x32_bf16 v[64:67], v[172:175], v[204:207], v[64:67]
	v_mfma_f32_16x16x32_bf16 v[116:119], v[168:171], v[184:187], v[116:119]
	v_mfma_f32_16x16x32_bf16 v[112:115], v[176:179], v[184:187], v[112:115]
	v_mfma_f32_16x16x32_bf16 v[100:103], v[168:171], v[192:195], v[100:103]
	v_mfma_f32_16x16x32_bf16 v[96:99], v[176:179], v[192:195], v[96:99]
	v_mfma_f32_16x16x32_bf16 v[84:87], v[168:171], v[200:203], v[84:87]
	v_mfma_f32_16x16x32_bf16 v[80:83], v[176:179], v[200:203], v[80:83]
	v_mfma_f32_16x16x32_bf16 v[68:71], v[168:171], v[208:211], v[68:71]
	v_mfma_f32_16x16x32_bf16 v[64:67], v[176:179], v[208:211], v[64:67]
	s_barrier
	s_add_i32 s33, s44, s35
	v_lshl_add_u64 v[144:145], s[28:29], 0, v[128:129]
	s_mov_b32 m0, s33
	ds_read_b128 v[180:183], v151 offset:16384
	ds_read_b128 v[184:187], v151 offset:17408
	ds_read_b128 v[188:191], v151 offset:18432
	ds_read_b128 v[192:195], v151 offset:19456
	ds_read_b128 v[196:199], v151 offset:20480
	ds_read_b128 v[200:203], v151 offset:21504
	ds_read_b128 v[204:207], v151 offset:22528
	ds_read_b128 v[208:211], v151 offset:23552
	global_load_lds_dwordx4 v[144:145], off
	s_add_i32 m0, s33, 0x2000
	s_add_u32 s54, s28, 0x160000
	v_lshl_add_u64 v[212:213], s[28:29], 0, v[130:131]
	s_addc_u32 s55, s29, 0
	s_add_i32 s33, s45, s35
	global_load_lds_dwordx4 v[212:213], off
	v_lshl_add_u64 v[214:215], s[54:55], 0, v[128:129]
	s_mov_b32 m0, s33
	v_lshl_add_u64 v[216:217], s[30:31], 0, v[130:131]
	global_load_lds_dwordx4 v[214:215], off
	v_lshl_add_u64 v[214:215], s[54:55], 0, v[130:131]
	s_add_i32 m0, s33, 0x2000
	s_nop 0
	global_load_lds_dwordx4 v[214:215], off
	v_lshl_add_u64 v[214:215], s[30:31], 0, v[128:129]
	s_mov_b32 m0, s36
	s_nop 0
	global_load_lds_dwordx4 v[214:215], off
	s_mov_b32 m0, s37
	s_nop 0
	global_load_lds_dwordx4 v[216:217], off
	s_waitcnt vmcnt(8)
	s_waitcnt lgkmcnt(0)
	s_barrier
	v_mfma_f32_16x16x32_bf16 v[60:63], v[140:143], v[180:183], v[60:63]
	v_mfma_f32_16x16x32_bf16 v[56:59], v[156:159], v[180:183], v[56:59]
	v_mfma_f32_16x16x32_bf16 v[44:47], v[140:143], v[188:191], v[44:47]
	v_mfma_f32_16x16x32_bf16 v[40:43], v[156:159], v[188:191], v[40:43]
	v_mfma_f32_16x16x32_bf16 v[28:31], v[140:143], v[196:199], v[28:31]
	v_mfma_f32_16x16x32_bf16 v[24:27], v[156:159], v[196:199], v[24:27]
	v_mfma_f32_16x16x32_bf16 v[12:15], v[140:143], v[204:207], v[12:15]
	v_mfma_f32_16x16x32_bf16 v[8:11], v[156:159], v[204:207], v[8:11]
	v_mfma_f32_16x16x32_bf16 v[60:63], v[152:155], v[184:187], v[60:63]
	v_mfma_f32_16x16x32_bf16 v[56:59], v[160:163], v[184:187], v[56:59]
	v_mfma_f32_16x16x32_bf16 v[44:47], v[152:155], v[192:195], v[44:47]
	v_mfma_f32_16x16x32_bf16 v[40:43], v[160:163], v[192:195], v[40:43]
	v_mfma_f32_16x16x32_bf16 v[28:31], v[152:155], v[200:203], v[28:31]
	v_mfma_f32_16x16x32_bf16 v[24:27], v[160:163], v[200:203], v[24:27]
	v_mfma_f32_16x16x32_bf16 v[12:15], v[152:155], v[208:211], v[12:15]
	v_mfma_f32_16x16x32_bf16 v[8:11], v[160:163], v[208:211], v[8:11]
	v_mfma_f32_16x16x32_bf16 v[52:55], v[164:167], v[180:183], v[52:55]
	v_mfma_f32_16x16x32_bf16 v[48:51], v[172:175], v[180:183], v[48:51]
	v_mfma_f32_16x16x32_bf16 v[36:39], v[164:167], v[188:191], v[36:39]
	v_mfma_f32_16x16x32_bf16 v[32:35], v[172:175], v[188:191], v[32:35]
	v_mfma_f32_16x16x32_bf16 v[20:23], v[164:167], v[196:199], v[20:23]
	v_mfma_f32_16x16x32_bf16 v[16:19], v[172:175], v[196:199], v[16:19]
	v_mfma_f32_16x16x32_bf16 v[4:7], v[164:167], v[204:207], v[4:7]
	v_mfma_f32_16x16x32_bf16 v[0:3], v[172:175], v[204:207], v[0:3]
	v_mfma_f32_16x16x32_bf16 v[52:55], v[168:171], v[184:187], v[52:55]
	v_mfma_f32_16x16x32_bf16 v[48:51], v[176:179], v[184:187], v[48:51]
	v_mfma_f32_16x16x32_bf16 v[36:39], v[168:171], v[192:195], v[36:39]
	v_mfma_f32_16x16x32_bf16 v[32:35], v[176:179], v[192:195], v[32:35]
	v_mfma_f32_16x16x32_bf16 v[20:23], v[168:171], v[200:203], v[20:23]
	v_mfma_f32_16x16x32_bf16 v[16:19], v[176:179], v[200:203], v[16:19]
	v_mfma_f32_16x16x32_bf16 v[4:7], v[168:171], v[208:211], v[4:7]
	v_mfma_f32_16x16x32_bf16 v[0:3], v[176:179], v[208:211], v[0:3]
	s_barrier
	s_add_i32 s33, 0, 0x18000
	s_add_i32 s53, 0, 0x1c000
	v_add_u32_e32 v160, s33, v147
	v_add_u32_e32 v176, s53, v147
	ds_read_b128 v[140:143], v160
	ds_read_b128 v[152:155], v160 offset:1024
	ds_read_b128 v[156:159], v160 offset:2048
	ds_read_b128 v[160:163], v160 offset:3072
	ds_read_b128 v[164:167], v176
	ds_read_b128 v[168:171], v176 offset:1024
	ds_read_b128 v[172:175], v176 offset:2048
	ds_read_b128 v[176:179], v176 offset:3072
	s_add_u32 s30, s30, 0x160000
	s_addc_u32 s31, s31, 0
	s_mov_b32 m0, s38
	v_lshl_add_u64 v[218:219], s[30:31], 0, v[128:129]
	ds_read_b128 v[180:183], v151 offset:32768
	ds_read_b128 v[184:187], v151 offset:33792
	ds_read_b128 v[188:191], v151 offset:34816
	ds_read_b128 v[192:195], v151 offset:35840
	ds_read_b128 v[196:199], v151 offset:36864
	ds_read_b128 v[200:203], v151 offset:37888
	ds_read_b128 v[204:207], v151 offset:38912
	ds_read_b128 v[208:211], v151 offset:39936
	global_load_lds_dwordx4 v[218:219], off
	v_lshl_add_u64 v[218:219], s[30:31], 0, v[130:131]
	s_mov_b32 m0, s39
	s_nop 0
	global_load_lds_dwordx4 v[218:219], off
	s_waitcnt vmcnt(8)
	s_waitcnt lgkmcnt(0)
	s_barrier
	v_mfma_f32_16x16x32_bf16 v[124:127], v[140:143], v[180:183], v[124:127]
	v_mfma_f32_16x16x32_bf16 v[120:123], v[156:159], v[180:183], v[120:123]
	v_mfma_f32_16x16x32_bf16 v[108:111], v[140:143], v[188:191], v[108:111]
	v_mfma_f32_16x16x32_bf16 v[104:107], v[156:159], v[188:191], v[104:107]
	v_mfma_f32_16x16x32_bf16 v[92:95], v[140:143], v[196:199], v[92:95]
	v_mfma_f32_16x16x32_bf16 v[88:91], v[156:159], v[196:199], v[88:91]
	v_mfma_f32_16x16x32_bf16 v[76:79], v[140:143], v[204:207], v[76:79]
	v_mfma_f32_16x16x32_bf16 v[72:75], v[156:159], v[204:207], v[72:75]
	v_mfma_f32_16x16x32_bf16 v[124:127], v[152:155], v[184:187], v[124:127]
	v_mfma_f32_16x16x32_bf16 v[120:123], v[160:163], v[184:187], v[120:123]
	v_mfma_f32_16x16x32_bf16 v[108:111], v[152:155], v[192:195], v[108:111]
	v_mfma_f32_16x16x32_bf16 v[104:107], v[160:163], v[192:195], v[104:107]
	v_mfma_f32_16x16x32_bf16 v[92:95], v[152:155], v[200:203], v[92:95]
	v_mfma_f32_16x16x32_bf16 v[88:91], v[160:163], v[200:203], v[88:91]
	v_mfma_f32_16x16x32_bf16 v[76:79], v[152:155], v[208:211], v[76:79]
	v_mfma_f32_16x16x32_bf16 v[72:75], v[160:163], v[208:211], v[72:75]
	v_mfma_f32_16x16x32_bf16 v[116:119], v[164:167], v[180:183], v[116:119]
	v_mfma_f32_16x16x32_bf16 v[112:115], v[172:175], v[180:183], v[112:115]
	v_mfma_f32_16x16x32_bf16 v[100:103], v[164:167], v[188:191], v[100:103]
	v_mfma_f32_16x16x32_bf16 v[96:99], v[172:175], v[188:191], v[96:99]
	v_mfma_f32_16x16x32_bf16 v[84:87], v[164:167], v[196:199], v[84:87]
	v_mfma_f32_16x16x32_bf16 v[80:83], v[172:175], v[196:199], v[80:83]
	v_mfma_f32_16x16x32_bf16 v[68:71], v[164:167], v[204:207], v[68:71]
	v_mfma_f32_16x16x32_bf16 v[64:67], v[172:175], v[204:207], v[64:67]
	v_mfma_f32_16x16x32_bf16 v[116:119], v[168:171], v[184:187], v[116:119]
	v_mfma_f32_16x16x32_bf16 v[112:115], v[176:179], v[184:187], v[112:115]
	v_mfma_f32_16x16x32_bf16 v[100:103], v[168:171], v[192:195], v[100:103]
	v_mfma_f32_16x16x32_bf16 v[96:99], v[176:179], v[192:195], v[96:99]
	v_mfma_f32_16x16x32_bf16 v[84:87], v[168:171], v[200:203], v[84:87]
	v_mfma_f32_16x16x32_bf16 v[80:83], v[176:179], v[200:203], v[80:83]
	v_mfma_f32_16x16x32_bf16 v[68:71], v[168:171], v[208:211], v[68:71]
	v_mfma_f32_16x16x32_bf16 v[64:67], v[176:179], v[208:211], v[64:67]
	s_barrier
	s_add_i32 s30, s33, s35
	v_lshl_add_u64 v[144:145], v[144:145], 0, s[10:11]
	s_mov_b32 m0, s30
	ds_read_b128 v[180:183], v151 offset:49152
	ds_read_b128 v[184:187], v151 offset:50176
	ds_read_b128 v[188:191], v151 offset:51200
	ds_read_b128 v[192:195], v151 offset:52224
	ds_read_b128 v[196:199], v151 offset:53248
	ds_read_b128 v[200:203], v151 offset:54272
	ds_read_b128 v[204:207], v151 offset:55296
	ds_read_b128 v[208:211], v151 offset:56320
	global_load_lds_dwordx4 v[144:145], off
	s_add_i32 m0, s30, 0x2000
	s_add_u32 s28, s28, 0x160080
	v_lshl_add_u64 v[144:145], v[212:213], 0, s[10:11]
	s_addc_u32 s29, s29, 0
	s_add_i32 s30, s53, s35
	global_load_lds_dwordx4 v[144:145], off
	v_lshl_add_u64 v[144:145], s[28:29], 0, v[128:129]
	s_mov_b32 m0, s30
	s_nop 0
	global_load_lds_dwordx4 v[144:145], off
	v_lshl_add_u64 v[144:145], s[28:29], 0, v[130:131]
	s_add_i32 m0, s30, 0x2000
	s_nop 0
	global_load_lds_dwordx4 v[144:145], off
	v_lshl_add_u64 v[144:145], v[214:215], 0, s[10:11]
	s_mov_b32 m0, s41
	s_nop 0
	global_load_lds_dwordx4 v[144:145], off
	v_lshl_add_u64 v[144:145], v[216:217], 0, s[10:11]
	s_mov_b32 m0, s42
	s_nop 0
	global_load_lds_dwordx4 v[144:145], off
	s_waitcnt vmcnt(8)
	s_waitcnt lgkmcnt(0)
	s_barrier
	v_mfma_f32_16x16x32_bf16 v[60:63], v[140:143], v[180:183], v[60:63]
	v_mfma_f32_16x16x32_bf16 v[56:59], v[156:159], v[180:183], v[56:59]
	v_mfma_f32_16x16x32_bf16 v[44:47], v[140:143], v[188:191], v[44:47]
	v_mfma_f32_16x16x32_bf16 v[40:43], v[156:159], v[188:191], v[40:43]
	v_mfma_f32_16x16x32_bf16 v[28:31], v[140:143], v[196:199], v[28:31]
	v_mfma_f32_16x16x32_bf16 v[24:27], v[156:159], v[196:199], v[24:27]
	v_mfma_f32_16x16x32_bf16 v[12:15], v[140:143], v[204:207], v[12:15]
	v_mfma_f32_16x16x32_bf16 v[8:11], v[156:159], v[204:207], v[8:11]
	v_mfma_f32_16x16x32_bf16 v[60:63], v[152:155], v[184:187], v[60:63]
	v_mfma_f32_16x16x32_bf16 v[56:59], v[160:163], v[184:187], v[56:59]
	v_mfma_f32_16x16x32_bf16 v[44:47], v[152:155], v[192:195], v[44:47]
	v_mfma_f32_16x16x32_bf16 v[40:43], v[160:163], v[192:195], v[40:43]
	v_mfma_f32_16x16x32_bf16 v[28:31], v[152:155], v[200:203], v[28:31]
	v_mfma_f32_16x16x32_bf16 v[24:27], v[160:163], v[200:203], v[24:27]
	v_mfma_f32_16x16x32_bf16 v[12:15], v[152:155], v[208:211], v[12:15]
	v_mfma_f32_16x16x32_bf16 v[8:11], v[160:163], v[208:211], v[8:11]
	v_mfma_f32_16x16x32_bf16 v[52:55], v[164:167], v[180:183], v[52:55]
	v_mfma_f32_16x16x32_bf16 v[48:51], v[172:175], v[180:183], v[48:51]
	v_mfma_f32_16x16x32_bf16 v[36:39], v[164:167], v[188:191], v[36:39]
	v_mfma_f32_16x16x32_bf16 v[32:35], v[172:175], v[188:191], v[32:35]
	v_mfma_f32_16x16x32_bf16 v[20:23], v[164:167], v[196:199], v[20:23]
	v_mfma_f32_16x16x32_bf16 v[16:19], v[172:175], v[196:199], v[16:19]
	v_mfma_f32_16x16x32_bf16 v[4:7], v[164:167], v[204:207], v[4:7]
	v_mfma_f32_16x16x32_bf16 v[0:3], v[172:175], v[204:207], v[0:3]
	v_mfma_f32_16x16x32_bf16 v[52:55], v[168:171], v[184:187], v[52:55]
	v_mfma_f32_16x16x32_bf16 v[48:51], v[176:179], v[184:187], v[48:51]
	v_mfma_f32_16x16x32_bf16 v[36:39], v[168:171], v[192:195], v[36:39]
	v_mfma_f32_16x16x32_bf16 v[32:35], v[176:179], v[192:195], v[32:35]
	v_mfma_f32_16x16x32_bf16 v[20:23], v[168:171], v[200:203], v[20:23]
	v_mfma_f32_16x16x32_bf16 v[16:19], v[176:179], v[200:203], v[16:19]
	v_mfma_f32_16x16x32_bf16 v[4:7], v[168:171], v[208:211], v[4:7]
	v_mfma_f32_16x16x32_bf16 v[0:3], v[176:179], v[208:211], v[0:3]
	s_barrier
	s_add_i32 s52, s52, 2
	s_add_u32 s24, s24, 0x100
	s_addc_u32 s25, s25, 0
	s_add_u32 s50, s50, 0x100
	s_addc_u32 s51, s51, 0
	s_cmpk_gt_u32 s52, 0x55
	s_cbranch_scc0 .LBB0_111
	s_and_b64 vcc, exec, s[14:15]
	s_cbranch_vccz .LBB0_114
	s_barrier

.LBB0_139:
	v_add_u32_e32 v147, s49, v145
	ds_read_b128 v[148:151], v147
	ds_read_b128 v[152:155], v147 offset:1024
	ds_read_b128 v[156:159], v147 offset:2048
	ds_read_b128 v[160:163], v147 offset:3072
	v_add_u32_e32 v147, s50, v145
	s_add_u32 s28, s10, s24
	ds_read_b128 v[164:167], v147
	ds_read_b128 v[168:171], v147 offset:1024
	ds_read_b128 v[172:175], v147 offset:2048
	ds_read_b128 v[176:179], v147 offset:3072
	s_addc_u32 s29, s11, s25
	s_add_u32 s28, s28, 0x100
	s_addc_u32 s29, s29, 0
	s_add_u32 s33, s17, s24
	s_addc_u32 s55, s53, s25
	s_cmpk_eq_i32 s24, 0x2b00
	s_cselect_b32 s31, s19, s29
	s_cselect_b32 s30, s18, s28
	s_cselect_b32 s29, s5, s55
	s_cselect_b32 s28, s4, s33
	v_lshl_add_u64 v[212:213], v[140:141], 0, s[24:25]
	s_add_i32 m0, s42, 0xc000
	ds_read_b128 v[180:183], v146
	ds_read_b128 v[184:187], v146 offset:1024
	ds_read_b128 v[188:191], v146 offset:2048
	ds_read_b128 v[192:195], v146 offset:3072
	ds_read_b128 v[196:199], v146 offset:4096
	ds_read_b128 v[200:203], v146 offset:5120
	ds_read_b128 v[204:207], v146 offset:6144
	ds_read_b128 v[208:211], v146 offset:7168
	global_load_lds_dwordx4 v[212:213], off
	v_lshl_add_u64 v[212:213], v[142:143], 0, s[24:25]
	s_add_i32 m0, s42, 0xe000
	s_nop 0
	global_load_lds_dwordx4 v[212:213], off
	s_waitcnt vmcnt(8)
	s_waitcnt lgkmcnt(0)
	s_barrier
	v_mfma_f32_16x16x32_bf16 v[124:127], v[148:151], v[180:183], v[124:127]
	v_mfma_f32_16x16x32_bf16 v[120:123], v[156:159], v[180:183], v[120:123]
	v_mfma_f32_16x16x32_bf16 v[108:111], v[148:151], v[188:191], v[108:111]
	v_mfma_f32_16x16x32_bf16 v[104:107], v[156:159], v[188:191], v[104:107]
	v_mfma_f32_16x16x32_bf16 v[92:95], v[148:151], v[196:199], v[92:95]
	v_mfma_f32_16x16x32_bf16 v[88:91], v[156:159], v[196:199], v[88:91]
	v_mfma_f32_16x16x32_bf16 v[76:79], v[148:151], v[204:207], v[76:79]
	v_mfma_f32_16x16x32_bf16 v[72:75], v[156:159], v[204:207], v[72:75]
	v_mfma_f32_16x16x32_bf16 v[124:127], v[152:155], v[184:187], v[124:127]
	v_mfma_f32_16x16x32_bf16 v[120:123], v[160:163], v[184:187], v[120:123]
	v_mfma_f32_16x16x32_bf16 v[108:111], v[152:155], v[192:195], v[108:111]
	v_mfma_f32_16x16x32_bf16 v[104:107], v[160:163], v[192:195], v[104:107]
	v_mfma_f32_16x16x32_bf16 v[92:95], v[152:155], v[200:203], v[92:95]
	v_mfma_f32_16x16x32_bf16 v[88:91], v[160:163], v[200:203], v[88:91]
	v_mfma_f32_16x16x32_bf16 v[76:79], v[152:155], v[208:211], v[76:79]
	v_mfma_f32_16x16x32_bf16 v[72:75], v[160:163], v[208:211], v[72:75]
	v_mfma_f32_16x16x32_bf16 v[116:119], v[164:167], v[180:183], v[116:119]
	v_mfma_f32_16x16x32_bf16 v[112:115], v[172:175], v[180:183], v[112:115]
	v_mfma_f32_16x16x32_bf16 v[100:103], v[164:167], v[188:191], v[100:103]
	v_mfma_f32_16x16x32_bf16 v[96:99], v[172:175], v[188:191], v[96:99]
	v_mfma_f32_16x16x32_bf16 v[84:87], v[164:167], v[196:199], v[84:87]
	v_mfma_f32_16x16x32_bf16 v[80:83], v[172:175], v[196:199], v[80:83]
	v_mfma_f32_16x16x32_bf16 v[68:71], v[164:167], v[204:207], v[68:71]
	v_mfma_f32_16x16x32_bf16 v[64:67], v[172:175], v[204:207], v[64:67]
	v_mfma_f32_16x16x32_bf16 v[116:119], v[168:171], v[184:187], v[116:119]
	v_mfma_f32_16x16x32_bf16 v[112:115], v[176:179], v[184:187], v[112:115]
	v_mfma_f32_16x16x32_bf16 v[100:103], v[168:171], v[192:195], v[100:103]
	v_mfma_f32_16x16x32_bf16 v[96:99], v[176:179], v[192:195], v[96:99]
	v_mfma_f32_16x16x32_bf16 v[84:87], v[168:171], v[200:203], v[84:87]
	v_mfma_f32_16x16x32_bf16 v[80:83], v[176:179], v[200:203], v[80:83]
	v_mfma_f32_16x16x32_bf16 v[68:71], v[168:171], v[208:211], v[68:71]
	v_mfma_f32_16x16x32_bf16 v[64:67], v[176:179], v[208:211], v[64:67]
	s_barrier
	s_add_i32 s33, s49, s41
	v_lshl_add_u64 v[212:213], s[28:29], 0, v[128:129]
	s_mov_b32 m0, s33
	ds_read_b128 v[180:183], v146 offset:16384
	ds_read_b128 v[184:187], v146 offset:17408
	ds_read_b128 v[188:191], v146 offset:18432
	ds_read_b128 v[192:195], v146 offset:19456
	ds_read_b128 v[196:199], v146 offset:20480
	ds_read_b128 v[200:203], v146 offset:21504
	ds_read_b128 v[204:207], v146 offset:22528
	ds_read_b128 v[208:211], v146 offset:23552
	global_load_lds_dwordx4 v[212:213], off
	s_add_i32 m0, s33, 0x2000
	s_add_u32 s56, s28, 0x160000
	v_lshl_add_u64 v[214:215], s[28:29], 0, v[130:131]
	s_addc_u32 s57, s29, 0
	s_add_i32 s33, s50, s41
	global_load_lds_dwordx4 v[214:215], off
	v_lshl_add_u64 v[216:217], s[56:57], 0, v[128:129]
	s_mov_b32 m0, s33
	v_lshl_add_u64 v[218:219], s[30:31], 0, v[130:131]
	global_load_lds_dwordx4 v[216:217], off
	v_lshl_add_u64 v[216:217], s[56:57], 0, v[130:131]
	s_add_i32 m0, s33, 0x2000
	s_nop 0
	global_load_lds_dwordx4 v[216:217], off
	v_lshl_add_u64 v[216:217], s[30:31], 0, v[128:129]
	s_mov_b32 m0, s42
	s_nop 0
	global_load_lds_dwordx4 v[216:217], off
	s_mov_b32 m0, s43
	s_nop 0
	global_load_lds_dwordx4 v[218:219], off
	s_waitcnt vmcnt(8)
	s_waitcnt lgkmcnt(0)
	s_barrier
	v_mfma_f32_16x16x32_bf16 v[60:63], v[148:151], v[180:183], v[60:63]
	v_mfma_f32_16x16x32_bf16 v[56:59], v[156:159], v[180:183], v[56:59]
	v_mfma_f32_16x16x32_bf16 v[44:47], v[148:151], v[188:191], v[44:47]
	v_mfma_f32_16x16x32_bf16 v[40:43], v[156:159], v[188:191], v[40:43]
	v_mfma_f32_16x16x32_bf16 v[28:31], v[148:151], v[196:199], v[28:31]
	v_mfma_f32_16x16x32_bf16 v[24:27], v[156:159], v[196:199], v[24:27]
	v_mfma_f32_16x16x32_bf16 v[12:15], v[148:151], v[204:207], v[12:15]
	v_mfma_f32_16x16x32_bf16 v[8:11], v[156:159], v[204:207], v[8:11]
	v_mfma_f32_16x16x32_bf16 v[60:63], v[152:155], v[184:187], v[60:63]
	v_mfma_f32_16x16x32_bf16 v[56:59], v[160:163], v[184:187], v[56:59]
	v_mfma_f32_16x16x32_bf16 v[44:47], v[152:155], v[192:195], v[44:47]
	v_mfma_f32_16x16x32_bf16 v[40:43], v[160:163], v[192:195], v[40:43]
	v_mfma_f32_16x16x32_bf16 v[28:31], v[152:155], v[200:203], v[28:31]
	v_mfma_f32_16x16x32_bf16 v[24:27], v[160:163], v[200:203], v[24:27]
	v_mfma_f32_16x16x32_bf16 v[12:15], v[152:155], v[208:211], v[12:15]
	v_mfma_f32_16x16x32_bf16 v[8:11], v[160:163], v[208:211], v[8:11]
	v_mfma_f32_16x16x32_bf16 v[52:55], v[164:167], v[180:183], v[52:55]
	v_mfma_f32_16x16x32_bf16 v[48:51], v[172:175], v[180:183], v[48:51]
	v_mfma_f32_16x16x32_bf16 v[36:39], v[164:167], v[188:191], v[36:39]
	v_mfma_f32_16x16x32_bf16 v[32:35], v[172:175], v[188:191], v[32:35]
	v_mfma_f32_16x16x32_bf16 v[20:23], v[164:167], v[196:199], v[20:23]
	v_mfma_f32_16x16x32_bf16 v[16:19], v[172:175], v[196:199], v[16:19]
	v_mfma_f32_16x16x32_bf16 v[4:7], v[164:167], v[204:207], v[4:7]
	v_mfma_f32_16x16x32_bf16 v[0:3], v[172:175], v[204:207], v[0:3]
	v_mfma_f32_16x16x32_bf16 v[52:55], v[168:171], v[184:187], v[52:55]
	v_mfma_f32_16x16x32_bf16 v[48:51], v[176:179], v[184:187], v[48:51]
	v_mfma_f32_16x16x32_bf16 v[36:39], v[168:171], v[192:195], v[36:39]
	v_mfma_f32_16x16x32_bf16 v[32:35], v[176:179], v[192:195], v[32:35]
	v_mfma_f32_16x16x32_bf16 v[20:23], v[168:171], v[200:203], v[20:23]
	v_mfma_f32_16x16x32_bf16 v[16:19], v[176:179], v[200:203], v[16:19]
	v_mfma_f32_16x16x32_bf16 v[4:7], v[168:171], v[208:211], v[4:7]
	v_mfma_f32_16x16x32_bf16 v[0:3], v[176:179], v[208:211], v[0:3]
	s_barrier
	s_add_i32 s33, 0, 0x18000
	v_add_u32_e32 v147, s33, v145
	s_add_i32 s55, 0, 0x1c000
	ds_read_b128 v[148:151], v147
	ds_read_b128 v[152:155], v147 offset:1024
	ds_read_b128 v[156:159], v147 offset:2048
	ds_read_b128 v[160:163], v147 offset:3072
	v_add_u32_e32 v147, s55, v145
	ds_read_b128 v[164:167], v147
	ds_read_b128 v[168:171], v147 offset:1024
	ds_read_b128 v[172:175], v147 offset:2048
	ds_read_b128 v[176:179], v147 offset:3072
	s_add_u32 s30, s30, 0x160000
	s_addc_u32 s31, s31, 0
	s_mov_b32 m0, s44
	v_lshl_add_u64 v[224:225], s[30:31], 0, v[128:129]
	ds_read_b128 v[180:183], v146 offset:32768
	ds_read_b128 v[184:187], v146 offset:33792
	ds_read_b128 v[188:191], v146 offset:34816
	ds_read_b128 v[192:195], v146 offset:35840
	ds_read_b128 v[196:199], v146 offset:36864
	ds_read_b128 v[200:203], v146 offset:37888
	ds_read_b128 v[204:207], v146 offset:38912
	ds_read_b128 v[208:211], v146 offset:39936
	global_load_lds_dwordx4 v[224:225], off
	v_lshl_add_u64 v[224:225], s[30:31], 0, v[130:131]
	s_mov_b32 m0, s45
	s_nop 0
	global_load_lds_dwordx4 v[224:225], off
	s_waitcnt vmcnt(8)
	s_waitcnt lgkmcnt(0)
	s_barrier
	v_mfma_f32_16x16x32_bf16 v[124:127], v[148:151], v[180:183], v[124:127]
	v_mfma_f32_16x16x32_bf16 v[120:123], v[156:159], v[180:183], v[120:123]
	v_mfma_f32_16x16x32_bf16 v[108:111], v[148:151], v[188:191], v[108:111]
	v_mfma_f32_16x16x32_bf16 v[104:107], v[156:159], v[188:191], v[104:107]
	v_mfma_f32_16x16x32_bf16 v[92:95], v[148:151], v[196:199], v[92:95]
	v_mfma_f32_16x16x32_bf16 v[88:91], v[156:159], v[196:199], v[88:91]
	v_mfma_f32_16x16x32_bf16 v[76:79], v[148:151], v[204:207], v[76:79]
	v_mfma_f32_16x16x32_bf16 v[72:75], v[156:159], v[204:207], v[72:75]
	v_mfma_f32_16x16x32_bf16 v[124:127], v[152:155], v[184:187], v[124:127]
	v_mfma_f32_16x16x32_bf16 v[120:123], v[160:163], v[184:187], v[120:123]
	v_mfma_f32_16x16x32_bf16 v[108:111], v[152:155], v[192:195], v[108:111]
	v_mfma_f32_16x16x32_bf16 v[104:107], v[160:163], v[192:195], v[104:107]
	v_mfma_f32_16x16x32_bf16 v[92:95], v[152:155], v[200:203], v[92:95]
	v_mfma_f32_16x16x32_bf16 v[88:91], v[160:163], v[200:203], v[88:91]
	v_mfma_f32_16x16x32_bf16 v[76:79], v[152:155], v[208:211], v[76:79]
	v_mfma_f32_16x16x32_bf16 v[72:75], v[160:163], v[208:211], v[72:75]
	v_mfma_f32_16x16x32_bf16 v[116:119], v[164:167], v[180:183], v[116:119]
	v_mfma_f32_16x16x32_bf16 v[112:115], v[172:175], v[180:183], v[112:115]
	v_mfma_f32_16x16x32_bf16 v[100:103], v[164:167], v[188:191], v[100:103]
	v_mfma_f32_16x16x32_bf16 v[96:99], v[172:175], v[188:191], v[96:99]
	v_mfma_f32_16x16x32_bf16 v[84:87], v[164:167], v[196:199], v[84:87]
	v_mfma_f32_16x16x32_bf16 v[80:83], v[172:175], v[196:199], v[80:83]
	v_mfma_f32_16x16x32_bf16 v[68:71], v[164:167], v[204:207], v[68:71]
	v_mfma_f32_16x16x32_bf16 v[64:67], v[172:175], v[204:207], v[64:67]
	v_mfma_f32_16x16x32_bf16 v[116:119], v[168:171], v[184:187], v[116:119]
	v_mfma_f32_16x16x32_bf16 v[112:115], v[176:179], v[184:187], v[112:115]
	v_mfma_f32_16x16x32_bf16 v[100:103], v[168:171], v[192:195], v[100:103]
	v_mfma_f32_16x16x32_bf16 v[96:99], v[176:179], v[192:195], v[96:99]
	v_mfma_f32_16x16x32_bf16 v[84:87], v[168:171], v[200:203], v[84:87]
	v_mfma_f32_16x16x32_bf16 v[80:83], v[176:179], v[200:203], v[80:83]
	v_mfma_f32_16x16x32_bf16 v[68:71], v[168:171], v[208:211], v[68:71]
	v_mfma_f32_16x16x32_bf16 v[64:67], v[176:179], v[208:211], v[64:67]
	s_barrier
	s_add_i32 s30, s33, s41
	v_lshl_add_u64 v[212:213], v[212:213], 0, s[14:15]
	s_mov_b32 m0, s30
	ds_read_b128 v[180:183], v146 offset:49152
	ds_read_b128 v[184:187], v146 offset:50176
	ds_read_b128 v[188:191], v146 offset:51200
	ds_read_b128 v[192:195], v146 offset:52224
	ds_read_b128 v[196:199], v146 offset:53248
	ds_read_b128 v[200:203], v146 offset:54272
	ds_read_b128 v[204:207], v146 offset:55296
	ds_read_b128 v[208:211], v146 offset:56320
	global_load_lds_dwordx4 v[212:213], off
	s_add_i32 m0, s30, 0x2000
	s_add_u32 s28, s28, 0x160080
	v_lshl_add_u64 v[212:213], v[214:215], 0, s[14:15]
	s_addc_u32 s29, s29, 0
	s_add_i32 s30, s55, s41
	global_load_lds_dwordx4 v[212:213], off
	v_lshl_add_u64 v[212:213], s[28:29], 0, v[128:129]
	s_mov_b32 m0, s30
	s_nop 0
	global_load_lds_dwordx4 v[212:213], off
	v_lshl_add_u64 v[212:213], s[28:29], 0, v[130:131]
	s_add_i32 m0, s30, 0x2000
	s_nop 0
	global_load_lds_dwordx4 v[212:213], off
	v_lshl_add_u64 v[212:213], v[216:217], 0, s[14:15]
	s_mov_b32 m0, s46
	s_nop 0
	global_load_lds_dwordx4 v[212:213], off
	v_lshl_add_u64 v[212:213], v[218:219], 0, s[14:15]
	s_mov_b32 m0, s47
	s_nop 0
	global_load_lds_dwordx4 v[212:213], off
	s_waitcnt vmcnt(8)
	s_waitcnt lgkmcnt(0)
	s_barrier
	v_mfma_f32_16x16x32_bf16 v[60:63], v[148:151], v[180:183], v[60:63]
	v_mfma_f32_16x16x32_bf16 v[56:59], v[156:159], v[180:183], v[56:59]
	v_mfma_f32_16x16x32_bf16 v[44:47], v[148:151], v[188:191], v[44:47]
	v_mfma_f32_16x16x32_bf16 v[40:43], v[156:159], v[188:191], v[40:43]
	v_mfma_f32_16x16x32_bf16 v[28:31], v[148:151], v[196:199], v[28:31]
	v_mfma_f32_16x16x32_bf16 v[24:27], v[156:159], v[196:199], v[24:27]
	v_mfma_f32_16x16x32_bf16 v[12:15], v[148:151], v[204:207], v[12:15]
	v_mfma_f32_16x16x32_bf16 v[8:11], v[156:159], v[204:207], v[8:11]
	v_mfma_f32_16x16x32_bf16 v[60:63], v[152:155], v[184:187], v[60:63]
	v_mfma_f32_16x16x32_bf16 v[56:59], v[160:163], v[184:187], v[56:59]
	v_mfma_f32_16x16x32_bf16 v[44:47], v[152:155], v[192:195], v[44:47]
	v_mfma_f32_16x16x32_bf16 v[40:43], v[160:163], v[192:195], v[40:43]
	v_mfma_f32_16x16x32_bf16 v[28:31], v[152:155], v[200:203], v[28:31]
	v_mfma_f32_16x16x32_bf16 v[24:27], v[160:163], v[200:203], v[24:27]
	v_mfma_f32_16x16x32_bf16 v[12:15], v[152:155], v[208:211], v[12:15]
	v_mfma_f32_16x16x32_bf16 v[8:11], v[160:163], v[208:211], v[8:11]
	v_mfma_f32_16x16x32_bf16 v[52:55], v[164:167], v[180:183], v[52:55]
	v_mfma_f32_16x16x32_bf16 v[48:51], v[172:175], v[180:183], v[48:51]
	v_mfma_f32_16x16x32_bf16 v[36:39], v[164:167], v[188:191], v[36:39]
	v_mfma_f32_16x16x32_bf16 v[32:35], v[172:175], v[188:191], v[32:35]
	v_mfma_f32_16x16x32_bf16 v[20:23], v[164:167], v[196:199], v[20:23]
	v_mfma_f32_16x16x32_bf16 v[16:19], v[172:175], v[196:199], v[16:19]
	v_mfma_f32_16x16x32_bf16 v[4:7], v[164:167], v[204:207], v[4:7]
	v_mfma_f32_16x16x32_bf16 v[0:3], v[172:175], v[204:207], v[0:3]
	v_mfma_f32_16x16x32_bf16 v[52:55], v[168:171], v[184:187], v[52:55]
	v_mfma_f32_16x16x32_bf16 v[48:51], v[176:179], v[184:187], v[48:51]
	v_mfma_f32_16x16x32_bf16 v[36:39], v[168:171], v[192:195], v[36:39]
	v_mfma_f32_16x16x32_bf16 v[32:35], v[176:179], v[192:195], v[32:35]
	v_mfma_f32_16x16x32_bf16 v[20:23], v[168:171], v[200:203], v[20:23]
	v_mfma_f32_16x16x32_bf16 v[16:19], v[176:179], v[200:203], v[16:19]
	v_mfma_f32_16x16x32_bf16 v[4:7], v[168:171], v[208:211], v[4:7]
	v_mfma_f32_16x16x32_bf16 v[0:3], v[176:179], v[208:211], v[0:3]
	s_barrier
	s_add_i32 s54, s54, 2
	s_add_u32 s24, s24, 0x100
	s_addc_u32 s25, s25, 0
	s_cmpk_gt_u32 s54, 0x55
	s_cbranch_scc0 .LBB0_139
	s_add_u32 s24, s17, 0xffffff00
	s_addc_u32 s25, s53, -1
	s_and_b64 vcc, exec, s[2:3]
	s_cbranch_vccnz .LBB0_142
	v_mov_b32_e32 v0, 0
	s_mov_b32 s38, s51
	s_mov_b32 s35, s52
	s_mov_b64 s[10:11], s[18:19]
	s_mov_b32 s48, s16
	v_mov_b32_e32 v1, v0
	v_mov_b32_e32 v2, v0
	v_mov_b32_e32 v3, v0
	v_mov_b32_e32 v4, v0
	v_mov_b32_e32 v5, v0
	v_mov_b32_e32 v6, v0
	v_mov_b32_e32 v7, v0
	v_mov_b32_e32 v16, v0
	v_mov_b32_e32 v17, v0
	v_mov_b32_e32 v18, v0
	v_mov_b32_e32 v19, v0
	v_mov_b32_e32 v20, v0
	v_mov_b32_e32 v21, v0
	v_mov_b32_e32 v22, v0
	v_mov_b32_e32 v23, v0
	v_mov_b32_e32 v32, v0
	v_mov_b32_e32 v33, v0
	v_mov_b32_e32 v34, v0
	v_mov_b32_e32 v35, v0
	v_mov_b32_e32 v36, v0
	v_mov_b32_e32 v37, v0
	v_mov_b32_e32 v38, v0
	v_mov_b32_e32 v39, v0
	v_mov_b32_e32 v48, v0
	v_mov_b32_e32 v49, v0
	v_mov_b32_e32 v50, v0
	v_mov_b32_e32 v51, v0
	v_mov_b32_e32 v52, v0
	v_mov_b32_e32 v53, v0
	v_mov_b32_e32 v54, v0
	v_mov_b32_e32 v55, v0
	v_mov_b32_e32 v8, v0
	v_mov_b32_e32 v9, v0
	v_mov_b32_e32 v10, v0
	v_mov_b32_e32 v11, v0
	v_mov_b32_e32 v12, v0
	v_mov_b32_e32 v13, v0
	v_mov_b32_e32 v14, v0
	v_mov_b32_e32 v15, v0
	v_mov_b32_e32 v24, v0
	v_mov_b32_e32 v25, v0
	v_mov_b32_e32 v26, v0
	v_mov_b32_e32 v27, v0
	v_mov_b32_e32 v28, v0
	v_mov_b32_e32 v29, v0
	v_mov_b32_e32 v30, v0
	v_mov_b32_e32 v31, v0
	v_mov_b32_e32 v40, v0
	v_mov_b32_e32 v41, v0
	v_mov_b32_e32 v42, v0
	v_mov_b32_e32 v43, v0
	v_mov_b32_e32 v44, v0
	v_mov_b32_e32 v45, v0
	v_mov_b32_e32 v46, v0
	v_mov_b32_e32 v47, v0
	v_mov_b32_e32 v56, v0
	v_mov_b32_e32 v57, v0
	v_mov_b32_e32 v58, v0
	v_mov_b32_e32 v59, v0
	v_mov_b32_e32 v60, v0
	v_mov_b32_e32 v61, v0
	v_mov_b32_e32 v62, v0
	v_mov_b32_e32 v63, v0
	v_mov_b32_e32 v64, v0
	v_mov_b32_e32 v65, v0
	v_mov_b32_e32 v66, v0
	v_mov_b32_e32 v67, v0
	v_mov_b32_e32 v68, v0
	v_mov_b32_e32 v69, v0
	v_mov_b32_e32 v70, v0
	v_mov_b32_e32 v71, v0
	v_mov_b32_e32 v80, v0
	v_mov_b32_e32 v81, v0
	v_mov_b32_e32 v82, v0
	v_mov_b32_e32 v83, v0
	v_mov_b32_e32 v84, v0
	v_mov_b32_e32 v85, v0
	v_mov_b32_e32 v86, v0
	v_mov_b32_e32 v87, v0
	v_mov_b32_e32 v96, v0
	v_mov_b32_e32 v97, v0
	v_mov_b32_e32 v98, v0
	v_mov_b32_e32 v99, v0
	v_mov_b32_e32 v100, v0
	v_mov_b32_e32 v101, v0
	v_mov_b32_e32 v102, v0
	v_mov_b32_e32 v103, v0
	v_mov_b32_e32 v112, v0
	v_mov_b32_e32 v113, v0
	v_mov_b32_e32 v114, v0
	v_mov_b32_e32 v115, v0
	v_mov_b32_e32 v116, v0
	v_mov_b32_e32 v117, v0
	v_mov_b32_e32 v118, v0
	v_mov_b32_e32 v119, v0
	v_mov_b32_e32 v72, v0
	v_mov_b32_e32 v73, v0
	v_mov_b32_e32 v74, v0
	v_mov_b32_e32 v75, v0
	v_mov_b32_e32 v76, v0
	v_mov_b32_e32 v77, v0
	v_mov_b32_e32 v78, v0
	v_mov_b32_e32 v79, v0
	v_mov_b32_e32 v88, v0
	v_mov_b32_e32 v89, v0
	v_mov_b32_e32 v90, v0
	v_mov_b32_e32 v91, v0
	v_mov_b32_e32 v92, v0
	v_mov_b32_e32 v93, v0
	v_mov_b32_e32 v94, v0
	v_mov_b32_e32 v95, v0
	v_mov_b32_e32 v104, v0
	v_mov_b32_e32 v105, v0
	v_mov_b32_e32 v106, v0
	v_mov_b32_e32 v107, v0
	v_mov_b32_e32 v108, v0
	v_mov_b32_e32 v109, v0
	v_mov_b32_e32 v110, v0
	v_mov_b32_e32 v111, v0
	v_mov_b32_e32 v120, v0
	v_mov_b32_e32 v121, v0
	v_mov_b32_e32 v122, v0
	v_mov_b32_e32 v123, v0
	v_mov_b32_e32 v124, v0
	v_mov_b32_e32 v125, v0
	v_mov_b32_e32 v126, v0
	v_mov_b32_e32 v127, v0
	s_andn2_b64 vcc, exec, s[0:1]
	s_cbranch_vccnz .LBB0_143
	s_branch .LBB0_144

.LBB0_331:
	ds_read_b128 v[158:161], v155
	ds_read_b128 v[162:165], v155 offset:1024
	ds_read_b128 v[166:169], v155 offset:2048
	ds_read_b128 v[170:173], v155 offset:3072
	ds_read_b128 v[174:177], v156
	ds_read_b128 v[178:181], v156 offset:1024
	ds_read_b128 v[182:185], v156 offset:2048
	ds_read_b128 v[186:189], v156 offset:3072
	s_add_u32 s24, s22, 0xfff80080
	s_addc_u32 s25, s23, -1
	s_cmp_eq_u32 s51, 28
	s_cselect_b32 s29, s15, s25
	s_cselect_b32 s28, s47, s24
	s_cselect_b32 s25, s13, s50
	s_cselect_b32 s24, s48, s49
	v_lshl_add_u64 v[218:219], s[22:23], 0, v[136:137]
	s_add_i32 m0, s21, 0xc000
	ds_read_b128 v[190:193], v157
	ds_read_b128 v[194:197], v157 offset:1024
	ds_read_b128 v[198:201], v157 offset:2048
	ds_read_b128 v[202:205], v157 offset:3072
	ds_read_b128 v[206:209], v157 offset:4096
	ds_read_b128 v[210:213], v157 offset:5120
	ds_read_b128 v[214:217], v157 offset:6144
	ds_read_b128 v[222:225], v157 offset:7168
	global_load_lds_dwordx4 v[218:219], off
	v_lshl_add_u64 v[218:219], s[22:23], 0, v[138:139]
	s_add_i32 m0, s21, 0xe000
	s_nop 0
	global_load_lds_dwordx4 v[218:219], off
	s_waitcnt vmcnt(8)
	s_waitcnt lgkmcnt(0)
	s_barrier
	v_mfma_f32_16x16x32_bf16 v[124:127], v[158:161], v[190:193], v[124:127]
	v_mfma_f32_16x16x32_bf16 v[120:123], v[166:169], v[190:193], v[120:123]
	v_mfma_f32_16x16x32_bf16 v[116:119], v[158:161], v[198:201], v[116:119]
	v_mfma_f32_16x16x32_bf16 v[108:111], v[166:169], v[198:201], v[108:111]
	v_mfma_f32_16x16x32_bf16 v[100:103], v[158:161], v[206:209], v[100:103]
	v_mfma_f32_16x16x32_bf16 v[92:95], v[166:169], v[206:209], v[92:95]
	v_mfma_f32_16x16x32_bf16 v[84:87], v[158:161], v[214:217], v[84:87]
	v_mfma_f32_16x16x32_bf16 v[76:79], v[166:169], v[214:217], v[76:79]
	v_mfma_f32_16x16x32_bf16 v[124:127], v[162:165], v[194:197], v[124:127]
	v_mfma_f32_16x16x32_bf16 v[120:123], v[170:173], v[194:197], v[120:123]
	v_mfma_f32_16x16x32_bf16 v[116:119], v[162:165], v[202:205], v[116:119]
	v_mfma_f32_16x16x32_bf16 v[108:111], v[170:173], v[202:205], v[108:111]
	v_mfma_f32_16x16x32_bf16 v[100:103], v[162:165], v[210:213], v[100:103]
	v_mfma_f32_16x16x32_bf16 v[92:95], v[170:173], v[210:213], v[92:95]
	v_mfma_f32_16x16x32_bf16 v[84:87], v[162:165], v[222:225], v[84:87]
	v_mfma_f32_16x16x32_bf16 v[76:79], v[170:173], v[222:225], v[76:79]
	v_mfma_f32_16x16x32_bf16 v[112:115], v[174:177], v[190:193], v[112:115]
	v_mfma_f32_16x16x32_bf16 v[104:107], v[182:185], v[190:193], v[104:107]
	v_mfma_f32_16x16x32_bf16 v[96:99], v[174:177], v[198:201], v[96:99]
	v_mfma_f32_16x16x32_bf16 v[88:91], v[182:185], v[198:201], v[88:91]
	v_mfma_f32_16x16x32_bf16 v[80:83], v[174:177], v[206:209], v[80:83]
	v_mfma_f32_16x16x32_bf16 v[72:75], v[182:185], v[206:209], v[72:75]
	v_mfma_f32_16x16x32_bf16 v[68:71], v[174:177], v[214:217], v[68:71]
	v_mfma_f32_16x16x32_bf16 v[64:67], v[182:185], v[214:217], v[64:67]
	v_mfma_f32_16x16x32_bf16 v[112:115], v[178:181], v[194:197], v[112:115]
	v_mfma_f32_16x16x32_bf16 v[104:107], v[186:189], v[194:197], v[104:107]
	v_mfma_f32_16x16x32_bf16 v[96:99], v[178:181], v[202:205], v[96:99]
	v_mfma_f32_16x16x32_bf16 v[88:91], v[186:189], v[202:205], v[88:91]
	v_mfma_f32_16x16x32_bf16 v[80:83], v[178:181], v[210:213], v[80:83]
	v_mfma_f32_16x16x32_bf16 v[72:75], v[186:189], v[210:213], v[72:75]
	v_mfma_f32_16x16x32_bf16 v[68:71], v[178:181], v[222:225], v[68:71]
	v_mfma_f32_16x16x32_bf16 v[64:67], v[186:189], v[222:225], v[64:67]
	s_barrier
	s_add_i32 s33, s43, s30
	v_lshl_add_u64 v[218:219], s[24:25], 0, v[130:131]
	s_mov_b32 m0, s33
	ds_read_b128 v[190:193], v157 offset:16384
	ds_read_b128 v[194:197], v157 offset:17408
	ds_read_b128 v[198:201], v157 offset:18432
	ds_read_b128 v[202:205], v157 offset:19456
	ds_read_b128 v[206:209], v157 offset:20480
	ds_read_b128 v[210:213], v157 offset:21504
	ds_read_b128 v[214:217], v157 offset:22528
	ds_read_b128 v[222:225], v157 offset:23552
	global_load_lds_dwordx4 v[218:219], off
	s_add_i32 m0, s33, 0x2000
	s_add_u32 s52, s24, 0x80000
	v_lshl_add_u64 v[226:227], s[24:25], 0, v[134:135]
	s_addc_u32 s53, s25, 0
	s_add_i32 s33, s44, s30
	global_load_lds_dwordx4 v[226:227], off
	v_lshl_add_u64 v[228:229], s[52:53], 0, v[130:131]
	s_mov_b32 m0, s33
	v_lshl_add_u64 v[230:231], s[28:29], 0, v[132:133]
	global_load_lds_dwordx4 v[228:229], off
	v_lshl_add_u64 v[228:229], s[52:53], 0, v[134:135]
	s_add_i32 m0, s33, 0x2000
	s_nop 0
	global_load_lds_dwordx4 v[228:229], off
	v_lshl_add_u64 v[228:229], s[28:29], 0, v[128:129]
	s_mov_b32 m0, s21
	s_nop 0
	global_load_lds_dwordx4 v[228:229], off
	s_mov_b32 m0, s35
	s_nop 0
	global_load_lds_dwordx4 v[230:231], off
	s_waitcnt vmcnt(8)
	s_waitcnt lgkmcnt(0)
	s_barrier
	v_mfma_f32_16x16x32_bf16 v[60:63], v[158:161], v[190:193], v[60:63]
	v_mfma_f32_16x16x32_bf16 v[56:59], v[166:169], v[190:193], v[56:59]
	v_mfma_f32_16x16x32_bf16 v[52:55], v[158:161], v[198:201], v[52:55]
	v_mfma_f32_16x16x32_bf16 v[44:47], v[166:169], v[198:201], v[44:47]
	v_mfma_f32_16x16x32_bf16 v[36:39], v[158:161], v[206:209], v[36:39]
	v_mfma_f32_16x16x32_bf16 v[28:31], v[166:169], v[206:209], v[28:31]
	v_mfma_f32_16x16x32_bf16 v[20:23], v[158:161], v[214:217], v[20:23]
	v_mfma_f32_16x16x32_bf16 v[12:15], v[166:169], v[214:217], v[12:15]
	v_mfma_f32_16x16x32_bf16 v[60:63], v[162:165], v[194:197], v[60:63]
	v_mfma_f32_16x16x32_bf16 v[56:59], v[170:173], v[194:197], v[56:59]
	v_mfma_f32_16x16x32_bf16 v[52:55], v[162:165], v[202:205], v[52:55]
	v_mfma_f32_16x16x32_bf16 v[44:47], v[170:173], v[202:205], v[44:47]
	v_mfma_f32_16x16x32_bf16 v[36:39], v[162:165], v[210:213], v[36:39]
	v_mfma_f32_16x16x32_bf16 v[28:31], v[170:173], v[210:213], v[28:31]
	v_mfma_f32_16x16x32_bf16 v[20:23], v[162:165], v[222:225], v[20:23]
	v_mfma_f32_16x16x32_bf16 v[12:15], v[170:173], v[222:225], v[12:15]
	v_mfma_f32_16x16x32_bf16 v[48:51], v[174:177], v[190:193], v[48:51]
	v_mfma_f32_16x16x32_bf16 v[40:43], v[182:185], v[190:193], v[40:43]
	v_mfma_f32_16x16x32_bf16 v[32:35], v[174:177], v[198:201], v[32:35]
	v_mfma_f32_16x16x32_bf16 v[24:27], v[182:185], v[198:201], v[24:27]
	v_mfma_f32_16x16x32_bf16 v[16:19], v[174:177], v[206:209], v[16:19]
	v_mfma_f32_16x16x32_bf16 v[8:11], v[182:185], v[206:209], v[8:11]
	v_mfma_f32_16x16x32_bf16 v[4:7], v[174:177], v[214:217], v[4:7]
	v_mfma_f32_16x16x32_bf16 v[0:3], v[182:185], v[214:217], v[0:3]
	v_mfma_f32_16x16x32_bf16 v[48:51], v[178:181], v[194:197], v[48:51]
	v_mfma_f32_16x16x32_bf16 v[40:43], v[186:189], v[194:197], v[40:43]
	v_mfma_f32_16x16x32_bf16 v[32:35], v[178:181], v[202:205], v[32:35]
	v_mfma_f32_16x16x32_bf16 v[24:27], v[186:189], v[202:205], v[24:27]
	v_mfma_f32_16x16x32_bf16 v[16:19], v[178:181], v[210:213], v[16:19]
	v_mfma_f32_16x16x32_bf16 v[8:11], v[186:189], v[210:213], v[8:11]
	v_mfma_f32_16x16x32_bf16 v[4:7], v[178:181], v[222:225], v[4:7]
	v_mfma_f32_16x16x32_bf16 v[0:3], v[186:189], v[222:225], v[0:3]
	s_barrier
	s_add_i32 s33, 0, 0x18000
	s_add_i32 s52, 0, 0x1c000
	v_add_u32_e32 v170, s33, v153
	v_add_u32_e32 v186, s52, v153
	ds_read_b128 v[158:161], v170
	ds_read_b128 v[162:165], v170 offset:1024
	ds_read_b128 v[166:169], v170 offset:2048
	ds_read_b128 v[170:173], v170 offset:3072
	ds_read_b128 v[174:177], v186
	ds_read_b128 v[178:181], v186 offset:1024
	ds_read_b128 v[182:185], v186 offset:2048
	ds_read_b128 v[186:189], v186 offset:3072
	s_add_u32 s28, s28, 0x80000
	s_addc_u32 s29, s29, 0
	s_mov_b32 m0, s37
	v_lshl_add_u64 v[232:233], s[28:29], 0, v[128:129]
	ds_read_b128 v[190:193], v157 offset:32768
	ds_read_b128 v[194:197], v157 offset:33792
	ds_read_b128 v[198:201], v157 offset:34816
	ds_read_b128 v[202:205], v157 offset:35840
	ds_read_b128 v[206:209], v157 offset:36864
	ds_read_b128 v[210:213], v157 offset:37888
	ds_read_b128 v[214:217], v157 offset:38912
	ds_read_b128 v[222:225], v157 offset:39936
	global_load_lds_dwordx4 v[232:233], off
	v_lshl_add_u64 v[232:233], s[28:29], 0, v[132:133]
	s_mov_b32 m0, s38
	s_nop 0
	global_load_lds_dwordx4 v[232:233], off
	s_waitcnt vmcnt(8)
	s_waitcnt lgkmcnt(0)
	s_barrier
	v_mfma_f32_16x16x32_bf16 v[124:127], v[158:161], v[190:193], v[124:127]
	v_mfma_f32_16x16x32_bf16 v[120:123], v[166:169], v[190:193], v[120:123]
	v_mfma_f32_16x16x32_bf16 v[116:119], v[158:161], v[198:201], v[116:119]
	v_mfma_f32_16x16x32_bf16 v[108:111], v[166:169], v[198:201], v[108:111]
	v_mfma_f32_16x16x32_bf16 v[100:103], v[158:161], v[206:209], v[100:103]
	v_mfma_f32_16x16x32_bf16 v[92:95], v[166:169], v[206:209], v[92:95]
	v_mfma_f32_16x16x32_bf16 v[84:87], v[158:161], v[214:217], v[84:87]
	v_mfma_f32_16x16x32_bf16 v[76:79], v[166:169], v[214:217], v[76:79]
	v_mfma_f32_16x16x32_bf16 v[124:127], v[162:165], v[194:197], v[124:127]
	v_mfma_f32_16x16x32_bf16 v[120:123], v[170:173], v[194:197], v[120:123]
	v_mfma_f32_16x16x32_bf16 v[116:119], v[162:165], v[202:205], v[116:119]
	v_mfma_f32_16x16x32_bf16 v[108:111], v[170:173], v[202:205], v[108:111]
	v_mfma_f32_16x16x32_bf16 v[100:103], v[162:165], v[210:213], v[100:103]
	v_mfma_f32_16x16x32_bf16 v[92:95], v[170:173], v[210:213], v[92:95]
	v_mfma_f32_16x16x32_bf16 v[84:87], v[162:165], v[222:225], v[84:87]
	v_mfma_f32_16x16x32_bf16 v[76:79], v[170:173], v[222:225], v[76:79]
	v_mfma_f32_16x16x32_bf16 v[112:115], v[174:177], v[190:193], v[112:115]
	v_mfma_f32_16x16x32_bf16 v[104:107], v[182:185], v[190:193], v[104:107]
	v_mfma_f32_16x16x32_bf16 v[96:99], v[174:177], v[198:201], v[96:99]
	v_mfma_f32_16x16x32_bf16 v[88:91], v[182:185], v[198:201], v[88:91]
	v_mfma_f32_16x16x32_bf16 v[80:83], v[174:177], v[206:209], v[80:83]
	v_mfma_f32_16x16x32_bf16 v[72:75], v[182:185], v[206:209], v[72:75]
	v_mfma_f32_16x16x32_bf16 v[68:71], v[174:177], v[214:217], v[68:71]
	v_mfma_f32_16x16x32_bf16 v[64:67], v[182:185], v[214:217], v[64:67]
	v_mfma_f32_16x16x32_bf16 v[112:115], v[178:181], v[194:197], v[112:115]
	v_mfma_f32_16x16x32_bf16 v[104:107], v[186:189], v[194:197], v[104:107]
	v_mfma_f32_16x16x32_bf16 v[96:99], v[178:181], v[202:205], v[96:99]
	v_mfma_f32_16x16x32_bf16 v[88:91], v[186:189], v[202:205], v[88:91]
	v_mfma_f32_16x16x32_bf16 v[80:83], v[178:181], v[210:213], v[80:83]
	v_mfma_f32_16x16x32_bf16 v[72:75], v[186:189], v[210:213], v[72:75]
	v_mfma_f32_16x16x32_bf16 v[68:71], v[178:181], v[222:225], v[68:71]
	v_mfma_f32_16x16x32_bf16 v[64:67], v[186:189], v[222:225], v[64:67]
	s_barrier
	s_add_i32 s28, s33, s30
	v_lshl_add_u64 v[218:219], v[218:219], 0, s[8:9]
	s_mov_b32 m0, s28
	ds_read_b128 v[190:193], v157 offset:49152
	ds_read_b128 v[194:197], v157 offset:50176
	ds_read_b128 v[198:201], v157 offset:51200
	ds_read_b128 v[202:205], v157 offset:52224
	ds_read_b128 v[206:209], v157 offset:53248
	ds_read_b128 v[210:213], v157 offset:54272
	ds_read_b128 v[214:217], v157 offset:55296
	ds_read_b128 v[222:225], v157 offset:56320
	global_load_lds_dwordx4 v[218:219], off
	s_add_i32 m0, s28, 0x2000
	s_add_u32 s24, s24, 0x80080
	v_lshl_add_u64 v[218:219], v[226:227], 0, s[8:9]
	s_addc_u32 s25, s25, 0
	s_add_i32 s28, s52, s30
	global_load_lds_dwordx4 v[218:219], off
	v_lshl_add_u64 v[218:219], s[24:25], 0, v[130:131]
	s_mov_b32 m0, s28
	s_nop 0
	global_load_lds_dwordx4 v[218:219], off
	v_lshl_add_u64 v[218:219], s[24:25], 0, v[134:135]
	s_add_i32 m0, s28, 0x2000
	s_nop 0
	global_load_lds_dwordx4 v[218:219], off
	v_lshl_add_u64 v[218:219], v[228:229], 0, s[8:9]
	s_mov_b32 m0, s40
	s_nop 0
	global_load_lds_dwordx4 v[218:219], off
	v_lshl_add_u64 v[218:219], v[230:231], 0, s[8:9]
	s_mov_b32 m0, s41
	s_nop 0
	global_load_lds_dwordx4 v[218:219], off
	s_waitcnt vmcnt(8)
	s_waitcnt lgkmcnt(0)
	s_barrier
	v_mfma_f32_16x16x32_bf16 v[60:63], v[158:161], v[190:193], v[60:63]
	v_mfma_f32_16x16x32_bf16 v[56:59], v[166:169], v[190:193], v[56:59]
	v_mfma_f32_16x16x32_bf16 v[52:55], v[158:161], v[198:201], v[52:55]
	v_mfma_f32_16x16x32_bf16 v[44:47], v[166:169], v[198:201], v[44:47]
	v_mfma_f32_16x16x32_bf16 v[36:39], v[158:161], v[206:209], v[36:39]
	v_mfma_f32_16x16x32_bf16 v[28:31], v[166:169], v[206:209], v[28:31]
	v_mfma_f32_16x16x32_bf16 v[20:23], v[158:161], v[214:217], v[20:23]
	v_mfma_f32_16x16x32_bf16 v[12:15], v[166:169], v[214:217], v[12:15]
	v_mfma_f32_16x16x32_bf16 v[60:63], v[162:165], v[194:197], v[60:63]
	v_mfma_f32_16x16x32_bf16 v[56:59], v[170:173], v[194:197], v[56:59]
	v_mfma_f32_16x16x32_bf16 v[52:55], v[162:165], v[202:205], v[52:55]
	v_mfma_f32_16x16x32_bf16 v[44:47], v[170:173], v[202:205], v[44:47]
	v_mfma_f32_16x16x32_bf16 v[36:39], v[162:165], v[210:213], v[36:39]
	v_mfma_f32_16x16x32_bf16 v[28:31], v[170:173], v[210:213], v[28:31]
	v_mfma_f32_16x16x32_bf16 v[20:23], v[162:165], v[222:225], v[20:23]
	v_mfma_f32_16x16x32_bf16 v[12:15], v[170:173], v[222:225], v[12:15]
	v_mfma_f32_16x16x32_bf16 v[48:51], v[174:177], v[190:193], v[48:51]
	v_mfma_f32_16x16x32_bf16 v[40:43], v[182:185], v[190:193], v[40:43]
	v_mfma_f32_16x16x32_bf16 v[32:35], v[174:177], v[198:201], v[32:35]
	v_mfma_f32_16x16x32_bf16 v[24:27], v[182:185], v[198:201], v[24:27]
	v_mfma_f32_16x16x32_bf16 v[16:19], v[174:177], v[206:209], v[16:19]
	v_mfma_f32_16x16x32_bf16 v[8:11], v[182:185], v[206:209], v[8:11]
	v_mfma_f32_16x16x32_bf16 v[4:7], v[174:177], v[214:217], v[4:7]
	v_mfma_f32_16x16x32_bf16 v[0:3], v[182:185], v[214:217], v[0:3]
	v_mfma_f32_16x16x32_bf16 v[48:51], v[178:181], v[194:197], v[48:51]
	v_mfma_f32_16x16x32_bf16 v[40:43], v[186:189], v[194:197], v[40:43]
	v_mfma_f32_16x16x32_bf16 v[32:35], v[178:181], v[202:205], v[32:35]
	v_mfma_f32_16x16x32_bf16 v[24:27], v[186:189], v[202:205], v[24:27]
	v_mfma_f32_16x16x32_bf16 v[16:19], v[178:181], v[210:213], v[16:19]
	v_mfma_f32_16x16x32_bf16 v[8:11], v[186:189], v[210:213], v[8:11]
	v_mfma_f32_16x16x32_bf16 v[4:7], v[178:181], v[222:225], v[4:7]
	v_mfma_f32_16x16x32_bf16 v[0:3], v[186:189], v[222:225], v[0:3]
	s_barrier
	s_add_i32 s51, s51, 2
	s_add_u32 s22, s22, 0x100
	s_addc_u32 s23, s23, 0
	s_add_u32 s49, s49, 0x100
	s_addc_u32 s50, s50, 0
	s_cmp_gt_u32 s51, 29
	s_cbranch_scc0 .LBB0_331
	s_and_b64 vcc, exec, s[10:11]
	s_cbranch_vccz .LBB0_334
	s_barrier

.LBB0_363:
	ds_read_b128 v[154:157], v144
	ds_read_b128 v[158:161], v144 offset:1024
	ds_read_b128 v[162:165], v144 offset:2048
	ds_read_b128 v[166:169], v144 offset:3072
	ds_read_b128 v[170:173], v145
	ds_read_b128 v[174:177], v145 offset:1024
	ds_read_b128 v[178:181], v145 offset:2048
	ds_read_b128 v[182:185], v145 offset:3072
	s_add_u32 s30, s28, 0xfff80080
	s_addc_u32 s31, s29, -1
	s_cmp_eq_u32 s50, 28
	s_cselect_b32 s35, s15, s31
	s_cselect_b32 s34, s46, s30
	s_cselect_b32 s31, s17, s49
	s_cselect_b32 s30, s47, s48
	v_lshl_add_u64 v[150:151], s[28:29], 0, v[136:137]
	s_add_i32 m0, s23, 0xc000
	ds_read_b128 v[186:189], v146
	ds_read_b128 v[190:193], v146 offset:1024
	ds_read_b128 v[194:197], v146 offset:2048
	ds_read_b128 v[198:201], v146 offset:3072
	ds_read_b128 v[202:205], v146 offset:4096
	ds_read_b128 v[206:209], v146 offset:5120
	ds_read_b128 v[210:213], v146 offset:6144
	ds_read_b128 v[214:217], v146 offset:7168
	global_load_lds_dwordx4 v[150:151], off
	v_lshl_add_u64 v[150:151], s[28:29], 0, v[138:139]
	s_add_i32 m0, s23, 0xe000
	s_nop 0
	global_load_lds_dwordx4 v[150:151], off
	s_waitcnt vmcnt(8)
	s_waitcnt lgkmcnt(0)
	s_barrier
	v_mfma_f32_16x16x32_bf16 v[124:127], v[154:157], v[186:189], v[124:127]
	v_mfma_f32_16x16x32_bf16 v[120:123], v[162:165], v[186:189], v[120:123]
	v_mfma_f32_16x16x32_bf16 v[116:119], v[154:157], v[194:197], v[116:119]
	v_mfma_f32_16x16x32_bf16 v[108:111], v[162:165], v[194:197], v[108:111]
	v_mfma_f32_16x16x32_bf16 v[100:103], v[154:157], v[202:205], v[100:103]
	v_mfma_f32_16x16x32_bf16 v[92:95], v[162:165], v[202:205], v[92:95]
	v_mfma_f32_16x16x32_bf16 v[84:87], v[154:157], v[210:213], v[84:87]
	v_mfma_f32_16x16x32_bf16 v[76:79], v[162:165], v[210:213], v[76:79]
	v_mfma_f32_16x16x32_bf16 v[124:127], v[158:161], v[190:193], v[124:127]
	v_mfma_f32_16x16x32_bf16 v[120:123], v[166:169], v[190:193], v[120:123]
	v_mfma_f32_16x16x32_bf16 v[116:119], v[158:161], v[198:201], v[116:119]
	v_mfma_f32_16x16x32_bf16 v[108:111], v[166:169], v[198:201], v[108:111]
	v_mfma_f32_16x16x32_bf16 v[100:103], v[158:161], v[206:209], v[100:103]
	v_mfma_f32_16x16x32_bf16 v[92:95], v[166:169], v[206:209], v[92:95]
	v_mfma_f32_16x16x32_bf16 v[84:87], v[158:161], v[214:217], v[84:87]
	v_mfma_f32_16x16x32_bf16 v[76:79], v[166:169], v[214:217], v[76:79]
	v_mfma_f32_16x16x32_bf16 v[112:115], v[170:173], v[186:189], v[112:115]
	v_mfma_f32_16x16x32_bf16 v[104:107], v[178:181], v[186:189], v[104:107]
	v_mfma_f32_16x16x32_bf16 v[96:99], v[170:173], v[194:197], v[96:99]
	v_mfma_f32_16x16x32_bf16 v[88:91], v[178:181], v[194:197], v[88:91]
	v_mfma_f32_16x16x32_bf16 v[80:83], v[170:173], v[202:205], v[80:83]
	v_mfma_f32_16x16x32_bf16 v[72:75], v[178:181], v[202:205], v[72:75]
	v_mfma_f32_16x16x32_bf16 v[68:71], v[170:173], v[210:213], v[68:71]
	v_mfma_f32_16x16x32_bf16 v[64:67], v[178:181], v[210:213], v[64:67]
	v_mfma_f32_16x16x32_bf16 v[112:115], v[174:177], v[190:193], v[112:115]
	v_mfma_f32_16x16x32_bf16 v[104:107], v[182:185], v[190:193], v[104:107]
	v_mfma_f32_16x16x32_bf16 v[96:99], v[174:177], v[198:201], v[96:99]
	v_mfma_f32_16x16x32_bf16 v[88:91], v[182:185], v[198:201], v[88:91]
	v_mfma_f32_16x16x32_bf16 v[80:83], v[174:177], v[206:209], v[80:83]
	v_mfma_f32_16x16x32_bf16 v[72:75], v[182:185], v[206:209], v[72:75]
	v_mfma_f32_16x16x32_bf16 v[68:71], v[174:177], v[214:217], v[68:71]
	v_mfma_f32_16x16x32_bf16 v[64:67], v[182:185], v[214:217], v[64:67]
	s_barrier
	s_add_i32 s33, s43, s38
	v_lshl_add_u64 v[150:151], s[30:31], 0, v[130:131]
	s_mov_b32 m0, s33
	ds_read_b128 v[186:189], v146 offset:16384
	ds_read_b128 v[190:193], v146 offset:17408
	ds_read_b128 v[194:197], v146 offset:18432
	ds_read_b128 v[198:201], v146 offset:19456
	ds_read_b128 v[202:205], v146 offset:20480
	ds_read_b128 v[206:209], v146 offset:21504
	ds_read_b128 v[210:213], v146 offset:22528
	ds_read_b128 v[214:217], v146 offset:23552
	global_load_lds_dwordx4 v[150:151], off
	s_add_i32 m0, s33, 0x2000
	s_add_u32 s52, s30, 0x80000
	v_lshl_add_u64 v[218:219], s[30:31], 0, v[134:135]
	s_addc_u32 s53, s31, 0
	s_add_i32 s33, s44, s38
	global_load_lds_dwordx4 v[218:219], off
	v_lshl_add_u64 v[222:223], s[52:53], 0, v[130:131]
	s_mov_b32 m0, s33
	v_lshl_add_u64 v[224:225], s[34:35], 0, v[132:133]
	global_load_lds_dwordx4 v[222:223], off
	v_lshl_add_u64 v[222:223], s[52:53], 0, v[134:135]
	s_add_i32 m0, s33, 0x2000
	s_nop 0
	global_load_lds_dwordx4 v[222:223], off
	v_lshl_add_u64 v[222:223], s[34:35], 0, v[128:129]
	s_mov_b32 m0, s23
	s_nop 0
	global_load_lds_dwordx4 v[222:223], off
	s_mov_b32 m0, s25
	s_nop 0
	global_load_lds_dwordx4 v[224:225], off
	s_waitcnt vmcnt(8)
	s_waitcnt lgkmcnt(0)
	s_barrier
	v_mfma_f32_16x16x32_bf16 v[60:63], v[154:157], v[186:189], v[60:63]
	v_mfma_f32_16x16x32_bf16 v[56:59], v[162:165], v[186:189], v[56:59]
	v_mfma_f32_16x16x32_bf16 v[52:55], v[154:157], v[194:197], v[52:55]
	v_mfma_f32_16x16x32_bf16 v[44:47], v[162:165], v[194:197], v[44:47]
	v_mfma_f32_16x16x32_bf16 v[36:39], v[154:157], v[202:205], v[36:39]
	v_mfma_f32_16x16x32_bf16 v[28:31], v[162:165], v[202:205], v[28:31]
	v_mfma_f32_16x16x32_bf16 v[20:23], v[154:157], v[210:213], v[20:23]
	v_mfma_f32_16x16x32_bf16 v[12:15], v[162:165], v[210:213], v[12:15]
	v_mfma_f32_16x16x32_bf16 v[60:63], v[158:161], v[190:193], v[60:63]
	v_mfma_f32_16x16x32_bf16 v[56:59], v[166:169], v[190:193], v[56:59]
	v_mfma_f32_16x16x32_bf16 v[52:55], v[158:161], v[198:201], v[52:55]
	v_mfma_f32_16x16x32_bf16 v[44:47], v[166:169], v[198:201], v[44:47]
	v_mfma_f32_16x16x32_bf16 v[36:39], v[158:161], v[206:209], v[36:39]
	v_mfma_f32_16x16x32_bf16 v[28:31], v[166:169], v[206:209], v[28:31]
	v_mfma_f32_16x16x32_bf16 v[20:23], v[158:161], v[214:217], v[20:23]
	v_mfma_f32_16x16x32_bf16 v[12:15], v[166:169], v[214:217], v[12:15]
	v_mfma_f32_16x16x32_bf16 v[48:51], v[170:173], v[186:189], v[48:51]
	v_mfma_f32_16x16x32_bf16 v[40:43], v[178:181], v[186:189], v[40:43]
	v_mfma_f32_16x16x32_bf16 v[32:35], v[170:173], v[194:197], v[32:35]
	v_mfma_f32_16x16x32_bf16 v[24:27], v[178:181], v[194:197], v[24:27]
	v_mfma_f32_16x16x32_bf16 v[16:19], v[170:173], v[202:205], v[16:19]
	v_mfma_f32_16x16x32_bf16 v[8:11], v[178:181], v[202:205], v[8:11]
	v_mfma_f32_16x16x32_bf16 v[4:7], v[170:173], v[210:213], v[4:7]
	v_mfma_f32_16x16x32_bf16 v[0:3], v[178:181], v[210:213], v[0:3]
	v_mfma_f32_16x16x32_bf16 v[48:51], v[174:177], v[190:193], v[48:51]
	v_mfma_f32_16x16x32_bf16 v[40:43], v[182:185], v[190:193], v[40:43]
	v_mfma_f32_16x16x32_bf16 v[32:35], v[174:177], v[198:201], v[32:35]
	v_mfma_f32_16x16x32_bf16 v[24:27], v[182:185], v[198:201], v[24:27]
	v_mfma_f32_16x16x32_bf16 v[16:19], v[174:177], v[206:209], v[16:19]
	v_mfma_f32_16x16x32_bf16 v[8:11], v[182:185], v[206:209], v[8:11]
	v_mfma_f32_16x16x32_bf16 v[4:7], v[174:177], v[214:217], v[4:7]
	v_mfma_f32_16x16x32_bf16 v[0:3], v[182:185], v[214:217], v[0:3]
	s_barrier
	s_add_i32 s33, 0, 0x18000
	v_add_u32_e32 v148, s33, v149
	s_add_i32 s51, 0, 0x1c000
	ds_read_b128 v[154:157], v148
	ds_read_b128 v[158:161], v148 offset:1024
	ds_read_b128 v[162:165], v148 offset:2048
	ds_read_b128 v[166:169], v148 offset:3072
	v_add_u32_e32 v148, s51, v149
	ds_read_b128 v[170:173], v148
	ds_read_b128 v[174:177], v148 offset:1024
	ds_read_b128 v[178:181], v148 offset:2048
	ds_read_b128 v[182:185], v148 offset:3072
	s_add_u32 s34, s34, 0x80000
	s_addc_u32 s35, s35, 0
	s_mov_b32 m0, s39
	v_lshl_add_u64 v[226:227], s[34:35], 0, v[128:129]
	ds_read_b128 v[186:189], v146 offset:32768
	ds_read_b128 v[190:193], v146 offset:33792
	ds_read_b128 v[194:197], v146 offset:34816
	ds_read_b128 v[198:201], v146 offset:35840
	ds_read_b128 v[202:205], v146 offset:36864
	ds_read_b128 v[206:209], v146 offset:37888
	ds_read_b128 v[210:213], v146 offset:38912
	ds_read_b128 v[214:217], v146 offset:39936
	global_load_lds_dwordx4 v[226:227], off
	v_lshl_add_u64 v[226:227], s[34:35], 0, v[132:133]
	s_mov_b32 m0, s40
	s_nop 0
	global_load_lds_dwordx4 v[226:227], off
	s_waitcnt vmcnt(8)
	s_waitcnt lgkmcnt(0)
	s_barrier
	v_mfma_f32_16x16x32_bf16 v[124:127], v[154:157], v[186:189], v[124:127]
	v_mfma_f32_16x16x32_bf16 v[120:123], v[162:165], v[186:189], v[120:123]
	v_mfma_f32_16x16x32_bf16 v[116:119], v[154:157], v[194:197], v[116:119]
	v_mfma_f32_16x16x32_bf16 v[108:111], v[162:165], v[194:197], v[108:111]
	v_mfma_f32_16x16x32_bf16 v[100:103], v[154:157], v[202:205], v[100:103]
	v_mfma_f32_16x16x32_bf16 v[92:95], v[162:165], v[202:205], v[92:95]
	v_mfma_f32_16x16x32_bf16 v[84:87], v[154:157], v[210:213], v[84:87]
	v_mfma_f32_16x16x32_bf16 v[76:79], v[162:165], v[210:213], v[76:79]
	v_mfma_f32_16x16x32_bf16 v[124:127], v[158:161], v[190:193], v[124:127]
	v_mfma_f32_16x16x32_bf16 v[120:123], v[166:169], v[190:193], v[120:123]
	v_mfma_f32_16x16x32_bf16 v[116:119], v[158:161], v[198:201], v[116:119]
	v_mfma_f32_16x16x32_bf16 v[108:111], v[166:169], v[198:201], v[108:111]
	v_mfma_f32_16x16x32_bf16 v[100:103], v[158:161], v[206:209], v[100:103]
	v_mfma_f32_16x16x32_bf16 v[92:95], v[166:169], v[206:209], v[92:95]
	v_mfma_f32_16x16x32_bf16 v[84:87], v[158:161], v[214:217], v[84:87]
	v_mfma_f32_16x16x32_bf16 v[76:79], v[166:169], v[214:217], v[76:79]
	v_mfma_f32_16x16x32_bf16 v[112:115], v[170:173], v[186:189], v[112:115]
	v_mfma_f32_16x16x32_bf16 v[104:107], v[178:181], v[186:189], v[104:107]
	v_mfma_f32_16x16x32_bf16 v[96:99], v[170:173], v[194:197], v[96:99]
	v_mfma_f32_16x16x32_bf16 v[88:91], v[178:181], v[194:197], v[88:91]
	v_mfma_f32_16x16x32_bf16 v[80:83], v[170:173], v[202:205], v[80:83]
	v_mfma_f32_16x16x32_bf16 v[72:75], v[178:181], v[202:205], v[72:75]
	v_mfma_f32_16x16x32_bf16 v[68:71], v[170:173], v[210:213], v[68:71]
	v_mfma_f32_16x16x32_bf16 v[64:67], v[178:181], v[210:213], v[64:67]
	v_mfma_f32_16x16x32_bf16 v[112:115], v[174:177], v[190:193], v[112:115]
	v_mfma_f32_16x16x32_bf16 v[104:107], v[182:185], v[190:193], v[104:107]
	v_mfma_f32_16x16x32_bf16 v[96:99], v[174:177], v[198:201], v[96:99]
	v_mfma_f32_16x16x32_bf16 v[88:91], v[182:185], v[198:201], v[88:91]
	v_mfma_f32_16x16x32_bf16 v[80:83], v[174:177], v[206:209], v[80:83]
	v_mfma_f32_16x16x32_bf16 v[72:75], v[182:185], v[206:209], v[72:75]
	v_mfma_f32_16x16x32_bf16 v[68:71], v[174:177], v[214:217], v[68:71]
	v_mfma_f32_16x16x32_bf16 v[64:67], v[182:185], v[214:217], v[64:67]
	s_barrier
	s_add_i32 s33, s33, s38
	v_lshl_add_u64 v[150:151], v[150:151], 0, s[10:11]
	s_mov_b32 m0, s33
	ds_read_b128 v[186:189], v146 offset:49152
	ds_read_b128 v[190:193], v146 offset:50176
	ds_read_b128 v[194:197], v146 offset:51200
	ds_read_b128 v[198:201], v146 offset:52224
	ds_read_b128 v[202:205], v146 offset:53248
	ds_read_b128 v[206:209], v146 offset:54272
	ds_read_b128 v[210:213], v146 offset:55296
	ds_read_b128 v[214:217], v146 offset:56320
	global_load_lds_dwordx4 v[150:151], off
	s_add_i32 m0, s33, 0x2000
	s_add_u32 s30, s30, 0x80080
	v_lshl_add_u64 v[150:151], v[218:219], 0, s[10:11]
	s_addc_u32 s31, s31, 0
	s_add_i32 s33, s51, s38
	global_load_lds_dwordx4 v[150:151], off
	v_lshl_add_u64 v[150:151], s[30:31], 0, v[130:131]
	s_mov_b32 m0, s33
	s_nop 0
	global_load_lds_dwordx4 v[150:151], off
	v_lshl_add_u64 v[150:151], s[30:31], 0, v[134:135]
	s_add_i32 m0, s33, 0x2000
	s_nop 0
	global_load_lds_dwordx4 v[150:151], off
	v_lshl_add_u64 v[150:151], v[222:223], 0, s[10:11]
	s_mov_b32 m0, s41
	s_nop 0
	global_load_lds_dwordx4 v[150:151], off
	v_lshl_add_u64 v[150:151], v[224:225], 0, s[10:11]
	s_mov_b32 m0, s42
	s_nop 0
	global_load_lds_dwordx4 v[150:151], off
	s_waitcnt vmcnt(8)
	s_waitcnt lgkmcnt(0)
	s_barrier
	v_mfma_f32_16x16x32_bf16 v[60:63], v[154:157], v[186:189], v[60:63]
	v_mfma_f32_16x16x32_bf16 v[56:59], v[162:165], v[186:189], v[56:59]
	v_mfma_f32_16x16x32_bf16 v[52:55], v[154:157], v[194:197], v[52:55]
	v_mfma_f32_16x16x32_bf16 v[44:47], v[162:165], v[194:197], v[44:47]
	v_mfma_f32_16x16x32_bf16 v[36:39], v[154:157], v[202:205], v[36:39]
	v_mfma_f32_16x16x32_bf16 v[28:31], v[162:165], v[202:205], v[28:31]
	v_mfma_f32_16x16x32_bf16 v[20:23], v[154:157], v[210:213], v[20:23]
	v_mfma_f32_16x16x32_bf16 v[12:15], v[162:165], v[210:213], v[12:15]
	v_mfma_f32_16x16x32_bf16 v[60:63], v[158:161], v[190:193], v[60:63]
	v_mfma_f32_16x16x32_bf16 v[56:59], v[166:169], v[190:193], v[56:59]
	v_mfma_f32_16x16x32_bf16 v[52:55], v[158:161], v[198:201], v[52:55]
	v_mfma_f32_16x16x32_bf16 v[44:47], v[166:169], v[198:201], v[44:47]
	v_mfma_f32_16x16x32_bf16 v[36:39], v[158:161], v[206:209], v[36:39]
	v_mfma_f32_16x16x32_bf16 v[28:31], v[166:169], v[206:209], v[28:31]
	v_mfma_f32_16x16x32_bf16 v[20:23], v[158:161], v[214:217], v[20:23]
	v_mfma_f32_16x16x32_bf16 v[12:15], v[166:169], v[214:217], v[12:15]
	v_mfma_f32_16x16x32_bf16 v[48:51], v[170:173], v[186:189], v[48:51]
	v_mfma_f32_16x16x32_bf16 v[40:43], v[178:181], v[186:189], v[40:43]
	v_mfma_f32_16x16x32_bf16 v[32:35], v[170:173], v[194:197], v[32:35]
	v_mfma_f32_16x16x32_bf16 v[24:27], v[178:181], v[194:197], v[24:27]
	v_mfma_f32_16x16x32_bf16 v[16:19], v[170:173], v[202:205], v[16:19]
	v_mfma_f32_16x16x32_bf16 v[8:11], v[178:181], v[202:205], v[8:11]
	v_mfma_f32_16x16x32_bf16 v[4:7], v[170:173], v[210:213], v[4:7]
	v_mfma_f32_16x16x32_bf16 v[0:3], v[178:181], v[210:213], v[0:3]
	v_mfma_f32_16x16x32_bf16 v[48:51], v[174:177], v[190:193], v[48:51]
	v_mfma_f32_16x16x32_bf16 v[40:43], v[182:185], v[190:193], v[40:43]
	v_mfma_f32_16x16x32_bf16 v[32:35], v[174:177], v[198:201], v[32:35]
	v_mfma_f32_16x16x32_bf16 v[24:27], v[182:185], v[198:201], v[24:27]
	v_mfma_f32_16x16x32_bf16 v[16:19], v[174:177], v[206:209], v[16:19]
	v_mfma_f32_16x16x32_bf16 v[8:11], v[182:185], v[206:209], v[8:11]
	v_mfma_f32_16x16x32_bf16 v[4:7], v[174:177], v[214:217], v[4:7]
	v_mfma_f32_16x16x32_bf16 v[0:3], v[182:185], v[214:217], v[0:3]
	s_barrier
	s_add_i32 s50, s50, 2
	s_add_u32 s28, s28, 0x100
	s_addc_u32 s29, s29, 0
	s_add_u32 s48, s48, 0x100
	s_addc_u32 s49, s49, 0
	s_cmp_gt_u32 s50, 29
	s_cbranch_scc0 .LBB0_363
	s_and_b64 vcc, exec, s[12:13]
	s_cbranch_vccz .LBB0_366
	s_barrier

.LBB0_530:
	ds_read_b128 v[150:153], v147
	ds_read_b128 v[154:157], v147 offset:1024
	ds_read_b128 v[158:161], v147 offset:2048
	ds_read_b128 v[162:165], v147 offset:3072
	ds_read_b128 v[166:169], v148
	ds_read_b128 v[170:173], v148 offset:1024
	ds_read_b128 v[174:177], v148 offset:2048
	ds_read_b128 v[178:181], v148 offset:3072
	s_add_u32 s22, s20, 0xfff80080
	s_addc_u32 s23, s21, -1
	s_cmp_eq_u32 s44, 28
	s_cselect_b32 s25, s11, s23
	s_cselect_b32 s24, s40, s22
	s_cselect_b32 s23, s13, s43
	s_cselect_b32 s22, s41, s42
	v_lshl_add_u64 v[214:215], s[20:21], 0, v[136:137]
	s_add_i32 m0, s19, 0xc000
	ds_read_b128 v[182:185], v149
	ds_read_b128 v[186:189], v149 offset:1024
	ds_read_b128 v[190:193], v149 offset:2048
	ds_read_b128 v[194:197], v149 offset:3072
	ds_read_b128 v[198:201], v149 offset:4096
	ds_read_b128 v[202:205], v149 offset:5120
	ds_read_b128 v[206:209], v149 offset:6144
	ds_read_b128 v[210:213], v149 offset:7168
	global_load_lds_dwordx4 v[214:215], off
	v_lshl_add_u64 v[214:215], s[20:21], 0, v[138:139]
	s_add_i32 m0, s19, 0xe000
	s_nop 0
	global_load_lds_dwordx4 v[214:215], off
	s_waitcnt vmcnt(8)
	s_waitcnt lgkmcnt(0)
	s_barrier
	v_mfma_f32_16x16x32_bf16 v[124:127], v[150:153], v[182:185], v[124:127]
	v_mfma_f32_16x16x32_bf16 v[120:123], v[158:161], v[182:185], v[120:123]
	v_mfma_f32_16x16x32_bf16 v[116:119], v[150:153], v[190:193], v[116:119]
	v_mfma_f32_16x16x32_bf16 v[108:111], v[158:161], v[190:193], v[108:111]
	v_mfma_f32_16x16x32_bf16 v[100:103], v[150:153], v[198:201], v[100:103]
	v_mfma_f32_16x16x32_bf16 v[92:95], v[158:161], v[198:201], v[92:95]
	v_mfma_f32_16x16x32_bf16 v[84:87], v[150:153], v[206:209], v[84:87]
	v_mfma_f32_16x16x32_bf16 v[76:79], v[158:161], v[206:209], v[76:79]
	v_mfma_f32_16x16x32_bf16 v[124:127], v[154:157], v[186:189], v[124:127]
	v_mfma_f32_16x16x32_bf16 v[120:123], v[162:165], v[186:189], v[120:123]
	v_mfma_f32_16x16x32_bf16 v[116:119], v[154:157], v[194:197], v[116:119]
	v_mfma_f32_16x16x32_bf16 v[108:111], v[162:165], v[194:197], v[108:111]
	v_mfma_f32_16x16x32_bf16 v[100:103], v[154:157], v[202:205], v[100:103]
	v_mfma_f32_16x16x32_bf16 v[92:95], v[162:165], v[202:205], v[92:95]
	v_mfma_f32_16x16x32_bf16 v[84:87], v[154:157], v[210:213], v[84:87]
	v_mfma_f32_16x16x32_bf16 v[76:79], v[162:165], v[210:213], v[76:79]
	v_mfma_f32_16x16x32_bf16 v[112:115], v[166:169], v[182:185], v[112:115]
	v_mfma_f32_16x16x32_bf16 v[104:107], v[174:177], v[182:185], v[104:107]
	v_mfma_f32_16x16x32_bf16 v[96:99], v[166:169], v[190:193], v[96:99]
	v_mfma_f32_16x16x32_bf16 v[88:91], v[174:177], v[190:193], v[88:91]
	v_mfma_f32_16x16x32_bf16 v[80:83], v[166:169], v[198:201], v[80:83]
	v_mfma_f32_16x16x32_bf16 v[72:75], v[174:177], v[198:201], v[72:75]
	v_mfma_f32_16x16x32_bf16 v[68:71], v[166:169], v[206:209], v[68:71]
	v_mfma_f32_16x16x32_bf16 v[64:67], v[174:177], v[206:209], v[64:67]
	v_mfma_f32_16x16x32_bf16 v[112:115], v[170:173], v[186:189], v[112:115]
	v_mfma_f32_16x16x32_bf16 v[104:107], v[178:181], v[186:189], v[104:107]
	v_mfma_f32_16x16x32_bf16 v[96:99], v[170:173], v[194:197], v[96:99]
	v_mfma_f32_16x16x32_bf16 v[88:91], v[178:181], v[194:197], v[88:91]
	v_mfma_f32_16x16x32_bf16 v[80:83], v[170:173], v[202:205], v[80:83]
	v_mfma_f32_16x16x32_bf16 v[72:75], v[178:181], v[202:205], v[72:75]
	v_mfma_f32_16x16x32_bf16 v[68:71], v[170:173], v[210:213], v[68:71]
	v_mfma_f32_16x16x32_bf16 v[64:67], v[178:181], v[210:213], v[64:67]
	s_barrier
	s_add_i32 s33, s35, s27
	v_lshl_add_u64 v[214:215], s[22:23], 0, v[130:131]
	s_mov_b32 m0, s33
	ds_read_b128 v[182:185], v149 offset:16384
	ds_read_b128 v[186:189], v149 offset:17408
	ds_read_b128 v[190:193], v149 offset:18432
	ds_read_b128 v[194:197], v149 offset:19456
	ds_read_b128 v[198:201], v149 offset:20480
	ds_read_b128 v[202:205], v149 offset:21504
	ds_read_b128 v[206:209], v149 offset:22528
	ds_read_b128 v[210:213], v149 offset:23552
	global_load_lds_dwordx4 v[214:215], off
	s_add_i32 m0, s33, 0x2000
	s_add_u32 s46, s22, 0x80000
	v_lshl_add_u64 v[216:217], s[22:23], 0, v[134:135]
	s_addc_u32 s47, s23, 0
	s_add_i32 s33, s37, s27
	global_load_lds_dwordx4 v[216:217], off
	v_lshl_add_u64 v[218:219], s[46:47], 0, v[130:131]
	s_mov_b32 m0, s33
	v_lshl_add_u64 v[222:223], s[24:25], 0, v[132:133]
	global_load_lds_dwordx4 v[218:219], off
	v_lshl_add_u64 v[218:219], s[46:47], 0, v[134:135]
	s_add_i32 m0, s33, 0x2000
	s_nop 0
	global_load_lds_dwordx4 v[218:219], off
	v_lshl_add_u64 v[218:219], s[24:25], 0, v[128:129]
	s_mov_b32 m0, s19
	s_nop 0
	global_load_lds_dwordx4 v[218:219], off
	s_mov_b32 m0, s28
	s_nop 0
	global_load_lds_dwordx4 v[222:223], off
	s_waitcnt vmcnt(8)
	s_waitcnt lgkmcnt(0)
	s_barrier
	v_mfma_f32_16x16x32_bf16 v[60:63], v[150:153], v[182:185], v[60:63]
	v_mfma_f32_16x16x32_bf16 v[56:59], v[158:161], v[182:185], v[56:59]
	v_mfma_f32_16x16x32_bf16 v[52:55], v[150:153], v[190:193], v[52:55]
	v_mfma_f32_16x16x32_bf16 v[44:47], v[158:161], v[190:193], v[44:47]
	v_mfma_f32_16x16x32_bf16 v[36:39], v[150:153], v[198:201], v[36:39]
	v_mfma_f32_16x16x32_bf16 v[28:31], v[158:161], v[198:201], v[28:31]
	v_mfma_f32_16x16x32_bf16 v[20:23], v[150:153], v[206:209], v[20:23]
	v_mfma_f32_16x16x32_bf16 v[12:15], v[158:161], v[206:209], v[12:15]
	v_mfma_f32_16x16x32_bf16 v[60:63], v[154:157], v[186:189], v[60:63]
	v_mfma_f32_16x16x32_bf16 v[56:59], v[162:165], v[186:189], v[56:59]
	v_mfma_f32_16x16x32_bf16 v[52:55], v[154:157], v[194:197], v[52:55]
	v_mfma_f32_16x16x32_bf16 v[44:47], v[162:165], v[194:197], v[44:47]
	v_mfma_f32_16x16x32_bf16 v[36:39], v[154:157], v[202:205], v[36:39]
	v_mfma_f32_16x16x32_bf16 v[28:31], v[162:165], v[202:205], v[28:31]
	v_mfma_f32_16x16x32_bf16 v[20:23], v[154:157], v[210:213], v[20:23]
	v_mfma_f32_16x16x32_bf16 v[12:15], v[162:165], v[210:213], v[12:15]
	v_mfma_f32_16x16x32_bf16 v[48:51], v[166:169], v[182:185], v[48:51]
	v_mfma_f32_16x16x32_bf16 v[40:43], v[174:177], v[182:185], v[40:43]
	v_mfma_f32_16x16x32_bf16 v[32:35], v[166:169], v[190:193], v[32:35]
	v_mfma_f32_16x16x32_bf16 v[24:27], v[174:177], v[190:193], v[24:27]
	v_mfma_f32_16x16x32_bf16 v[16:19], v[166:169], v[198:201], v[16:19]
	v_mfma_f32_16x16x32_bf16 v[8:11], v[174:177], v[198:201], v[8:11]
	v_mfma_f32_16x16x32_bf16 v[4:7], v[166:169], v[206:209], v[4:7]
	v_mfma_f32_16x16x32_bf16 v[0:3], v[174:177], v[206:209], v[0:3]
	v_mfma_f32_16x16x32_bf16 v[48:51], v[170:173], v[186:189], v[48:51]
	v_mfma_f32_16x16x32_bf16 v[40:43], v[178:181], v[186:189], v[40:43]
	v_mfma_f32_16x16x32_bf16 v[32:35], v[170:173], v[194:197], v[32:35]
	v_mfma_f32_16x16x32_bf16 v[24:27], v[178:181], v[194:197], v[24:27]
	v_mfma_f32_16x16x32_bf16 v[16:19], v[170:173], v[202:205], v[16:19]
	v_mfma_f32_16x16x32_bf16 v[8:11], v[178:181], v[202:205], v[8:11]
	v_mfma_f32_16x16x32_bf16 v[4:7], v[170:173], v[210:213], v[4:7]
	v_mfma_f32_16x16x32_bf16 v[0:3], v[178:181], v[210:213], v[0:3]
	s_barrier
	s_add_i32 s33, 0, 0x18000
	s_add_i32 s36, 0, 0x1c000
	v_add_u32_e32 v162, s33, v145
	v_add_u32_e32 v178, s36, v145
	ds_read_b128 v[150:153], v162
	ds_read_b128 v[154:157], v162 offset:1024
	ds_read_b128 v[158:161], v162 offset:2048
	ds_read_b128 v[162:165], v162 offset:3072
	ds_read_b128 v[166:169], v178
	ds_read_b128 v[170:173], v178 offset:1024
	ds_read_b128 v[174:177], v178 offset:2048
	ds_read_b128 v[178:181], v178 offset:3072
	s_add_u32 s24, s24, 0x80000
	s_addc_u32 s25, s25, 0
	s_mov_b32 m0, s29
	v_lshl_add_u64 v[224:225], s[24:25], 0, v[128:129]
	ds_read_b128 v[182:185], v149 offset:32768
	ds_read_b128 v[186:189], v149 offset:33792
	ds_read_b128 v[190:193], v149 offset:34816
	ds_read_b128 v[194:197], v149 offset:35840
	ds_read_b128 v[198:201], v149 offset:36864
	ds_read_b128 v[202:205], v149 offset:37888
	ds_read_b128 v[206:209], v149 offset:38912
	ds_read_b128 v[210:213], v149 offset:39936
	global_load_lds_dwordx4 v[224:225], off
	v_lshl_add_u64 v[224:225], s[24:25], 0, v[132:133]
	s_mov_b32 m0, s30
	s_nop 0
	global_load_lds_dwordx4 v[224:225], off
	s_waitcnt vmcnt(8)
	s_waitcnt lgkmcnt(0)
	s_barrier
	v_mfma_f32_16x16x32_bf16 v[124:127], v[150:153], v[182:185], v[124:127]
	v_mfma_f32_16x16x32_bf16 v[120:123], v[158:161], v[182:185], v[120:123]
	v_mfma_f32_16x16x32_bf16 v[116:119], v[150:153], v[190:193], v[116:119]
	v_mfma_f32_16x16x32_bf16 v[108:111], v[158:161], v[190:193], v[108:111]
	v_mfma_f32_16x16x32_bf16 v[100:103], v[150:153], v[198:201], v[100:103]
	v_mfma_f32_16x16x32_bf16 v[92:95], v[158:161], v[198:201], v[92:95]
	v_mfma_f32_16x16x32_bf16 v[84:87], v[150:153], v[206:209], v[84:87]
	v_mfma_f32_16x16x32_bf16 v[76:79], v[158:161], v[206:209], v[76:79]
	v_mfma_f32_16x16x32_bf16 v[124:127], v[154:157], v[186:189], v[124:127]
	v_mfma_f32_16x16x32_bf16 v[120:123], v[162:165], v[186:189], v[120:123]
	v_mfma_f32_16x16x32_bf16 v[116:119], v[154:157], v[194:197], v[116:119]
	v_mfma_f32_16x16x32_bf16 v[108:111], v[162:165], v[194:197], v[108:111]
	v_mfma_f32_16x16x32_bf16 v[100:103], v[154:157], v[202:205], v[100:103]
	v_mfma_f32_16x16x32_bf16 v[92:95], v[162:165], v[202:205], v[92:95]
	v_mfma_f32_16x16x32_bf16 v[84:87], v[154:157], v[210:213], v[84:87]
	v_mfma_f32_16x16x32_bf16 v[76:79], v[162:165], v[210:213], v[76:79]
	v_mfma_f32_16x16x32_bf16 v[112:115], v[166:169], v[182:185], v[112:115]
	v_mfma_f32_16x16x32_bf16 v[104:107], v[174:177], v[182:185], v[104:107]
	v_mfma_f32_16x16x32_bf16 v[96:99], v[166:169], v[190:193], v[96:99]
	v_mfma_f32_16x16x32_bf16 v[88:91], v[174:177], v[190:193], v[88:91]
	v_mfma_f32_16x16x32_bf16 v[80:83], v[166:169], v[198:201], v[80:83]
	v_mfma_f32_16x16x32_bf16 v[72:75], v[174:177], v[198:201], v[72:75]
	v_mfma_f32_16x16x32_bf16 v[68:71], v[166:169], v[206:209], v[68:71]
	v_mfma_f32_16x16x32_bf16 v[64:67], v[174:177], v[206:209], v[64:67]
	v_mfma_f32_16x16x32_bf16 v[112:115], v[170:173], v[186:189], v[112:115]
	v_mfma_f32_16x16x32_bf16 v[104:107], v[178:181], v[186:189], v[104:107]
	v_mfma_f32_16x16x32_bf16 v[96:99], v[170:173], v[194:197], v[96:99]
	v_mfma_f32_16x16x32_bf16 v[88:91], v[178:181], v[194:197], v[88:91]
	v_mfma_f32_16x16x32_bf16 v[80:83], v[170:173], v[202:205], v[80:83]
	v_mfma_f32_16x16x32_bf16 v[72:75], v[178:181], v[202:205], v[72:75]
	v_mfma_f32_16x16x32_bf16 v[68:71], v[170:173], v[210:213], v[68:71]
	v_mfma_f32_16x16x32_bf16 v[64:67], v[178:181], v[210:213], v[64:67]
	s_barrier
	s_add_i32 s24, s33, s27
	v_lshl_add_u64 v[214:215], v[214:215], 0, s[6:7]
	s_mov_b32 m0, s24
	ds_read_b128 v[182:185], v149 offset:49152
	ds_read_b128 v[186:189], v149 offset:50176
	ds_read_b128 v[190:193], v149 offset:51200
	ds_read_b128 v[194:197], v149 offset:52224
	ds_read_b128 v[198:201], v149 offset:53248
	ds_read_b128 v[202:205], v149 offset:54272
	ds_read_b128 v[206:209], v149 offset:55296
	ds_read_b128 v[210:213], v149 offset:56320
	global_load_lds_dwordx4 v[214:215], off
	s_add_i32 m0, s24, 0x2000
	s_add_u32 s22, s22, 0x80080
	v_lshl_add_u64 v[214:215], v[216:217], 0, s[6:7]
	s_addc_u32 s23, s23, 0
	s_add_i32 s24, s36, s27
	global_load_lds_dwordx4 v[214:215], off
	v_lshl_add_u64 v[214:215], s[22:23], 0, v[130:131]
	s_mov_b32 m0, s24
	s_nop 0
	global_load_lds_dwordx4 v[214:215], off
	v_lshl_add_u64 v[214:215], s[22:23], 0, v[134:135]
	s_add_i32 m0, s24, 0x2000
	s_nop 0
	global_load_lds_dwordx4 v[214:215], off
	v_lshl_add_u64 v[214:215], v[218:219], 0, s[6:7]
	s_mov_b32 m0, s31
	s_nop 0
	global_load_lds_dwordx4 v[214:215], off
	v_lshl_add_u64 v[214:215], v[222:223], 0, s[6:7]
	s_mov_b32 m0, s34
	s_nop 0
	global_load_lds_dwordx4 v[214:215], off
	s_waitcnt vmcnt(8)
	s_waitcnt lgkmcnt(0)
	s_barrier
	v_mfma_f32_16x16x32_bf16 v[60:63], v[150:153], v[182:185], v[60:63]
	v_mfma_f32_16x16x32_bf16 v[56:59], v[158:161], v[182:185], v[56:59]
	v_mfma_f32_16x16x32_bf16 v[52:55], v[150:153], v[190:193], v[52:55]
	v_mfma_f32_16x16x32_bf16 v[44:47], v[158:161], v[190:193], v[44:47]
	v_mfma_f32_16x16x32_bf16 v[36:39], v[150:153], v[198:201], v[36:39]
	v_mfma_f32_16x16x32_bf16 v[28:31], v[158:161], v[198:201], v[28:31]
	v_mfma_f32_16x16x32_bf16 v[20:23], v[150:153], v[206:209], v[20:23]
	v_mfma_f32_16x16x32_bf16 v[12:15], v[158:161], v[206:209], v[12:15]
	v_mfma_f32_16x16x32_bf16 v[60:63], v[154:157], v[186:189], v[60:63]
	v_mfma_f32_16x16x32_bf16 v[56:59], v[162:165], v[186:189], v[56:59]
	v_mfma_f32_16x16x32_bf16 v[52:55], v[154:157], v[194:197], v[52:55]
	v_mfma_f32_16x16x32_bf16 v[44:47], v[162:165], v[194:197], v[44:47]
	v_mfma_f32_16x16x32_bf16 v[36:39], v[154:157], v[202:205], v[36:39]
	v_mfma_f32_16x16x32_bf16 v[28:31], v[162:165], v[202:205], v[28:31]
	v_mfma_f32_16x16x32_bf16 v[20:23], v[154:157], v[210:213], v[20:23]
	v_mfma_f32_16x16x32_bf16 v[12:15], v[162:165], v[210:213], v[12:15]
	v_mfma_f32_16x16x32_bf16 v[48:51], v[166:169], v[182:185], v[48:51]
	v_mfma_f32_16x16x32_bf16 v[40:43], v[174:177], v[182:185], v[40:43]
	v_mfma_f32_16x16x32_bf16 v[32:35], v[166:169], v[190:193], v[32:35]
	v_mfma_f32_16x16x32_bf16 v[24:27], v[174:177], v[190:193], v[24:27]
	v_mfma_f32_16x16x32_bf16 v[16:19], v[166:169], v[198:201], v[16:19]
	v_mfma_f32_16x16x32_bf16 v[8:11], v[174:177], v[198:201], v[8:11]
	v_mfma_f32_16x16x32_bf16 v[4:7], v[166:169], v[206:209], v[4:7]
	v_mfma_f32_16x16x32_bf16 v[0:3], v[174:177], v[206:209], v[0:3]
	v_mfma_f32_16x16x32_bf16 v[48:51], v[170:173], v[186:189], v[48:51]
	v_mfma_f32_16x16x32_bf16 v[40:43], v[178:181], v[186:189], v[40:43]
	v_mfma_f32_16x16x32_bf16 v[32:35], v[170:173], v[194:197], v[32:35]
	v_mfma_f32_16x16x32_bf16 v[24:27], v[178:181], v[194:197], v[24:27]
	v_mfma_f32_16x16x32_bf16 v[16:19], v[170:173], v[202:205], v[16:19]
	v_mfma_f32_16x16x32_bf16 v[8:11], v[178:181], v[202:205], v[8:11]
	v_mfma_f32_16x16x32_bf16 v[4:7], v[170:173], v[210:213], v[4:7]
	v_mfma_f32_16x16x32_bf16 v[0:3], v[178:181], v[210:213], v[0:3]
	s_barrier
	s_add_i32 s44, s44, 2
	s_add_u32 s20, s20, 0x100
	s_addc_u32 s21, s21, 0
	s_add_u32 s42, s42, 0x100
	s_addc_u32 s43, s43, 0
	s_cmp_gt_u32 s44, 29
	s_cbranch_scc0 .LBB0_530
	s_and_b64 vcc, exec, s[8:9]
	s_cbranch_vccz .LBB0_533
	s_barrier

.LBB0_601:
	ds_read_b128 v[148:151], v145
	ds_read_b128 v[152:155], v145 offset:1024
	ds_read_b128 v[156:159], v145 offset:2048
	ds_read_b128 v[160:163], v145 offset:3072
	ds_read_b128 v[164:167], v146
	ds_read_b128 v[168:171], v146 offset:1024
	ds_read_b128 v[172:175], v146 offset:2048
	ds_read_b128 v[176:179], v146 offset:3072
	s_add_u32 s33, s34, 0xfff80080
	s_addc_u32 s36, s35, -1
	s_cmp_eq_u32 s56, 28
	s_cselect_b32 s39, s25, s36
	s_cselect_b32 s38, s52, s33
	s_cselect_b32 s37, s23, s55
	s_cselect_b32 s36, s53, s54
	v_lshl_add_u64 v[140:141], s[34:35], 0, v[132:133]
	s_add_i32 m0, s31, 0xc000
	ds_read_b128 v[180:183], v147
	ds_read_b128 v[184:187], v147 offset:1024
	ds_read_b128 v[188:191], v147 offset:2048
	ds_read_b128 v[192:195], v147 offset:3072
	ds_read_b128 v[196:199], v147 offset:4096
	ds_read_b128 v[200:203], v147 offset:5120
	ds_read_b128 v[204:207], v147 offset:6144
	ds_read_b128 v[208:211], v147 offset:7168
	global_load_lds_dwordx4 v[140:141], off
	v_lshl_add_u64 v[140:141], s[34:35], 0, v[134:135]
	s_add_i32 m0, s31, 0xe000
	s_nop 0
	global_load_lds_dwordx4 v[140:141], off
	s_waitcnt vmcnt(8)
	s_waitcnt lgkmcnt(0)
	s_barrier
	v_mfma_f32_16x16x32_bf16 v[124:127], v[148:151], v[180:183], v[124:127]
	v_mfma_f32_16x16x32_bf16 v[120:123], v[156:159], v[180:183], v[120:123]
	v_mfma_f32_16x16x32_bf16 v[112:115], v[148:151], v[188:191], v[112:115]
	v_mfma_f32_16x16x32_bf16 v[108:111], v[156:159], v[188:191], v[108:111]
	v_mfma_f32_16x16x32_bf16 v[96:99], v[148:151], v[196:199], v[96:99]
	v_mfma_f32_16x16x32_bf16 v[92:95], v[156:159], v[196:199], v[92:95]
	v_mfma_f32_16x16x32_bf16 v[80:83], v[148:151], v[204:207], v[80:83]
	v_mfma_f32_16x16x32_bf16 v[76:79], v[156:159], v[204:207], v[76:79]
	v_mfma_f32_16x16x32_bf16 v[124:127], v[152:155], v[184:187], v[124:127]
	v_mfma_f32_16x16x32_bf16 v[120:123], v[160:163], v[184:187], v[120:123]
	v_mfma_f32_16x16x32_bf16 v[112:115], v[152:155], v[192:195], v[112:115]
	v_mfma_f32_16x16x32_bf16 v[108:111], v[160:163], v[192:195], v[108:111]
	v_mfma_f32_16x16x32_bf16 v[96:99], v[152:155], v[200:203], v[96:99]
	v_mfma_f32_16x16x32_bf16 v[92:95], v[160:163], v[200:203], v[92:95]
	v_mfma_f32_16x16x32_bf16 v[80:83], v[152:155], v[208:211], v[80:83]
	v_mfma_f32_16x16x32_bf16 v[76:79], v[160:163], v[208:211], v[76:79]
	v_mfma_f32_16x16x32_bf16 v[116:119], v[164:167], v[180:183], v[116:119]
	v_mfma_f32_16x16x32_bf16 v[104:107], v[172:175], v[180:183], v[104:107]
	v_mfma_f32_16x16x32_bf16 v[100:103], v[164:167], v[188:191], v[100:103]
	v_mfma_f32_16x16x32_bf16 v[88:91], v[172:175], v[188:191], v[88:91]
	v_mfma_f32_16x16x32_bf16 v[84:87], v[164:167], v[196:199], v[84:87]
	v_mfma_f32_16x16x32_bf16 v[72:75], v[172:175], v[196:199], v[72:75]
	v_mfma_f32_16x16x32_bf16 v[68:71], v[164:167], v[204:207], v[68:71]
	v_mfma_f32_16x16x32_bf16 v[64:67], v[172:175], v[204:207], v[64:67]
	v_mfma_f32_16x16x32_bf16 v[116:119], v[168:171], v[184:187], v[116:119]
	v_mfma_f32_16x16x32_bf16 v[104:107], v[176:179], v[184:187], v[104:107]
	v_mfma_f32_16x16x32_bf16 v[100:103], v[168:171], v[192:195], v[100:103]
	v_mfma_f32_16x16x32_bf16 v[88:91], v[176:179], v[192:195], v[88:91]
	v_mfma_f32_16x16x32_bf16 v[84:87], v[168:171], v[200:203], v[84:87]
	v_mfma_f32_16x16x32_bf16 v[72:75], v[176:179], v[200:203], v[72:75]
	v_mfma_f32_16x16x32_bf16 v[68:71], v[168:171], v[208:211], v[68:71]
	v_mfma_f32_16x16x32_bf16 v[64:67], v[176:179], v[208:211], v[64:67]
	s_barrier
	s_add_i32 s33, s49, s41
	v_lshl_add_u64 v[140:141], s[36:37], 0, v[128:129]
	s_mov_b32 m0, s33
	ds_read_b128 v[180:183], v147 offset:16384
	ds_read_b128 v[184:187], v147 offset:17408
	ds_read_b128 v[188:191], v147 offset:18432
	ds_read_b128 v[192:195], v147 offset:19456
	ds_read_b128 v[196:199], v147 offset:20480
	ds_read_b128 v[200:203], v147 offset:21504
	ds_read_b128 v[204:207], v147 offset:22528
	ds_read_b128 v[208:211], v147 offset:23552
	global_load_lds_dwordx4 v[140:141], off
	s_add_i32 m0, s33, 0x2000
	s_add_u32 s58, s36, 0x80000
	v_lshl_add_u64 v[212:213], s[36:37], 0, v[130:131]
	s_addc_u32 s59, s37, 0
	s_add_i32 s33, s50, s41
	global_load_lds_dwordx4 v[212:213], off
	v_lshl_add_u64 v[214:215], s[58:59], 0, v[128:129]
	s_mov_b32 m0, s33
	v_lshl_add_u64 v[216:217], s[38:39], 0, v[130:131]
	global_load_lds_dwordx4 v[214:215], off
	v_lshl_add_u64 v[214:215], s[58:59], 0, v[130:131]
	s_add_i32 m0, s33, 0x2000
	s_nop 0
	global_load_lds_dwordx4 v[214:215], off
	v_lshl_add_u64 v[214:215], s[38:39], 0, v[128:129]
	s_mov_b32 m0, s31
	s_nop 0
	global_load_lds_dwordx4 v[214:215], off
	s_mov_b32 m0, s42
	s_nop 0
	global_load_lds_dwordx4 v[216:217], off
	s_waitcnt vmcnt(8)
	s_waitcnt lgkmcnt(0)
	s_barrier
	v_mfma_f32_16x16x32_bf16 v[60:63], v[148:151], v[180:183], v[60:63]
	v_mfma_f32_16x16x32_bf16 v[56:59], v[156:159], v[180:183], v[56:59]
	v_mfma_f32_16x16x32_bf16 v[48:51], v[148:151], v[188:191], v[48:51]
	v_mfma_f32_16x16x32_bf16 v[44:47], v[156:159], v[188:191], v[44:47]
	v_mfma_f32_16x16x32_bf16 v[32:35], v[148:151], v[196:199], v[32:35]
	v_mfma_f32_16x16x32_bf16 v[28:31], v[156:159], v[196:199], v[28:31]
	v_mfma_f32_16x16x32_bf16 v[16:19], v[148:151], v[204:207], v[16:19]
	v_mfma_f32_16x16x32_bf16 v[12:15], v[156:159], v[204:207], v[12:15]
	v_mfma_f32_16x16x32_bf16 v[60:63], v[152:155], v[184:187], v[60:63]
	v_mfma_f32_16x16x32_bf16 v[56:59], v[160:163], v[184:187], v[56:59]
	v_mfma_f32_16x16x32_bf16 v[48:51], v[152:155], v[192:195], v[48:51]
	v_mfma_f32_16x16x32_bf16 v[44:47], v[160:163], v[192:195], v[44:47]
	v_mfma_f32_16x16x32_bf16 v[32:35], v[152:155], v[200:203], v[32:35]
	v_mfma_f32_16x16x32_bf16 v[28:31], v[160:163], v[200:203], v[28:31]
	v_mfma_f32_16x16x32_bf16 v[16:19], v[152:155], v[208:211], v[16:19]
	v_mfma_f32_16x16x32_bf16 v[12:15], v[160:163], v[208:211], v[12:15]
	v_mfma_f32_16x16x32_bf16 v[52:55], v[164:167], v[180:183], v[52:55]
	v_mfma_f32_16x16x32_bf16 v[40:43], v[172:175], v[180:183], v[40:43]
	v_mfma_f32_16x16x32_bf16 v[36:39], v[164:167], v[188:191], v[36:39]
	v_mfma_f32_16x16x32_bf16 v[24:27], v[172:175], v[188:191], v[24:27]
	v_mfma_f32_16x16x32_bf16 v[20:23], v[164:167], v[196:199], v[20:23]
	v_mfma_f32_16x16x32_bf16 v[8:11], v[172:175], v[196:199], v[8:11]
	v_mfma_f32_16x16x32_bf16 v[4:7], v[164:167], v[204:207], v[4:7]
	v_mfma_f32_16x16x32_bf16 v[0:3], v[172:175], v[204:207], v[0:3]
	v_mfma_f32_16x16x32_bf16 v[52:55], v[168:171], v[184:187], v[52:55]
	v_mfma_f32_16x16x32_bf16 v[40:43], v[176:179], v[184:187], v[40:43]
	v_mfma_f32_16x16x32_bf16 v[36:39], v[168:171], v[192:195], v[36:39]
	v_mfma_f32_16x16x32_bf16 v[24:27], v[176:179], v[192:195], v[24:27]
	v_mfma_f32_16x16x32_bf16 v[20:23], v[168:171], v[200:203], v[20:23]
	v_mfma_f32_16x16x32_bf16 v[8:11], v[176:179], v[200:203], v[8:11]
	v_mfma_f32_16x16x32_bf16 v[4:7], v[168:171], v[208:211], v[4:7]
	v_mfma_f32_16x16x32_bf16 v[0:3], v[176:179], v[208:211], v[0:3]
	s_barrier
	s_add_i32 s33, 0, 0x18000
	s_add_i32 s57, 0, 0x1c000
	v_add_u32_e32 v160, s33, v143
	v_add_u32_e32 v176, s57, v143
	ds_read_b128 v[148:151], v160
	ds_read_b128 v[152:155], v160 offset:1024
	ds_read_b128 v[156:159], v160 offset:2048
	ds_read_b128 v[160:163], v160 offset:3072
	ds_read_b128 v[164:167], v176
	ds_read_b128 v[168:171], v176 offset:1024
	ds_read_b128 v[172:175], v176 offset:2048
	ds_read_b128 v[176:179], v176 offset:3072
	s_add_u32 s38, s38, 0x80000
	s_addc_u32 s39, s39, 0
	s_mov_b32 m0, s43
	v_lshl_add_u64 v[218:219], s[38:39], 0, v[128:129]
	ds_read_b128 v[180:183], v147 offset:32768
	ds_read_b128 v[184:187], v147 offset:33792
	ds_read_b128 v[188:191], v147 offset:34816
	ds_read_b128 v[192:195], v147 offset:35840
	ds_read_b128 v[196:199], v147 offset:36864
	ds_read_b128 v[200:203], v147 offset:37888
	ds_read_b128 v[204:207], v147 offset:38912
	ds_read_b128 v[208:211], v147 offset:39936
	global_load_lds_dwordx4 v[218:219], off
	v_lshl_add_u64 v[218:219], s[38:39], 0, v[130:131]
	s_mov_b32 m0, s44
	s_nop 0
	global_load_lds_dwordx4 v[218:219], off
	s_waitcnt vmcnt(8)
	s_waitcnt lgkmcnt(0)
	s_barrier
	v_mfma_f32_16x16x32_bf16 v[124:127], v[148:151], v[180:183], v[124:127]
	v_mfma_f32_16x16x32_bf16 v[120:123], v[156:159], v[180:183], v[120:123]
	v_mfma_f32_16x16x32_bf16 v[112:115], v[148:151], v[188:191], v[112:115]
	v_mfma_f32_16x16x32_bf16 v[108:111], v[156:159], v[188:191], v[108:111]
	v_mfma_f32_16x16x32_bf16 v[96:99], v[148:151], v[196:199], v[96:99]
	v_mfma_f32_16x16x32_bf16 v[92:95], v[156:159], v[196:199], v[92:95]
	v_mfma_f32_16x16x32_bf16 v[80:83], v[148:151], v[204:207], v[80:83]
	v_mfma_f32_16x16x32_bf16 v[76:79], v[156:159], v[204:207], v[76:79]
	v_mfma_f32_16x16x32_bf16 v[124:127], v[152:155], v[184:187], v[124:127]
	v_mfma_f32_16x16x32_bf16 v[120:123], v[160:163], v[184:187], v[120:123]
	v_mfma_f32_16x16x32_bf16 v[112:115], v[152:155], v[192:195], v[112:115]
	v_mfma_f32_16x16x32_bf16 v[108:111], v[160:163], v[192:195], v[108:111]
	v_mfma_f32_16x16x32_bf16 v[96:99], v[152:155], v[200:203], v[96:99]
	v_mfma_f32_16x16x32_bf16 v[92:95], v[160:163], v[200:203], v[92:95]
	v_mfma_f32_16x16x32_bf16 v[80:83], v[152:155], v[208:211], v[80:83]
	v_mfma_f32_16x16x32_bf16 v[76:79], v[160:163], v[208:211], v[76:79]
	v_mfma_f32_16x16x32_bf16 v[116:119], v[164:167], v[180:183], v[116:119]
	v_mfma_f32_16x16x32_bf16 v[104:107], v[172:175], v[180:183], v[104:107]
	v_mfma_f32_16x16x32_bf16 v[100:103], v[164:167], v[188:191], v[100:103]
	v_mfma_f32_16x16x32_bf16 v[88:91], v[172:175], v[188:191], v[88:91]
	v_mfma_f32_16x16x32_bf16 v[84:87], v[164:167], v[196:199], v[84:87]
	v_mfma_f32_16x16x32_bf16 v[72:75], v[172:175], v[196:199], v[72:75]
	v_mfma_f32_16x16x32_bf16 v[68:71], v[164:167], v[204:207], v[68:71]
	v_mfma_f32_16x16x32_bf16 v[64:67], v[172:175], v[204:207], v[64:67]
	v_mfma_f32_16x16x32_bf16 v[116:119], v[168:171], v[184:187], v[116:119]
	v_mfma_f32_16x16x32_bf16 v[104:107], v[176:179], v[184:187], v[104:107]
	v_mfma_f32_16x16x32_bf16 v[100:103], v[168:171], v[192:195], v[100:103]
	v_mfma_f32_16x16x32_bf16 v[88:91], v[176:179], v[192:195], v[88:91]
	v_mfma_f32_16x16x32_bf16 v[84:87], v[168:171], v[200:203], v[84:87]
	v_mfma_f32_16x16x32_bf16 v[72:75], v[176:179], v[200:203], v[72:75]
	v_mfma_f32_16x16x32_bf16 v[68:71], v[168:171], v[208:211], v[68:71]
	v_mfma_f32_16x16x32_bf16 v[64:67], v[176:179], v[208:211], v[64:67]
	s_barrier
	s_add_i32 s33, s33, s41
	v_lshl_add_u64 v[140:141], v[140:141], 0, s[6:7]
	s_mov_b32 m0, s33
	ds_read_b128 v[180:183], v147 offset:49152
	ds_read_b128 v[184:187], v147 offset:50176
	ds_read_b128 v[188:191], v147 offset:51200
	ds_read_b128 v[192:195], v147 offset:52224
	ds_read_b128 v[196:199], v147 offset:53248
	ds_read_b128 v[200:203], v147 offset:54272
	ds_read_b128 v[204:207], v147 offset:55296
	ds_read_b128 v[208:211], v147 offset:56320
	global_load_lds_dwordx4 v[140:141], off
	s_add_i32 m0, s33, 0x2000
	s_add_u32 s36, s36, 0x80080
	v_lshl_add_u64 v[140:141], v[212:213], 0, s[6:7]
	s_addc_u32 s37, s37, 0
	s_add_i32 s33, s57, s41
	global_load_lds_dwordx4 v[140:141], off
	v_lshl_add_u64 v[140:141], s[36:37], 0, v[128:129]
	s_mov_b32 m0, s33
	s_nop 0
	global_load_lds_dwordx4 v[140:141], off
	v_lshl_add_u64 v[140:141], s[36:37], 0, v[130:131]
	s_add_i32 m0, s33, 0x2000
	s_nop 0
	global_load_lds_dwordx4 v[140:141], off
	v_lshl_add_u64 v[140:141], v[214:215], 0, s[6:7]
	s_mov_b32 m0, s46
	s_nop 0
	global_load_lds_dwordx4 v[140:141], off
	v_lshl_add_u64 v[140:141], v[216:217], 0, s[6:7]
	s_mov_b32 m0, s47
	s_nop 0
	global_load_lds_dwordx4 v[140:141], off
	s_waitcnt vmcnt(8)
	s_waitcnt lgkmcnt(0)
	s_barrier
	v_mfma_f32_16x16x32_bf16 v[60:63], v[148:151], v[180:183], v[60:63]
	v_mfma_f32_16x16x32_bf16 v[56:59], v[156:159], v[180:183], v[56:59]
	v_mfma_f32_16x16x32_bf16 v[48:51], v[148:151], v[188:191], v[48:51]
	v_mfma_f32_16x16x32_bf16 v[44:47], v[156:159], v[188:191], v[44:47]
	v_mfma_f32_16x16x32_bf16 v[32:35], v[148:151], v[196:199], v[32:35]
	v_mfma_f32_16x16x32_bf16 v[28:31], v[156:159], v[196:199], v[28:31]
	v_mfma_f32_16x16x32_bf16 v[16:19], v[148:151], v[204:207], v[16:19]
	v_mfma_f32_16x16x32_bf16 v[12:15], v[156:159], v[204:207], v[12:15]
	v_mfma_f32_16x16x32_bf16 v[60:63], v[152:155], v[184:187], v[60:63]
	v_mfma_f32_16x16x32_bf16 v[56:59], v[160:163], v[184:187], v[56:59]
	v_mfma_f32_16x16x32_bf16 v[48:51], v[152:155], v[192:195], v[48:51]
	v_mfma_f32_16x16x32_bf16 v[44:47], v[160:163], v[192:195], v[44:47]
	v_mfma_f32_16x16x32_bf16 v[32:35], v[152:155], v[200:203], v[32:35]
	v_mfma_f32_16x16x32_bf16 v[28:31], v[160:163], v[200:203], v[28:31]
	v_mfma_f32_16x16x32_bf16 v[16:19], v[152:155], v[208:211], v[16:19]
	v_mfma_f32_16x16x32_bf16 v[12:15], v[160:163], v[208:211], v[12:15]
	v_mfma_f32_16x16x32_bf16 v[52:55], v[164:167], v[180:183], v[52:55]
	v_mfma_f32_16x16x32_bf16 v[40:43], v[172:175], v[180:183], v[40:43]
	v_mfma_f32_16x16x32_bf16 v[36:39], v[164:167], v[188:191], v[36:39]
	v_mfma_f32_16x16x32_bf16 v[24:27], v[172:175], v[188:191], v[24:27]
	v_mfma_f32_16x16x32_bf16 v[20:23], v[164:167], v[196:199], v[20:23]
	v_mfma_f32_16x16x32_bf16 v[8:11], v[172:175], v[196:199], v[8:11]
	v_mfma_f32_16x16x32_bf16 v[4:7], v[164:167], v[204:207], v[4:7]
	v_mfma_f32_16x16x32_bf16 v[0:3], v[172:175], v[204:207], v[0:3]
	v_mfma_f32_16x16x32_bf16 v[52:55], v[168:171], v[184:187], v[52:55]
	v_mfma_f32_16x16x32_bf16 v[40:43], v[176:179], v[184:187], v[40:43]
	v_mfma_f32_16x16x32_bf16 v[36:39], v[168:171], v[192:195], v[36:39]
	v_mfma_f32_16x16x32_bf16 v[24:27], v[176:179], v[192:195], v[24:27]
	v_mfma_f32_16x16x32_bf16 v[20:23], v[168:171], v[200:203], v[20:23]
	v_mfma_f32_16x16x32_bf16 v[8:11], v[176:179], v[200:203], v[8:11]
	v_mfma_f32_16x16x32_bf16 v[4:7], v[168:171], v[208:211], v[4:7]
	v_mfma_f32_16x16x32_bf16 v[0:3], v[176:179], v[208:211], v[0:3]
	s_barrier
	s_add_i32 s56, s56, 2
	s_add_u32 s34, s34, 0x100
	s_addc_u32 s35, s35, 0
	s_add_u32 s54, s54, 0x100
	s_addc_u32 s55, s55, 0
	s_cmp_gt_u32 s56, 29
	s_cbranch_scc0 .LBB0_601
	s_and_b64 vcc, exec, s[10:11]
	s_cbranch_vccz .LBB0_604
	s_barrier

.LBB0_625:
	v_add_u32_e32 v147, s45, v145
	ds_read_b128 v[148:151], v147
	ds_read_b128 v[152:155], v147 offset:1024
	ds_read_b128 v[156:159], v147 offset:2048
	ds_read_b128 v[160:163], v147 offset:3072
	v_add_u32_e32 v147, s46, v145
	s_add_u32 s26, s10, s24
	ds_read_b128 v[164:167], v147
	ds_read_b128 v[168:171], v147 offset:1024
	ds_read_b128 v[172:175], v147 offset:2048
	ds_read_b128 v[178:181], v147 offset:3072
	s_addc_u32 s27, s11, s25
	s_add_u32 s26, s26, 0x100
	s_addc_u32 s27, s27, 0
	s_add_u32 s33, s21, s24
	s_addc_u32 s51, s47, s25
	s_cmpk_eq_i32 s24, 0xf00
	s_cselect_b32 s29, s17, s27
	s_cselect_b32 s28, s48, s26
	s_cselect_b32 s27, s15, s51
	s_cselect_b32 s26, s49, s33
	v_lshl_add_u64 v[214:215], v[140:141], 0, s[24:25]
	s_add_i32 m0, s37, 0xc000
	ds_read_b128 v[182:185], v146
	ds_read_b128 v[186:189], v146 offset:1024
	ds_read_b128 v[190:193], v146 offset:2048
	ds_read_b128 v[194:197], v146 offset:3072
	ds_read_b128 v[198:201], v146 offset:4096
	ds_read_b128 v[202:205], v146 offset:5120
	ds_read_b128 v[206:209], v146 offset:6144
	ds_read_b128 v[210:213], v146 offset:7168
	global_load_lds_dwordx4 v[214:215], off
	v_lshl_add_u64 v[214:215], v[142:143], 0, s[24:25]
	s_add_i32 m0, s37, 0xe000
	s_nop 0
	global_load_lds_dwordx4 v[214:215], off
	s_waitcnt vmcnt(8)
	s_waitcnt lgkmcnt(0)
	s_barrier
	v_mfma_f32_16x16x32_bf16 v[124:127], v[148:151], v[182:185], v[124:127]
	v_mfma_f32_16x16x32_bf16 v[120:123], v[156:159], v[182:185], v[120:123]
	v_mfma_f32_16x16x32_bf16 v[108:111], v[148:151], v[190:193], v[108:111]
	v_mfma_f32_16x16x32_bf16 v[104:107], v[156:159], v[190:193], v[104:107]
	v_mfma_f32_16x16x32_bf16 v[92:95], v[148:151], v[198:201], v[92:95]
	v_mfma_f32_16x16x32_bf16 v[88:91], v[156:159], v[198:201], v[88:91]
	v_mfma_f32_16x16x32_bf16 v[76:79], v[148:151], v[206:209], v[76:79]
	v_mfma_f32_16x16x32_bf16 v[72:75], v[156:159], v[206:209], v[72:75]
	v_mfma_f32_16x16x32_bf16 v[124:127], v[152:155], v[186:189], v[124:127]
	v_mfma_f32_16x16x32_bf16 v[120:123], v[160:163], v[186:189], v[120:123]
	v_mfma_f32_16x16x32_bf16 v[108:111], v[152:155], v[194:197], v[108:111]
	v_mfma_f32_16x16x32_bf16 v[104:107], v[160:163], v[194:197], v[104:107]
	v_mfma_f32_16x16x32_bf16 v[92:95], v[152:155], v[202:205], v[92:95]
	v_mfma_f32_16x16x32_bf16 v[88:91], v[160:163], v[202:205], v[88:91]
	v_mfma_f32_16x16x32_bf16 v[76:79], v[152:155], v[210:213], v[76:79]
	v_mfma_f32_16x16x32_bf16 v[72:75], v[160:163], v[210:213], v[72:75]
	v_mfma_f32_16x16x32_bf16 v[116:119], v[164:167], v[182:185], v[116:119]
	v_mfma_f32_16x16x32_bf16 v[112:115], v[172:175], v[182:185], v[112:115]
	v_mfma_f32_16x16x32_bf16 v[100:103], v[164:167], v[190:193], v[100:103]
	v_mfma_f32_16x16x32_bf16 v[96:99], v[172:175], v[190:193], v[96:99]
	v_mfma_f32_16x16x32_bf16 v[84:87], v[164:167], v[198:201], v[84:87]
	v_mfma_f32_16x16x32_bf16 v[80:83], v[172:175], v[198:201], v[80:83]
	v_mfma_f32_16x16x32_bf16 v[68:71], v[164:167], v[206:209], v[68:71]
	v_mfma_f32_16x16x32_bf16 v[64:67], v[172:175], v[206:209], v[64:67]
	v_mfma_f32_16x16x32_bf16 v[116:119], v[168:171], v[186:189], v[116:119]
	v_mfma_f32_16x16x32_bf16 v[112:115], v[178:181], v[186:189], v[112:115]
	v_mfma_f32_16x16x32_bf16 v[100:103], v[168:171], v[194:197], v[100:103]
	v_mfma_f32_16x16x32_bf16 v[96:99], v[178:181], v[194:197], v[96:99]
	v_mfma_f32_16x16x32_bf16 v[84:87], v[168:171], v[202:205], v[84:87]
	v_mfma_f32_16x16x32_bf16 v[80:83], v[178:181], v[202:205], v[80:83]
	v_mfma_f32_16x16x32_bf16 v[68:71], v[168:171], v[210:213], v[68:71]
	v_mfma_f32_16x16x32_bf16 v[64:67], v[178:181], v[210:213], v[64:67]
	s_barrier
	s_add_i32 s33, s45, s36
	v_lshl_add_u64 v[214:215], s[26:27], 0, v[128:129]
	s_mov_b32 m0, s33
	ds_read_b128 v[182:185], v146 offset:16384
	ds_read_b128 v[186:189], v146 offset:17408
	ds_read_b128 v[190:193], v146 offset:18432
	ds_read_b128 v[194:197], v146 offset:19456
	ds_read_b128 v[198:201], v146 offset:20480
	ds_read_b128 v[202:205], v146 offset:21504
	ds_read_b128 v[206:209], v146 offset:22528
	ds_read_b128 v[210:213], v146 offset:23552
	global_load_lds_dwordx4 v[214:215], off
	s_add_i32 m0, s33, 0x2000
	s_add_u32 s52, s26, 0x80000
	v_lshl_add_u64 v[216:217], s[26:27], 0, v[130:131]
	s_addc_u32 s53, s27, 0
	s_add_i32 s33, s46, s36
	global_load_lds_dwordx4 v[216:217], off
	v_lshl_add_u64 v[218:219], s[52:53], 0, v[128:129]
	s_mov_b32 m0, s33
	v_lshl_add_u64 v[222:223], s[28:29], 0, v[130:131]
	global_load_lds_dwordx4 v[218:219], off
	v_lshl_add_u64 v[218:219], s[52:53], 0, v[130:131]
	s_add_i32 m0, s33, 0x2000
	s_nop 0
	global_load_lds_dwordx4 v[218:219], off
	v_lshl_add_u64 v[218:219], s[28:29], 0, v[128:129]
	s_mov_b32 m0, s37
	s_nop 0
	global_load_lds_dwordx4 v[218:219], off
	s_mov_b32 m0, s38
	s_nop 0
	global_load_lds_dwordx4 v[222:223], off
	s_waitcnt vmcnt(8)
	s_waitcnt lgkmcnt(0)
	s_barrier
	v_mfma_f32_16x16x32_bf16 v[60:63], v[148:151], v[182:185], v[60:63]
	v_mfma_f32_16x16x32_bf16 v[56:59], v[156:159], v[182:185], v[56:59]
	v_mfma_f32_16x16x32_bf16 v[44:47], v[148:151], v[190:193], v[44:47]
	v_mfma_f32_16x16x32_bf16 v[40:43], v[156:159], v[190:193], v[40:43]
	v_mfma_f32_16x16x32_bf16 v[28:31], v[148:151], v[198:201], v[28:31]
	v_mfma_f32_16x16x32_bf16 v[24:27], v[156:159], v[198:201], v[24:27]
	v_mfma_f32_16x16x32_bf16 v[12:15], v[148:151], v[206:209], v[12:15]
	v_mfma_f32_16x16x32_bf16 v[8:11], v[156:159], v[206:209], v[8:11]
	v_mfma_f32_16x16x32_bf16 v[60:63], v[152:155], v[186:189], v[60:63]
	v_mfma_f32_16x16x32_bf16 v[56:59], v[160:163], v[186:189], v[56:59]
	v_mfma_f32_16x16x32_bf16 v[44:47], v[152:155], v[194:197], v[44:47]
	v_mfma_f32_16x16x32_bf16 v[40:43], v[160:163], v[194:197], v[40:43]
	v_mfma_f32_16x16x32_bf16 v[28:31], v[152:155], v[202:205], v[28:31]
	v_mfma_f32_16x16x32_bf16 v[24:27], v[160:163], v[202:205], v[24:27]
	v_mfma_f32_16x16x32_bf16 v[12:15], v[152:155], v[210:213], v[12:15]
	v_mfma_f32_16x16x32_bf16 v[8:11], v[160:163], v[210:213], v[8:11]
	v_mfma_f32_16x16x32_bf16 v[52:55], v[164:167], v[182:185], v[52:55]
	v_mfma_f32_16x16x32_bf16 v[48:51], v[172:175], v[182:185], v[48:51]
	v_mfma_f32_16x16x32_bf16 v[36:39], v[164:167], v[190:193], v[36:39]
	v_mfma_f32_16x16x32_bf16 v[32:35], v[172:175], v[190:193], v[32:35]
	v_mfma_f32_16x16x32_bf16 v[20:23], v[164:167], v[198:201], v[20:23]
	v_mfma_f32_16x16x32_bf16 v[16:19], v[172:175], v[198:201], v[16:19]
	v_mfma_f32_16x16x32_bf16 v[4:7], v[164:167], v[206:209], v[4:7]
	v_mfma_f32_16x16x32_bf16 v[0:3], v[172:175], v[206:209], v[0:3]
	v_mfma_f32_16x16x32_bf16 v[52:55], v[168:171], v[186:189], v[52:55]
	v_mfma_f32_16x16x32_bf16 v[48:51], v[178:181], v[186:189], v[48:51]
	v_mfma_f32_16x16x32_bf16 v[36:39], v[168:171], v[194:197], v[36:39]
	v_mfma_f32_16x16x32_bf16 v[32:35], v[178:181], v[194:197], v[32:35]
	v_mfma_f32_16x16x32_bf16 v[20:23], v[168:171], v[202:205], v[20:23]
	v_mfma_f32_16x16x32_bf16 v[16:19], v[178:181], v[202:205], v[16:19]
	v_mfma_f32_16x16x32_bf16 v[4:7], v[168:171], v[210:213], v[4:7]
	v_mfma_f32_16x16x32_bf16 v[0:3], v[178:181], v[210:213], v[0:3]
	s_barrier
	s_add_i32 s33, 0, 0x18000
	v_add_u32_e32 v147, s33, v145
	s_add_i32 s51, 0, 0x1c000
	ds_read_b128 v[148:151], v147
	ds_read_b128 v[152:155], v147 offset:1024
	ds_read_b128 v[156:159], v147 offset:2048
	ds_read_b128 v[160:163], v147 offset:3072
	v_add_u32_e32 v147, s51, v145
	ds_read_b128 v[164:167], v147
	ds_read_b128 v[168:171], v147 offset:1024
	ds_read_b128 v[172:175], v147 offset:2048
	ds_read_b128 v[178:181], v147 offset:3072
	s_add_u32 s28, s28, 0x80000
	s_addc_u32 s29, s29, 0
	s_mov_b32 m0, s39
	v_lshl_add_u64 v[224:225], s[28:29], 0, v[128:129]
	ds_read_b128 v[182:185], v146 offset:32768
	ds_read_b128 v[186:189], v146 offset:33792
	ds_read_b128 v[190:193], v146 offset:34816
	ds_read_b128 v[194:197], v146 offset:35840
	ds_read_b128 v[198:201], v146 offset:36864
	ds_read_b128 v[202:205], v146 offset:37888
	ds_read_b128 v[206:209], v146 offset:38912
	ds_read_b128 v[210:213], v146 offset:39936
	global_load_lds_dwordx4 v[224:225], off
	v_lshl_add_u64 v[224:225], s[28:29], 0, v[130:131]
	s_mov_b32 m0, s41
	s_nop 0
	global_load_lds_dwordx4 v[224:225], off
	s_waitcnt vmcnt(8)
	s_waitcnt lgkmcnt(0)
	s_barrier
	v_mfma_f32_16x16x32_bf16 v[124:127], v[148:151], v[182:185], v[124:127]
	v_mfma_f32_16x16x32_bf16 v[120:123], v[156:159], v[182:185], v[120:123]
	v_mfma_f32_16x16x32_bf16 v[108:111], v[148:151], v[190:193], v[108:111]
	v_mfma_f32_16x16x32_bf16 v[104:107], v[156:159], v[190:193], v[104:107]
	v_mfma_f32_16x16x32_bf16 v[92:95], v[148:151], v[198:201], v[92:95]
	v_mfma_f32_16x16x32_bf16 v[88:91], v[156:159], v[198:201], v[88:91]
	v_mfma_f32_16x16x32_bf16 v[76:79], v[148:151], v[206:209], v[76:79]
	v_mfma_f32_16x16x32_bf16 v[72:75], v[156:159], v[206:209], v[72:75]
	v_mfma_f32_16x16x32_bf16 v[124:127], v[152:155], v[186:189], v[124:127]
	v_mfma_f32_16x16x32_bf16 v[120:123], v[160:163], v[186:189], v[120:123]
	v_mfma_f32_16x16x32_bf16 v[108:111], v[152:155], v[194:197], v[108:111]
	v_mfma_f32_16x16x32_bf16 v[104:107], v[160:163], v[194:197], v[104:107]
	v_mfma_f32_16x16x32_bf16 v[92:95], v[152:155], v[202:205], v[92:95]
	v_mfma_f32_16x16x32_bf16 v[88:91], v[160:163], v[202:205], v[88:91]
	v_mfma_f32_16x16x32_bf16 v[76:79], v[152:155], v[210:213], v[76:79]
	v_mfma_f32_16x16x32_bf16 v[72:75], v[160:163], v[210:213], v[72:75]
	v_mfma_f32_16x16x32_bf16 v[116:119], v[164:167], v[182:185], v[116:119]
	v_mfma_f32_16x16x32_bf16 v[112:115], v[172:175], v[182:185], v[112:115]
	v_mfma_f32_16x16x32_bf16 v[100:103], v[164:167], v[190:193], v[100:103]
	v_mfma_f32_16x16x32_bf16 v[96:99], v[172:175], v[190:193], v[96:99]
	v_mfma_f32_16x16x32_bf16 v[84:87], v[164:167], v[198:201], v[84:87]
	v_mfma_f32_16x16x32_bf16 v[80:83], v[172:175], v[198:201], v[80:83]
	v_mfma_f32_16x16x32_bf16 v[68:71], v[164:167], v[206:209], v[68:71]
	v_mfma_f32_16x16x32_bf16 v[64:67], v[172:175], v[206:209], v[64:67]
	v_mfma_f32_16x16x32_bf16 v[116:119], v[168:171], v[186:189], v[116:119]
	v_mfma_f32_16x16x32_bf16 v[112:115], v[178:181], v[186:189], v[112:115]
	v_mfma_f32_16x16x32_bf16 v[100:103], v[168:171], v[194:197], v[100:103]
	v_mfma_f32_16x16x32_bf16 v[96:99], v[178:181], v[194:197], v[96:99]
	v_mfma_f32_16x16x32_bf16 v[84:87], v[168:171], v[202:205], v[84:87]
	v_mfma_f32_16x16x32_bf16 v[80:83], v[178:181], v[202:205], v[80:83]
	v_mfma_f32_16x16x32_bf16 v[68:71], v[168:171], v[210:213], v[68:71]
	v_mfma_f32_16x16x32_bf16 v[64:67], v[178:181], v[210:213], v[64:67]
	s_barrier
	s_add_i32 s28, s33, s36
	v_lshl_add_u64 v[214:215], v[214:215], 0, s[12:13]
	s_mov_b32 m0, s28
	ds_read_b128 v[182:185], v146 offset:49152
	ds_read_b128 v[186:189], v146 offset:50176
	ds_read_b128 v[190:193], v146 offset:51200
	ds_read_b128 v[194:197], v146 offset:52224
	ds_read_b128 v[198:201], v146 offset:53248
	ds_read_b128 v[202:205], v146 offset:54272
	ds_read_b128 v[206:209], v146 offset:55296
	ds_read_b128 v[210:213], v146 offset:56320
	global_load_lds_dwordx4 v[214:215], off
	s_add_i32 m0, s28, 0x2000
	s_add_u32 s26, s26, 0x80080
	v_lshl_add_u64 v[214:215], v[216:217], 0, s[12:13]
	s_addc_u32 s27, s27, 0
	s_add_i32 s28, s51, s36
	global_load_lds_dwordx4 v[214:215], off
	v_lshl_add_u64 v[214:215], s[26:27], 0, v[128:129]
	s_mov_b32 m0, s28
	s_nop 0
	global_load_lds_dwordx4 v[214:215], off
	v_lshl_add_u64 v[214:215], s[26:27], 0, v[130:131]
	s_add_i32 m0, s28, 0x2000
	s_nop 0
	global_load_lds_dwordx4 v[214:215], off
	v_lshl_add_u64 v[214:215], v[218:219], 0, s[12:13]
	s_mov_b32 m0, s42
	s_nop 0
	global_load_lds_dwordx4 v[214:215], off
	v_lshl_add_u64 v[214:215], v[222:223], 0, s[12:13]
	s_mov_b32 m0, s43
	s_nop 0
	global_load_lds_dwordx4 v[214:215], off
	s_waitcnt vmcnt(8)
	s_waitcnt lgkmcnt(0)
	s_barrier
	v_mfma_f32_16x16x32_bf16 v[60:63], v[148:151], v[182:185], v[60:63]
	v_mfma_f32_16x16x32_bf16 v[56:59], v[156:159], v[182:185], v[56:59]
	v_mfma_f32_16x16x32_bf16 v[44:47], v[148:151], v[190:193], v[44:47]
	v_mfma_f32_16x16x32_bf16 v[40:43], v[156:159], v[190:193], v[40:43]
	v_mfma_f32_16x16x32_bf16 v[28:31], v[148:151], v[198:201], v[28:31]
	v_mfma_f32_16x16x32_bf16 v[24:27], v[156:159], v[198:201], v[24:27]
	v_mfma_f32_16x16x32_bf16 v[12:15], v[148:151], v[206:209], v[12:15]
	v_mfma_f32_16x16x32_bf16 v[8:11], v[156:159], v[206:209], v[8:11]
	v_mfma_f32_16x16x32_bf16 v[60:63], v[152:155], v[186:189], v[60:63]
	v_mfma_f32_16x16x32_bf16 v[56:59], v[160:163], v[186:189], v[56:59]
	v_mfma_f32_16x16x32_bf16 v[44:47], v[152:155], v[194:197], v[44:47]
	v_mfma_f32_16x16x32_bf16 v[40:43], v[160:163], v[194:197], v[40:43]
	v_mfma_f32_16x16x32_bf16 v[28:31], v[152:155], v[202:205], v[28:31]
	v_mfma_f32_16x16x32_bf16 v[24:27], v[160:163], v[202:205], v[24:27]
	v_mfma_f32_16x16x32_bf16 v[12:15], v[152:155], v[210:213], v[12:15]
	v_mfma_f32_16x16x32_bf16 v[8:11], v[160:163], v[210:213], v[8:11]
	v_mfma_f32_16x16x32_bf16 v[52:55], v[164:167], v[182:185], v[52:55]
	v_mfma_f32_16x16x32_bf16 v[48:51], v[172:175], v[182:185], v[48:51]
	v_mfma_f32_16x16x32_bf16 v[36:39], v[164:167], v[190:193], v[36:39]
	v_mfma_f32_16x16x32_bf16 v[32:35], v[172:175], v[190:193], v[32:35]
	v_mfma_f32_16x16x32_bf16 v[20:23], v[164:167], v[198:201], v[20:23]
	v_mfma_f32_16x16x32_bf16 v[16:19], v[172:175], v[198:201], v[16:19]
	v_mfma_f32_16x16x32_bf16 v[4:7], v[164:167], v[206:209], v[4:7]
	v_mfma_f32_16x16x32_bf16 v[0:3], v[172:175], v[206:209], v[0:3]
	v_mfma_f32_16x16x32_bf16 v[52:55], v[168:171], v[186:189], v[52:55]
	v_mfma_f32_16x16x32_bf16 v[48:51], v[178:181], v[186:189], v[48:51]
	v_mfma_f32_16x16x32_bf16 v[36:39], v[168:171], v[194:197], v[36:39]
	v_mfma_f32_16x16x32_bf16 v[32:35], v[178:181], v[194:197], v[32:35]
	v_mfma_f32_16x16x32_bf16 v[20:23], v[168:171], v[202:205], v[20:23]
	v_mfma_f32_16x16x32_bf16 v[16:19], v[178:181], v[202:205], v[16:19]
	v_mfma_f32_16x16x32_bf16 v[4:7], v[168:171], v[210:213], v[4:7]
	v_mfma_f32_16x16x32_bf16 v[0:3], v[178:181], v[210:213], v[0:3]
	s_barrier
	s_add_i32 s50, s50, 2
	s_add_u32 s24, s24, 0x100
	s_addc_u32 s25, s25, 0
	s_cmp_gt_u32 s50, 29
	s_cbranch_scc0 .LBB0_625
	s_add_u32 s24, s21, 0xffffff00
	s_addc_u32 s25, s47, -1
	s_andn2_b64 vcc, exec, s[2:3]
	s_cbranch_vccnz .LBB0_628
	v_mov_b32_e32 v0, 0
	s_mov_b32 s31, s14
	s_mov_b32 s6, s16
	s_mov_b64 s[10:11], s[22:23]
	s_mov_b32 s44, s20
	v_mov_b32_e32 v1, v0
	v_mov_b32_e32 v2, v0
	v_mov_b32_e32 v3, v0
	v_mov_b32_e32 v4, v0
	v_mov_b32_e32 v5, v0
	v_mov_b32_e32 v6, v0
	v_mov_b32_e32 v7, v0
	v_mov_b32_e32 v16, v0
	v_mov_b32_e32 v17, v0
	v_mov_b32_e32 v18, v0
	v_mov_b32_e32 v19, v0
	v_mov_b32_e32 v20, v0
	v_mov_b32_e32 v21, v0
	v_mov_b32_e32 v22, v0
	v_mov_b32_e32 v23, v0
	v_mov_b32_e32 v32, v0
	v_mov_b32_e32 v33, v0
	v_mov_b32_e32 v34, v0
	v_mov_b32_e32 v35, v0
	v_mov_b32_e32 v36, v0
	v_mov_b32_e32 v37, v0
	v_mov_b32_e32 v38, v0
	v_mov_b32_e32 v39, v0
	v_mov_b32_e32 v48, v0
	v_mov_b32_e32 v49, v0
	v_mov_b32_e32 v50, v0
	v_mov_b32_e32 v51, v0
	v_mov_b32_e32 v52, v0
	v_mov_b32_e32 v53, v0
	v_mov_b32_e32 v54, v0
	v_mov_b32_e32 v55, v0
	v_mov_b32_e32 v8, v0
	v_mov_b32_e32 v9, v0
	v_mov_b32_e32 v10, v0
	v_mov_b32_e32 v11, v0
	v_mov_b32_e32 v12, v0
	v_mov_b32_e32 v13, v0
	v_mov_b32_e32 v14, v0
	v_mov_b32_e32 v15, v0
	v_mov_b32_e32 v24, v0
	v_mov_b32_e32 v25, v0
	v_mov_b32_e32 v26, v0
	v_mov_b32_e32 v27, v0
	v_mov_b32_e32 v28, v0
	v_mov_b32_e32 v29, v0
	v_mov_b32_e32 v30, v0
	v_mov_b32_e32 v31, v0
	v_mov_b32_e32 v40, v0
	v_mov_b32_e32 v41, v0
	v_mov_b32_e32 v42, v0
	v_mov_b32_e32 v43, v0
	v_mov_b32_e32 v44, v0
	v_mov_b32_e32 v45, v0
	v_mov_b32_e32 v46, v0
	v_mov_b32_e32 v47, v0
	v_mov_b32_e32 v56, v0
	v_mov_b32_e32 v57, v0
	v_mov_b32_e32 v58, v0
	v_mov_b32_e32 v59, v0
	v_mov_b32_e32 v60, v0
	v_mov_b32_e32 v61, v0
	v_mov_b32_e32 v62, v0
	v_mov_b32_e32 v63, v0
	v_mov_b32_e32 v64, v0
	v_mov_b32_e32 v65, v0
	v_mov_b32_e32 v66, v0
	v_mov_b32_e32 v67, v0
	v_mov_b32_e32 v68, v0
	v_mov_b32_e32 v69, v0
	v_mov_b32_e32 v70, v0
	v_mov_b32_e32 v71, v0
	v_mov_b32_e32 v80, v0
	v_mov_b32_e32 v81, v0
	v_mov_b32_e32 v82, v0
	v_mov_b32_e32 v83, v0
	v_mov_b32_e32 v84, v0
	v_mov_b32_e32 v85, v0
	v_mov_b32_e32 v86, v0
	v_mov_b32_e32 v87, v0
	v_mov_b32_e32 v96, v0
	v_mov_b32_e32 v97, v0
	v_mov_b32_e32 v98, v0
	v_mov_b32_e32 v99, v0
	v_mov_b32_e32 v100, v0
	v_mov_b32_e32 v101, v0
	v_mov_b32_e32 v102, v0
	v_mov_b32_e32 v103, v0
	v_mov_b32_e32 v112, v0
	v_mov_b32_e32 v113, v0
	v_mov_b32_e32 v114, v0
	v_mov_b32_e32 v115, v0
	v_mov_b32_e32 v116, v0
	v_mov_b32_e32 v117, v0
	v_mov_b32_e32 v118, v0
	v_mov_b32_e32 v119, v0
	v_mov_b32_e32 v72, v0
	v_mov_b32_e32 v73, v0
	v_mov_b32_e32 v74, v0
	v_mov_b32_e32 v75, v0
	v_mov_b32_e32 v76, v0
	v_mov_b32_e32 v77, v0
	v_mov_b32_e32 v78, v0
	v_mov_b32_e32 v79, v0
	v_mov_b32_e32 v88, v0
	v_mov_b32_e32 v89, v0
	v_mov_b32_e32 v90, v0
	v_mov_b32_e32 v91, v0
	v_mov_b32_e32 v92, v0
	v_mov_b32_e32 v93, v0
	v_mov_b32_e32 v94, v0
	v_mov_b32_e32 v95, v0
	v_mov_b32_e32 v104, v0
	v_mov_b32_e32 v105, v0
	v_mov_b32_e32 v106, v0
	v_mov_b32_e32 v107, v0
	v_mov_b32_e32 v108, v0
	v_mov_b32_e32 v109, v0
	v_mov_b32_e32 v110, v0
	v_mov_b32_e32 v111, v0
	v_mov_b32_e32 v120, v0
	v_mov_b32_e32 v121, v0
	v_mov_b32_e32 v122, v0
	v_mov_b32_e32 v123, v0
	v_mov_b32_e32 v124, v0
	v_mov_b32_e32 v125, v0
	v_mov_b32_e32 v126, v0
	v_mov_b32_e32 v127, v0
	s_andn2_b64 vcc, exec, s[0:1]
	s_cbranch_vccnz .LBB0_629
	s_branch .LBB0_630

.LBB0_715:
	ds_read_b128 v[150:153], v147
	ds_read_b128 v[154:157], v147 offset:1024
	ds_read_b128 v[158:161], v147 offset:2048
	ds_read_b128 v[162:165], v147 offset:3072
	ds_read_b128 v[166:169], v148
	ds_read_b128 v[170:173], v148 offset:1024
	ds_read_b128 v[174:177], v148 offset:2048
	ds_read_b128 v[178:181], v148 offset:3072
	s_add_u32 s26, s24, 0xfff80080
	s_addc_u32 s27, s25, -1
	s_cmp_eq_u32 s51, 28
	s_cselect_b32 s29, s17, s27
	s_cselect_b32 s28, s47, s26
	s_cselect_b32 s27, s15, s50
	s_cselect_b32 s26, s48, s49
	v_lshl_add_u64 v[214:215], s[24:25], 0, v[136:137]
	s_add_i32 m0, s23, 0xc000
	ds_read_b128 v[182:185], v149
	ds_read_b128 v[186:189], v149 offset:1024
	ds_read_b128 v[190:193], v149 offset:2048
	ds_read_b128 v[194:197], v149 offset:3072
	ds_read_b128 v[198:201], v149 offset:4096
	ds_read_b128 v[202:205], v149 offset:5120
	ds_read_b128 v[206:209], v149 offset:6144
	ds_read_b128 v[210:213], v149 offset:7168
	global_load_lds_dwordx4 v[214:215], off
	v_lshl_add_u64 v[214:215], s[24:25], 0, v[138:139]
	s_add_i32 m0, s23, 0xe000
	s_nop 0
	global_load_lds_dwordx4 v[214:215], off
	s_waitcnt vmcnt(8)
	s_waitcnt lgkmcnt(0)
	s_barrier
	v_mfma_f32_16x16x32_bf16 v[124:127], v[150:153], v[182:185], v[124:127]
	v_mfma_f32_16x16x32_bf16 v[120:123], v[158:161], v[182:185], v[120:123]
	v_mfma_f32_16x16x32_bf16 v[108:111], v[150:153], v[190:193], v[108:111]
	v_mfma_f32_16x16x32_bf16 v[104:107], v[158:161], v[190:193], v[104:107]
	v_mfma_f32_16x16x32_bf16 v[92:95], v[150:153], v[198:201], v[92:95]
	v_mfma_f32_16x16x32_bf16 v[88:91], v[158:161], v[198:201], v[88:91]
	v_mfma_f32_16x16x32_bf16 v[76:79], v[150:153], v[206:209], v[76:79]
	v_mfma_f32_16x16x32_bf16 v[72:75], v[158:161], v[206:209], v[72:75]
	v_mfma_f32_16x16x32_bf16 v[124:127], v[154:157], v[186:189], v[124:127]
	v_mfma_f32_16x16x32_bf16 v[120:123], v[162:165], v[186:189], v[120:123]
	v_mfma_f32_16x16x32_bf16 v[108:111], v[154:157], v[194:197], v[108:111]
	v_mfma_f32_16x16x32_bf16 v[104:107], v[162:165], v[194:197], v[104:107]
	v_mfma_f32_16x16x32_bf16 v[92:95], v[154:157], v[202:205], v[92:95]
	v_mfma_f32_16x16x32_bf16 v[88:91], v[162:165], v[202:205], v[88:91]
	v_mfma_f32_16x16x32_bf16 v[76:79], v[154:157], v[210:213], v[76:79]
	v_mfma_f32_16x16x32_bf16 v[72:75], v[162:165], v[210:213], v[72:75]
	v_mfma_f32_16x16x32_bf16 v[116:119], v[166:169], v[182:185], v[116:119]
	v_mfma_f32_16x16x32_bf16 v[112:115], v[174:177], v[182:185], v[112:115]
	v_mfma_f32_16x16x32_bf16 v[100:103], v[166:169], v[190:193], v[100:103]
	v_mfma_f32_16x16x32_bf16 v[96:99], v[174:177], v[190:193], v[96:99]
	v_mfma_f32_16x16x32_bf16 v[84:87], v[166:169], v[198:201], v[84:87]
	v_mfma_f32_16x16x32_bf16 v[80:83], v[174:177], v[198:201], v[80:83]
	v_mfma_f32_16x16x32_bf16 v[68:71], v[166:169], v[206:209], v[68:71]
	v_mfma_f32_16x16x32_bf16 v[64:67], v[174:177], v[206:209], v[64:67]
	v_mfma_f32_16x16x32_bf16 v[116:119], v[170:173], v[186:189], v[116:119]
	v_mfma_f32_16x16x32_bf16 v[112:115], v[178:181], v[186:189], v[112:115]
	v_mfma_f32_16x16x32_bf16 v[100:103], v[170:173], v[194:197], v[100:103]
	v_mfma_f32_16x16x32_bf16 v[96:99], v[178:181], v[194:197], v[96:99]
	v_mfma_f32_16x16x32_bf16 v[84:87], v[170:173], v[202:205], v[84:87]
	v_mfma_f32_16x16x32_bf16 v[80:83], v[178:181], v[202:205], v[80:83]
	v_mfma_f32_16x16x32_bf16 v[68:71], v[170:173], v[210:213], v[68:71]
	v_mfma_f32_16x16x32_bf16 v[64:67], v[178:181], v[210:213], v[64:67]
	s_barrier
	s_add_i32 s33, s43, s31
	v_lshl_add_u64 v[214:215], s[26:27], 0, v[132:133]
	s_mov_b32 m0, s33
	ds_read_b128 v[182:185], v149 offset:16384
	ds_read_b128 v[186:189], v149 offset:17408
	ds_read_b128 v[190:193], v149 offset:18432
	ds_read_b128 v[194:197], v149 offset:19456
	ds_read_b128 v[198:201], v149 offset:20480
	ds_read_b128 v[202:205], v149 offset:21504
	ds_read_b128 v[206:209], v149 offset:22528
	ds_read_b128 v[210:213], v149 offset:23552
	global_load_lds_dwordx4 v[214:215], off
	s_add_i32 m0, s33, 0x2000
	s_add_u32 s52, s26, 0x80000
	v_lshl_add_u64 v[216:217], s[26:27], 0, v[128:129]
	s_addc_u32 s53, s27, 0
	s_add_i32 s33, s44, s31
	global_load_lds_dwordx4 v[216:217], off
	v_lshl_add_u64 v[218:219], s[52:53], 0, v[132:133]
	s_mov_b32 m0, s33
	v_lshl_add_u64 v[222:223], s[28:29], 0, v[130:131]
	global_load_lds_dwordx4 v[218:219], off
	v_lshl_add_u64 v[218:219], s[52:53], 0, v[128:129]
	s_add_i32 m0, s33, 0x2000
	s_nop 0
	global_load_lds_dwordx4 v[218:219], off
	v_lshl_add_u64 v[218:219], s[28:29], 0, v[134:135]
	s_mov_b32 m0, s23
	s_nop 0
	global_load_lds_dwordx4 v[218:219], off
	s_mov_b32 m0, s36
	s_nop 0
	global_load_lds_dwordx4 v[222:223], off
	s_waitcnt vmcnt(8)
	s_waitcnt lgkmcnt(0)
	s_barrier
	v_mfma_f32_16x16x32_bf16 v[60:63], v[150:153], v[182:185], v[60:63]
	v_mfma_f32_16x16x32_bf16 v[56:59], v[158:161], v[182:185], v[56:59]
	v_mfma_f32_16x16x32_bf16 v[44:47], v[150:153], v[190:193], v[44:47]
	v_mfma_f32_16x16x32_bf16 v[40:43], v[158:161], v[190:193], v[40:43]
	v_mfma_f32_16x16x32_bf16 v[28:31], v[150:153], v[198:201], v[28:31]
	v_mfma_f32_16x16x32_bf16 v[24:27], v[158:161], v[198:201], v[24:27]
	v_mfma_f32_16x16x32_bf16 v[12:15], v[150:153], v[206:209], v[12:15]
	v_mfma_f32_16x16x32_bf16 v[8:11], v[158:161], v[206:209], v[8:11]
	v_mfma_f32_16x16x32_bf16 v[60:63], v[154:157], v[186:189], v[60:63]
	v_mfma_f32_16x16x32_bf16 v[56:59], v[162:165], v[186:189], v[56:59]
	v_mfma_f32_16x16x32_bf16 v[44:47], v[154:157], v[194:197], v[44:47]
	v_mfma_f32_16x16x32_bf16 v[40:43], v[162:165], v[194:197], v[40:43]
	v_mfma_f32_16x16x32_bf16 v[28:31], v[154:157], v[202:205], v[28:31]
	v_mfma_f32_16x16x32_bf16 v[24:27], v[162:165], v[202:205], v[24:27]
	v_mfma_f32_16x16x32_bf16 v[12:15], v[154:157], v[210:213], v[12:15]
	v_mfma_f32_16x16x32_bf16 v[8:11], v[162:165], v[210:213], v[8:11]
	v_mfma_f32_16x16x32_bf16 v[52:55], v[166:169], v[182:185], v[52:55]
	v_mfma_f32_16x16x32_bf16 v[48:51], v[174:177], v[182:185], v[48:51]
	v_mfma_f32_16x16x32_bf16 v[36:39], v[166:169], v[190:193], v[36:39]
	v_mfma_f32_16x16x32_bf16 v[32:35], v[174:177], v[190:193], v[32:35]
	v_mfma_f32_16x16x32_bf16 v[20:23], v[166:169], v[198:201], v[20:23]
	v_mfma_f32_16x16x32_bf16 v[16:19], v[174:177], v[198:201], v[16:19]
	v_mfma_f32_16x16x32_bf16 v[4:7], v[166:169], v[206:209], v[4:7]
	v_mfma_f32_16x16x32_bf16 v[0:3], v[174:177], v[206:209], v[0:3]
	v_mfma_f32_16x16x32_bf16 v[52:55], v[170:173], v[186:189], v[52:55]
	v_mfma_f32_16x16x32_bf16 v[48:51], v[178:181], v[186:189], v[48:51]
	v_mfma_f32_16x16x32_bf16 v[36:39], v[170:173], v[194:197], v[36:39]
	v_mfma_f32_16x16x32_bf16 v[32:35], v[178:181], v[194:197], v[32:35]
	v_mfma_f32_16x16x32_bf16 v[20:23], v[170:173], v[202:205], v[20:23]
	v_mfma_f32_16x16x32_bf16 v[16:19], v[178:181], v[202:205], v[16:19]
	v_mfma_f32_16x16x32_bf16 v[4:7], v[170:173], v[210:213], v[4:7]
	v_mfma_f32_16x16x32_bf16 v[0:3], v[178:181], v[210:213], v[0:3]
	s_barrier
	s_add_i32 s33, 0, 0x18000
	s_add_i32 s52, 0, 0x1c000
	v_add_u32_e32 v162, s33, v145
	v_add_u32_e32 v178, s52, v145
	ds_read_b128 v[150:153], v162
	ds_read_b128 v[154:157], v162 offset:1024
	ds_read_b128 v[158:161], v162 offset:2048
	ds_read_b128 v[162:165], v162 offset:3072
	ds_read_b128 v[166:169], v178
	ds_read_b128 v[170:173], v178 offset:1024
	ds_read_b128 v[174:177], v178 offset:2048
	ds_read_b128 v[178:181], v178 offset:3072
	s_add_u32 s28, s28, 0x80000
	s_addc_u32 s29, s29, 0
	s_mov_b32 m0, s37
	v_lshl_add_u64 v[224:225], s[28:29], 0, v[134:135]
	ds_read_b128 v[182:185], v149 offset:32768
	ds_read_b128 v[186:189], v149 offset:33792
	ds_read_b128 v[190:193], v149 offset:34816
	ds_read_b128 v[194:197], v149 offset:35840
	ds_read_b128 v[198:201], v149 offset:36864
	ds_read_b128 v[202:205], v149 offset:37888
	ds_read_b128 v[206:209], v149 offset:38912
	ds_read_b128 v[210:213], v149 offset:39936
	global_load_lds_dwordx4 v[224:225], off
	v_lshl_add_u64 v[224:225], s[28:29], 0, v[130:131]
	s_mov_b32 m0, s38
	s_nop 0
	global_load_lds_dwordx4 v[224:225], off
	s_waitcnt vmcnt(8)
	s_waitcnt lgkmcnt(0)
	s_barrier
	v_mfma_f32_16x16x32_bf16 v[124:127], v[150:153], v[182:185], v[124:127]
	v_mfma_f32_16x16x32_bf16 v[120:123], v[158:161], v[182:185], v[120:123]
	v_mfma_f32_16x16x32_bf16 v[108:111], v[150:153], v[190:193], v[108:111]
	v_mfma_f32_16x16x32_bf16 v[104:107], v[158:161], v[190:193], v[104:107]
	v_mfma_f32_16x16x32_bf16 v[92:95], v[150:153], v[198:201], v[92:95]
	v_mfma_f32_16x16x32_bf16 v[88:91], v[158:161], v[198:201], v[88:91]
	v_mfma_f32_16x16x32_bf16 v[76:79], v[150:153], v[206:209], v[76:79]
	v_mfma_f32_16x16x32_bf16 v[72:75], v[158:161], v[206:209], v[72:75]
	v_mfma_f32_16x16x32_bf16 v[124:127], v[154:157], v[186:189], v[124:127]
	v_mfma_f32_16x16x32_bf16 v[120:123], v[162:165], v[186:189], v[120:123]
	v_mfma_f32_16x16x32_bf16 v[108:111], v[154:157], v[194:197], v[108:111]
	v_mfma_f32_16x16x32_bf16 v[104:107], v[162:165], v[194:197], v[104:107]
	v_mfma_f32_16x16x32_bf16 v[92:95], v[154:157], v[202:205], v[92:95]
	v_mfma_f32_16x16x32_bf16 v[88:91], v[162:165], v[202:205], v[88:91]
	v_mfma_f32_16x16x32_bf16 v[76:79], v[154:157], v[210:213], v[76:79]
	v_mfma_f32_16x16x32_bf16 v[72:75], v[162:165], v[210:213], v[72:75]
	v_mfma_f32_16x16x32_bf16 v[116:119], v[166:169], v[182:185], v[116:119]
	v_mfma_f32_16x16x32_bf16 v[112:115], v[174:177], v[182:185], v[112:115]
	v_mfma_f32_16x16x32_bf16 v[100:103], v[166:169], v[190:193], v[100:103]
	v_mfma_f32_16x16x32_bf16 v[96:99], v[174:177], v[190:193], v[96:99]
	v_mfma_f32_16x16x32_bf16 v[84:87], v[166:169], v[198:201], v[84:87]
	v_mfma_f32_16x16x32_bf16 v[80:83], v[174:177], v[198:201], v[80:83]
	v_mfma_f32_16x16x32_bf16 v[68:71], v[166:169], v[206:209], v[68:71]
	v_mfma_f32_16x16x32_bf16 v[64:67], v[174:177], v[206:209], v[64:67]
	v_mfma_f32_16x16x32_bf16 v[116:119], v[170:173], v[186:189], v[116:119]
	v_mfma_f32_16x16x32_bf16 v[112:115], v[178:181], v[186:189], v[112:115]
	v_mfma_f32_16x16x32_bf16 v[100:103], v[170:173], v[194:197], v[100:103]
	v_mfma_f32_16x16x32_bf16 v[96:99], v[178:181], v[194:197], v[96:99]
	v_mfma_f32_16x16x32_bf16 v[84:87], v[170:173], v[202:205], v[84:87]
	v_mfma_f32_16x16x32_bf16 v[80:83], v[178:181], v[202:205], v[80:83]
	v_mfma_f32_16x16x32_bf16 v[68:71], v[170:173], v[210:213], v[68:71]
	v_mfma_f32_16x16x32_bf16 v[64:67], v[178:181], v[210:213], v[64:67]
	s_barrier
	s_add_i32 s28, s33, s31
	v_lshl_add_u64 v[214:215], v[214:215], 0, s[10:11]
	s_mov_b32 m0, s28
	ds_read_b128 v[182:185], v149 offset:49152
	ds_read_b128 v[186:189], v149 offset:50176
	ds_read_b128 v[190:193], v149 offset:51200
	ds_read_b128 v[194:197], v149 offset:52224
	ds_read_b128 v[198:201], v149 offset:53248
	ds_read_b128 v[202:205], v149 offset:54272
	ds_read_b128 v[206:209], v149 offset:55296
	ds_read_b128 v[210:213], v149 offset:56320
	global_load_lds_dwordx4 v[214:215], off
	s_add_i32 m0, s28, 0x2000
	s_add_u32 s26, s26, 0x80080
	v_lshl_add_u64 v[214:215], v[216:217], 0, s[10:11]
	s_addc_u32 s27, s27, 0
	s_add_i32 s28, s52, s31
	global_load_lds_dwordx4 v[214:215], off
	v_lshl_add_u64 v[214:215], s[26:27], 0, v[132:133]
	s_mov_b32 m0, s28
	s_nop 0
	global_load_lds_dwordx4 v[214:215], off
	v_lshl_add_u64 v[214:215], s[26:27], 0, v[128:129]
	s_add_i32 m0, s28, 0x2000
	s_nop 0
	global_load_lds_dwordx4 v[214:215], off
	v_lshl_add_u64 v[214:215], v[218:219], 0, s[10:11]
	s_mov_b32 m0, s40
	s_nop 0
	global_load_lds_dwordx4 v[214:215], off
	v_lshl_add_u64 v[214:215], v[222:223], 0, s[10:11]
	s_mov_b32 m0, s41
	s_nop 0
	global_load_lds_dwordx4 v[214:215], off
	s_waitcnt vmcnt(8)
	s_waitcnt lgkmcnt(0)
	s_barrier
	v_mfma_f32_16x16x32_bf16 v[60:63], v[150:153], v[182:185], v[60:63]
	v_mfma_f32_16x16x32_bf16 v[56:59], v[158:161], v[182:185], v[56:59]
	v_mfma_f32_16x16x32_bf16 v[44:47], v[150:153], v[190:193], v[44:47]
	v_mfma_f32_16x16x32_bf16 v[40:43], v[158:161], v[190:193], v[40:43]
	v_mfma_f32_16x16x32_bf16 v[28:31], v[150:153], v[198:201], v[28:31]
	v_mfma_f32_16x16x32_bf16 v[24:27], v[158:161], v[198:201], v[24:27]
	v_mfma_f32_16x16x32_bf16 v[12:15], v[150:153], v[206:209], v[12:15]
	v_mfma_f32_16x16x32_bf16 v[8:11], v[158:161], v[206:209], v[8:11]
	v_mfma_f32_16x16x32_bf16 v[60:63], v[154:157], v[186:189], v[60:63]
	v_mfma_f32_16x16x32_bf16 v[56:59], v[162:165], v[186:189], v[56:59]
	v_mfma_f32_16x16x32_bf16 v[44:47], v[154:157], v[194:197], v[44:47]
	v_mfma_f32_16x16x32_bf16 v[40:43], v[162:165], v[194:197], v[40:43]
	v_mfma_f32_16x16x32_bf16 v[28:31], v[154:157], v[202:205], v[28:31]
	v_mfma_f32_16x16x32_bf16 v[24:27], v[162:165], v[202:205], v[24:27]
	v_mfma_f32_16x16x32_bf16 v[12:15], v[154:157], v[210:213], v[12:15]
	v_mfma_f32_16x16x32_bf16 v[8:11], v[162:165], v[210:213], v[8:11]
	v_mfma_f32_16x16x32_bf16 v[52:55], v[166:169], v[182:185], v[52:55]
	v_mfma_f32_16x16x32_bf16 v[48:51], v[174:177], v[182:185], v[48:51]
	v_mfma_f32_16x16x32_bf16 v[36:39], v[166:169], v[190:193], v[36:39]
	v_mfma_f32_16x16x32_bf16 v[32:35], v[174:177], v[190:193], v[32:35]
	v_mfma_f32_16x16x32_bf16 v[20:23], v[166:169], v[198:201], v[20:23]
	v_mfma_f32_16x16x32_bf16 v[16:19], v[174:177], v[198:201], v[16:19]
	v_mfma_f32_16x16x32_bf16 v[4:7], v[166:169], v[206:209], v[4:7]
	v_mfma_f32_16x16x32_bf16 v[0:3], v[174:177], v[206:209], v[0:3]
	v_mfma_f32_16x16x32_bf16 v[52:55], v[170:173], v[186:189], v[52:55]
	v_mfma_f32_16x16x32_bf16 v[48:51], v[178:181], v[186:189], v[48:51]
	v_mfma_f32_16x16x32_bf16 v[36:39], v[170:173], v[194:197], v[36:39]
	v_mfma_f32_16x16x32_bf16 v[32:35], v[178:181], v[194:197], v[32:35]
	v_mfma_f32_16x16x32_bf16 v[20:23], v[170:173], v[202:205], v[20:23]
	v_mfma_f32_16x16x32_bf16 v[16:19], v[178:181], v[202:205], v[16:19]
	v_mfma_f32_16x16x32_bf16 v[4:7], v[170:173], v[210:213], v[4:7]
	v_mfma_f32_16x16x32_bf16 v[0:3], v[178:181], v[210:213], v[0:3]
	s_barrier
	s_add_i32 s51, s51, 2
	s_add_u32 s24, s24, 0x100
	s_addc_u32 s25, s25, 0
	s_add_u32 s49, s49, 0x100
	s_addc_u32 s50, s50, 0
	s_cmp_gt_u32 s51, 29
	s_cbranch_scc0 .LBB0_715
	s_and_b64 vcc, exec, s[12:13]
	s_cbranch_vccz .LBB0_718
	s_barrier

.LBB0_770:
	ds_read_b128 v[148:151], v145
	ds_read_b128 v[152:155], v145 offset:1024
	ds_read_b128 v[156:159], v145 offset:2048
	ds_read_b128 v[160:163], v145 offset:3072
	ds_read_b128 v[164:167], v146
	ds_read_b128 v[168:171], v146 offset:1024
	ds_read_b128 v[172:175], v146 offset:2048
	ds_read_b128 v[176:179], v146 offset:3072
	s_add_u32 s30, s28, 0xffea0080
	s_addc_u32 s31, s29, -1
	s_cmpk_eq_i32 s54, 0x54
	s_cselect_b32 s35, s5, s31
	s_cselect_b32 s34, s4, s30
	s_cselect_b32 s31, s27, s53
	s_cselect_b32 s30, s26, s52
	v_lshl_add_u64 v[140:141], s[28:29], 0, v[132:133]
	s_add_i32 m0, s38, 0xc000
	ds_read_b128 v[180:183], v147
	ds_read_b128 v[184:187], v147 offset:1024
	ds_read_b128 v[188:191], v147 offset:2048
	ds_read_b128 v[192:195], v147 offset:3072
	ds_read_b128 v[196:199], v147 offset:4096
	ds_read_b128 v[200:203], v147 offset:5120
	ds_read_b128 v[204:207], v147 offset:6144
	ds_read_b128 v[208:211], v147 offset:7168
	global_load_lds_dwordx4 v[140:141], off
	v_lshl_add_u64 v[140:141], s[28:29], 0, v[134:135]
	s_add_i32 m0, s38, 0xe000
	s_nop 0
	global_load_lds_dwordx4 v[140:141], off
	s_waitcnt vmcnt(8)
	s_waitcnt lgkmcnt(0)
	s_barrier
	v_mfma_f32_16x16x32_bf16 v[124:127], v[148:151], v[180:183], v[124:127]
	v_mfma_f32_16x16x32_bf16 v[120:123], v[156:159], v[180:183], v[120:123]
	v_mfma_f32_16x16x32_bf16 v[112:115], v[148:151], v[188:191], v[112:115]
	v_mfma_f32_16x16x32_bf16 v[104:107], v[156:159], v[188:191], v[104:107]
	v_mfma_f32_16x16x32_bf16 v[96:99], v[148:151], v[196:199], v[96:99]
	v_mfma_f32_16x16x32_bf16 v[88:91], v[156:159], v[196:199], v[88:91]
	v_mfma_f32_16x16x32_bf16 v[80:83], v[148:151], v[204:207], v[80:83]
	v_mfma_f32_16x16x32_bf16 v[72:75], v[156:159], v[204:207], v[72:75]
	v_mfma_f32_16x16x32_bf16 v[124:127], v[152:155], v[184:187], v[124:127]
	v_mfma_f32_16x16x32_bf16 v[120:123], v[160:163], v[184:187], v[120:123]
	v_mfma_f32_16x16x32_bf16 v[112:115], v[152:155], v[192:195], v[112:115]
	v_mfma_f32_16x16x32_bf16 v[104:107], v[160:163], v[192:195], v[104:107]
	v_mfma_f32_16x16x32_bf16 v[96:99], v[152:155], v[200:203], v[96:99]
	v_mfma_f32_16x16x32_bf16 v[88:91], v[160:163], v[200:203], v[88:91]
	v_mfma_f32_16x16x32_bf16 v[80:83], v[152:155], v[208:211], v[80:83]
	v_mfma_f32_16x16x32_bf16 v[72:75], v[160:163], v[208:211], v[72:75]
	v_mfma_f32_16x16x32_bf16 v[116:119], v[164:167], v[180:183], v[116:119]
	v_mfma_f32_16x16x32_bf16 v[108:111], v[172:175], v[180:183], v[108:111]
	v_mfma_f32_16x16x32_bf16 v[100:103], v[164:167], v[188:191], v[100:103]
	v_mfma_f32_16x16x32_bf16 v[92:95], v[172:175], v[188:191], v[92:95]
	v_mfma_f32_16x16x32_bf16 v[84:87], v[164:167], v[196:199], v[84:87]
	v_mfma_f32_16x16x32_bf16 v[76:79], v[172:175], v[196:199], v[76:79]
	v_mfma_f32_16x16x32_bf16 v[68:71], v[164:167], v[204:207], v[68:71]
	v_mfma_f32_16x16x32_bf16 v[64:67], v[172:175], v[204:207], v[64:67]
	v_mfma_f32_16x16x32_bf16 v[116:119], v[168:171], v[184:187], v[116:119]
	v_mfma_f32_16x16x32_bf16 v[108:111], v[176:179], v[184:187], v[108:111]
	v_mfma_f32_16x16x32_bf16 v[100:103], v[168:171], v[192:195], v[100:103]
	v_mfma_f32_16x16x32_bf16 v[92:95], v[176:179], v[192:195], v[92:95]
	v_mfma_f32_16x16x32_bf16 v[84:87], v[168:171], v[200:203], v[84:87]
	v_mfma_f32_16x16x32_bf16 v[76:79], v[176:179], v[200:203], v[76:79]
	v_mfma_f32_16x16x32_bf16 v[68:71], v[168:171], v[208:211], v[68:71]
	v_mfma_f32_16x16x32_bf16 v[64:67], v[176:179], v[208:211], v[64:67]
	s_barrier
	s_add_i32 s33, s63, s37
	v_lshl_add_u64 v[140:141], s[30:31], 0, v[128:129]
	s_mov_b32 m0, s33
	ds_read_b128 v[180:183], v147 offset:16384
	ds_read_b128 v[184:187], v147 offset:17408
	ds_read_b128 v[188:191], v147 offset:18432
	ds_read_b128 v[192:195], v147 offset:19456
	ds_read_b128 v[196:199], v147 offset:20480
	ds_read_b128 v[200:203], v147 offset:21504
	ds_read_b128 v[204:207], v147 offset:22528
	ds_read_b128 v[208:211], v147 offset:23552
	global_load_lds_dwordx4 v[140:141], off
	s_add_i32 m0, s33, 0x2000
	s_add_u32 s56, s30, 0x160000
	v_lshl_add_u64 v[212:213], s[30:31], 0, v[130:131]
	s_addc_u32 s57, s31, 0
	s_add_i32 s33, s64, s37
	global_load_lds_dwordx4 v[212:213], off
	v_lshl_add_u64 v[214:215], s[56:57], 0, v[128:129]
	s_mov_b32 m0, s33
	v_lshl_add_u64 v[216:217], s[34:35], 0, v[130:131]
	global_load_lds_dwordx4 v[214:215], off
	v_lshl_add_u64 v[214:215], s[56:57], 0, v[130:131]
	s_add_i32 m0, s33, 0x2000
	s_nop 0
	global_load_lds_dwordx4 v[214:215], off
	v_lshl_add_u64 v[214:215], s[34:35], 0, v[128:129]
	s_mov_b32 m0, s38
	s_nop 0
	global_load_lds_dwordx4 v[214:215], off
	s_mov_b32 m0, s39
	s_nop 0
	global_load_lds_dwordx4 v[216:217], off
	s_waitcnt vmcnt(8)
	s_waitcnt lgkmcnt(0)
	s_barrier
	v_mfma_f32_16x16x32_bf16 v[60:63], v[148:151], v[180:183], v[60:63]
	v_mfma_f32_16x16x32_bf16 v[56:59], v[156:159], v[180:183], v[56:59]
	v_mfma_f32_16x16x32_bf16 v[48:51], v[148:151], v[188:191], v[48:51]
	v_mfma_f32_16x16x32_bf16 v[40:43], v[156:159], v[188:191], v[40:43]
	v_mfma_f32_16x16x32_bf16 v[32:35], v[148:151], v[196:199], v[32:35]
	v_mfma_f32_16x16x32_bf16 v[24:27], v[156:159], v[196:199], v[24:27]
	v_mfma_f32_16x16x32_bf16 v[16:19], v[148:151], v[204:207], v[16:19]
	v_mfma_f32_16x16x32_bf16 v[8:11], v[156:159], v[204:207], v[8:11]
	v_mfma_f32_16x16x32_bf16 v[60:63], v[152:155], v[184:187], v[60:63]
	v_mfma_f32_16x16x32_bf16 v[56:59], v[160:163], v[184:187], v[56:59]
	v_mfma_f32_16x16x32_bf16 v[48:51], v[152:155], v[192:195], v[48:51]
	v_mfma_f32_16x16x32_bf16 v[40:43], v[160:163], v[192:195], v[40:43]
	v_mfma_f32_16x16x32_bf16 v[32:35], v[152:155], v[200:203], v[32:35]
	v_mfma_f32_16x16x32_bf16 v[24:27], v[160:163], v[200:203], v[24:27]
	v_mfma_f32_16x16x32_bf16 v[16:19], v[152:155], v[208:211], v[16:19]
	v_mfma_f32_16x16x32_bf16 v[8:11], v[160:163], v[208:211], v[8:11]
	v_mfma_f32_16x16x32_bf16 v[52:55], v[164:167], v[180:183], v[52:55]
	v_mfma_f32_16x16x32_bf16 v[44:47], v[172:175], v[180:183], v[44:47]
	v_mfma_f32_16x16x32_bf16 v[36:39], v[164:167], v[188:191], v[36:39]
	v_mfma_f32_16x16x32_bf16 v[28:31], v[172:175], v[188:191], v[28:31]
	v_mfma_f32_16x16x32_bf16 v[20:23], v[164:167], v[196:199], v[20:23]
	v_mfma_f32_16x16x32_bf16 v[12:15], v[172:175], v[196:199], v[12:15]
	v_mfma_f32_16x16x32_bf16 v[4:7], v[164:167], v[204:207], v[4:7]
	v_mfma_f32_16x16x32_bf16 v[0:3], v[172:175], v[204:207], v[0:3]
	v_mfma_f32_16x16x32_bf16 v[52:55], v[168:171], v[184:187], v[52:55]
	v_mfma_f32_16x16x32_bf16 v[44:47], v[176:179], v[184:187], v[44:47]
	v_mfma_f32_16x16x32_bf16 v[36:39], v[168:171], v[192:195], v[36:39]
	v_mfma_f32_16x16x32_bf16 v[28:31], v[176:179], v[192:195], v[28:31]
	v_mfma_f32_16x16x32_bf16 v[20:23], v[168:171], v[200:203], v[20:23]
	v_mfma_f32_16x16x32_bf16 v[12:15], v[176:179], v[200:203], v[12:15]
	v_mfma_f32_16x16x32_bf16 v[4:7], v[168:171], v[208:211], v[4:7]
	v_mfma_f32_16x16x32_bf16 v[0:3], v[176:179], v[208:211], v[0:3]
	s_barrier
	s_add_i32 s33, 0, 0x18000
	s_add_i32 s55, 0, 0x1c000
	v_add_u32_e32 v160, s33, v143
	v_add_u32_e32 v176, s55, v143
	ds_read_b128 v[148:151], v160
	ds_read_b128 v[152:155], v160 offset:1024
	ds_read_b128 v[156:159], v160 offset:2048
	ds_read_b128 v[160:163], v160 offset:3072
	ds_read_b128 v[164:167], v176
	ds_read_b128 v[168:171], v176 offset:1024
	ds_read_b128 v[172:175], v176 offset:2048
	ds_read_b128 v[176:179], v176 offset:3072
	s_add_u32 s34, s34, 0x160000
	s_addc_u32 s35, s35, 0
	s_mov_b32 m0, s40
	v_lshl_add_u64 v[218:219], s[34:35], 0, v[128:129]
	ds_read_b128 v[180:183], v147 offset:32768
	ds_read_b128 v[184:187], v147 offset:33792
	ds_read_b128 v[188:191], v147 offset:34816
	ds_read_b128 v[192:195], v147 offset:35840
	ds_read_b128 v[196:199], v147 offset:36864
	ds_read_b128 v[200:203], v147 offset:37888
	ds_read_b128 v[204:207], v147 offset:38912
	ds_read_b128 v[208:211], v147 offset:39936
	global_load_lds_dwordx4 v[218:219], off
	v_lshl_add_u64 v[218:219], s[34:35], 0, v[130:131]
	s_mov_b32 m0, s41
	s_nop 0
	global_load_lds_dwordx4 v[218:219], off
	s_waitcnt vmcnt(8)
	s_waitcnt lgkmcnt(0)
	s_barrier
	v_mfma_f32_16x16x32_bf16 v[124:127], v[148:151], v[180:183], v[124:127]
	v_mfma_f32_16x16x32_bf16 v[120:123], v[156:159], v[180:183], v[120:123]
	v_mfma_f32_16x16x32_bf16 v[112:115], v[148:151], v[188:191], v[112:115]
	v_mfma_f32_16x16x32_bf16 v[104:107], v[156:159], v[188:191], v[104:107]
	v_mfma_f32_16x16x32_bf16 v[96:99], v[148:151], v[196:199], v[96:99]
	v_mfma_f32_16x16x32_bf16 v[88:91], v[156:159], v[196:199], v[88:91]
	v_mfma_f32_16x16x32_bf16 v[80:83], v[148:151], v[204:207], v[80:83]
	v_mfma_f32_16x16x32_bf16 v[72:75], v[156:159], v[204:207], v[72:75]
	v_mfma_f32_16x16x32_bf16 v[124:127], v[152:155], v[184:187], v[124:127]
	v_mfma_f32_16x16x32_bf16 v[120:123], v[160:163], v[184:187], v[120:123]
	v_mfma_f32_16x16x32_bf16 v[112:115], v[152:155], v[192:195], v[112:115]
	v_mfma_f32_16x16x32_bf16 v[104:107], v[160:163], v[192:195], v[104:107]
	v_mfma_f32_16x16x32_bf16 v[96:99], v[152:155], v[200:203], v[96:99]
	v_mfma_f32_16x16x32_bf16 v[88:91], v[160:163], v[200:203], v[88:91]
	v_mfma_f32_16x16x32_bf16 v[80:83], v[152:155], v[208:211], v[80:83]
	v_mfma_f32_16x16x32_bf16 v[72:75], v[160:163], v[208:211], v[72:75]
	v_mfma_f32_16x16x32_bf16 v[116:119], v[164:167], v[180:183], v[116:119]
	v_mfma_f32_16x16x32_bf16 v[108:111], v[172:175], v[180:183], v[108:111]
	v_mfma_f32_16x16x32_bf16 v[100:103], v[164:167], v[188:191], v[100:103]
	v_mfma_f32_16x16x32_bf16 v[92:95], v[172:175], v[188:191], v[92:95]
	v_mfma_f32_16x16x32_bf16 v[84:87], v[164:167], v[196:199], v[84:87]
	v_mfma_f32_16x16x32_bf16 v[76:79], v[172:175], v[196:199], v[76:79]
	v_mfma_f32_16x16x32_bf16 v[68:71], v[164:167], v[204:207], v[68:71]
	v_mfma_f32_16x16x32_bf16 v[64:67], v[172:175], v[204:207], v[64:67]
	v_mfma_f32_16x16x32_bf16 v[116:119], v[168:171], v[184:187], v[116:119]
	v_mfma_f32_16x16x32_bf16 v[108:111], v[176:179], v[184:187], v[108:111]
	v_mfma_f32_16x16x32_bf16 v[100:103], v[168:171], v[192:195], v[100:103]
	v_mfma_f32_16x16x32_bf16 v[92:95], v[176:179], v[192:195], v[92:95]
	v_mfma_f32_16x16x32_bf16 v[84:87], v[168:171], v[200:203], v[84:87]
	v_mfma_f32_16x16x32_bf16 v[76:79], v[176:179], v[200:203], v[76:79]
	v_mfma_f32_16x16x32_bf16 v[68:71], v[168:171], v[208:211], v[68:71]
	v_mfma_f32_16x16x32_bf16 v[64:67], v[176:179], v[208:211], v[64:67]
	s_barrier
	s_add_i32 s33, s33, s37
	v_lshl_add_u64 v[140:141], v[140:141], 0, s[14:15]
	s_mov_b32 m0, s33
	ds_read_b128 v[180:183], v147 offset:49152
	ds_read_b128 v[184:187], v147 offset:50176
	ds_read_b128 v[188:191], v147 offset:51200
	ds_read_b128 v[192:195], v147 offset:52224
	ds_read_b128 v[196:199], v147 offset:53248
	ds_read_b128 v[200:203], v147 offset:54272
	ds_read_b128 v[204:207], v147 offset:55296
	ds_read_b128 v[208:211], v147 offset:56320
	global_load_lds_dwordx4 v[140:141], off
	s_add_i32 m0, s33, 0x2000
	s_add_u32 s30, s30, 0x160080
	v_lshl_add_u64 v[140:141], v[212:213], 0, s[14:15]
	s_addc_u32 s31, s31, 0
	s_add_i32 s33, s55, s37
	global_load_lds_dwordx4 v[140:141], off
	v_lshl_add_u64 v[140:141], s[30:31], 0, v[128:129]
	s_mov_b32 m0, s33
	s_nop 0
	global_load_lds_dwordx4 v[140:141], off
	v_lshl_add_u64 v[140:141], s[30:31], 0, v[130:131]
	s_add_i32 m0, s33, 0x2000
	s_nop 0
	global_load_lds_dwordx4 v[140:141], off
	v_lshl_add_u64 v[140:141], v[214:215], 0, s[14:15]
	s_mov_b32 m0, s43
	s_nop 0
	global_load_lds_dwordx4 v[140:141], off
	v_lshl_add_u64 v[140:141], v[216:217], 0, s[14:15]
	s_mov_b32 m0, s61
	s_nop 0
	global_load_lds_dwordx4 v[140:141], off
	s_waitcnt vmcnt(8)
	s_waitcnt lgkmcnt(0)
	s_barrier
	v_mfma_f32_16x16x32_bf16 v[60:63], v[148:151], v[180:183], v[60:63]
	v_mfma_f32_16x16x32_bf16 v[56:59], v[156:159], v[180:183], v[56:59]
	v_mfma_f32_16x16x32_bf16 v[48:51], v[148:151], v[188:191], v[48:51]
	v_mfma_f32_16x16x32_bf16 v[40:43], v[156:159], v[188:191], v[40:43]
	v_mfma_f32_16x16x32_bf16 v[32:35], v[148:151], v[196:199], v[32:35]
	v_mfma_f32_16x16x32_bf16 v[24:27], v[156:159], v[196:199], v[24:27]
	v_mfma_f32_16x16x32_bf16 v[16:19], v[148:151], v[204:207], v[16:19]
	v_mfma_f32_16x16x32_bf16 v[8:11], v[156:159], v[204:207], v[8:11]
	v_mfma_f32_16x16x32_bf16 v[60:63], v[152:155], v[184:187], v[60:63]
	v_mfma_f32_16x16x32_bf16 v[56:59], v[160:163], v[184:187], v[56:59]
	v_mfma_f32_16x16x32_bf16 v[48:51], v[152:155], v[192:195], v[48:51]
	v_mfma_f32_16x16x32_bf16 v[40:43], v[160:163], v[192:195], v[40:43]
	v_mfma_f32_16x16x32_bf16 v[32:35], v[152:155], v[200:203], v[32:35]
	v_mfma_f32_16x16x32_bf16 v[24:27], v[160:163], v[200:203], v[24:27]
	v_mfma_f32_16x16x32_bf16 v[16:19], v[152:155], v[208:211], v[16:19]
	v_mfma_f32_16x16x32_bf16 v[8:11], v[160:163], v[208:211], v[8:11]
	v_mfma_f32_16x16x32_bf16 v[52:55], v[164:167], v[180:183], v[52:55]
	v_mfma_f32_16x16x32_bf16 v[44:47], v[172:175], v[180:183], v[44:47]
	v_mfma_f32_16x16x32_bf16 v[36:39], v[164:167], v[188:191], v[36:39]
	v_mfma_f32_16x16x32_bf16 v[28:31], v[172:175], v[188:191], v[28:31]
	v_mfma_f32_16x16x32_bf16 v[20:23], v[164:167], v[196:199], v[20:23]
	v_mfma_f32_16x16x32_bf16 v[12:15], v[172:175], v[196:199], v[12:15]
	v_mfma_f32_16x16x32_bf16 v[4:7], v[164:167], v[204:207], v[4:7]
	v_mfma_f32_16x16x32_bf16 v[0:3], v[172:175], v[204:207], v[0:3]
	v_mfma_f32_16x16x32_bf16 v[52:55], v[168:171], v[184:187], v[52:55]
	v_mfma_f32_16x16x32_bf16 v[44:47], v[176:179], v[184:187], v[44:47]
	v_mfma_f32_16x16x32_bf16 v[36:39], v[168:171], v[192:195], v[36:39]
	v_mfma_f32_16x16x32_bf16 v[28:31], v[176:179], v[192:195], v[28:31]
	v_mfma_f32_16x16x32_bf16 v[20:23], v[168:171], v[200:203], v[20:23]
	v_mfma_f32_16x16x32_bf16 v[12:15], v[176:179], v[200:203], v[12:15]
	v_mfma_f32_16x16x32_bf16 v[4:7], v[168:171], v[208:211], v[4:7]
	v_mfma_f32_16x16x32_bf16 v[0:3], v[176:179], v[208:211], v[0:3]
	s_barrier
	s_add_i32 s54, s54, 2
	s_add_u32 s28, s28, 0x100
	s_addc_u32 s29, s29, 0
	s_add_u32 s52, s52, 0x100
	s_addc_u32 s53, s53, 0
	s_cmpk_gt_u32 s54, 0x55
	s_cbranch_scc0 .LBB0_770
	s_and_b64 vcc, exec, s[16:17]
	s_cbranch_vccz .LBB0_773
	s_barrier

.LBB0_798:
	v_add_u32_e32 v147, s43, v145
	ds_read_b128 v[148:151], v147
	ds_read_b128 v[152:155], v147 offset:1024
	ds_read_b128 v[156:159], v147 offset:2048
	ds_read_b128 v[160:163], v147 offset:3072
	v_add_u32_e32 v147, s44, v145
	s_add_u32 s22, s12, s20
	ds_read_b128 v[164:167], v147
	ds_read_b128 v[172:175], v147 offset:1024
	ds_read_b128 v[176:179], v147 offset:2048
	ds_read_b128 v[180:183], v147 offset:3072
	s_addc_u32 s23, s13, s21
	s_add_u32 s22, s22, 0x100
	s_addc_u32 s23, s23, 0
	s_add_u32 s33, s17, s20
	s_addc_u32 s49, s47, s21
	s_cmpk_eq_i32 s20, 0x2b00
	s_cselect_b32 s25, s19, s23
	s_cselect_b32 s24, s18, s22
	s_cselect_b32 s23, s7, s49
	s_cselect_b32 s22, s6, s33
	v_lshl_add_u64 v[168:169], v[140:141], 0, s[20:21]
	s_add_i32 m0, s35, 0xc000
	ds_read_b128 v[184:187], v146
	ds_read_b128 v[188:191], v146 offset:1024
	ds_read_b128 v[192:195], v146 offset:2048
	ds_read_b128 v[196:199], v146 offset:3072
	ds_read_b128 v[200:203], v146 offset:4096
	ds_read_b128 v[204:207], v146 offset:5120
	ds_read_b128 v[208:211], v146 offset:6144
	ds_read_b128 v[212:215], v146 offset:7168
	global_load_lds_dwordx4 v[168:169], off
	v_lshl_add_u64 v[168:169], v[142:143], 0, s[20:21]
	s_add_i32 m0, s35, 0xe000
	s_nop 0
	global_load_lds_dwordx4 v[168:169], off
	s_waitcnt vmcnt(8)
	s_waitcnt lgkmcnt(0)
	s_barrier
	v_mfma_f32_16x16x32_bf16 v[124:127], v[148:151], v[184:187], v[124:127]
	v_mfma_f32_16x16x32_bf16 v[120:123], v[156:159], v[184:187], v[120:123]
	v_mfma_f32_16x16x32_bf16 v[108:111], v[148:151], v[192:195], v[108:111]
	v_mfma_f32_16x16x32_bf16 v[104:107], v[156:159], v[192:195], v[104:107]
	v_mfma_f32_16x16x32_bf16 v[92:95], v[148:151], v[200:203], v[92:95]
	v_mfma_f32_16x16x32_bf16 v[88:91], v[156:159], v[200:203], v[88:91]
	v_mfma_f32_16x16x32_bf16 v[76:79], v[148:151], v[208:211], v[76:79]
	v_mfma_f32_16x16x32_bf16 v[72:75], v[156:159], v[208:211], v[72:75]
	v_mfma_f32_16x16x32_bf16 v[124:127], v[152:155], v[188:191], v[124:127]
	v_mfma_f32_16x16x32_bf16 v[120:123], v[160:163], v[188:191], v[120:123]
	v_mfma_f32_16x16x32_bf16 v[108:111], v[152:155], v[196:199], v[108:111]
	v_mfma_f32_16x16x32_bf16 v[104:107], v[160:163], v[196:199], v[104:107]
	v_mfma_f32_16x16x32_bf16 v[92:95], v[152:155], v[204:207], v[92:95]
	v_mfma_f32_16x16x32_bf16 v[88:91], v[160:163], v[204:207], v[88:91]
	v_mfma_f32_16x16x32_bf16 v[76:79], v[152:155], v[212:215], v[76:79]
	v_mfma_f32_16x16x32_bf16 v[72:75], v[160:163], v[212:215], v[72:75]
	v_mfma_f32_16x16x32_bf16 v[116:119], v[164:167], v[184:187], v[116:119]
	v_mfma_f32_16x16x32_bf16 v[112:115], v[176:179], v[184:187], v[112:115]
	v_mfma_f32_16x16x32_bf16 v[100:103], v[164:167], v[192:195], v[100:103]
	v_mfma_f32_16x16x32_bf16 v[96:99], v[176:179], v[192:195], v[96:99]
	v_mfma_f32_16x16x32_bf16 v[84:87], v[164:167], v[200:203], v[84:87]
	v_mfma_f32_16x16x32_bf16 v[80:83], v[176:179], v[200:203], v[80:83]
	v_mfma_f32_16x16x32_bf16 v[68:71], v[164:167], v[208:211], v[68:71]
	v_mfma_f32_16x16x32_bf16 v[64:67], v[176:179], v[208:211], v[64:67]
	v_mfma_f32_16x16x32_bf16 v[116:119], v[172:175], v[188:191], v[116:119]
	v_mfma_f32_16x16x32_bf16 v[112:115], v[180:183], v[188:191], v[112:115]
	v_mfma_f32_16x16x32_bf16 v[100:103], v[172:175], v[196:199], v[100:103]
	v_mfma_f32_16x16x32_bf16 v[96:99], v[180:183], v[196:199], v[96:99]
	v_mfma_f32_16x16x32_bf16 v[84:87], v[172:175], v[204:207], v[84:87]
	v_mfma_f32_16x16x32_bf16 v[80:83], v[180:183], v[204:207], v[80:83]
	v_mfma_f32_16x16x32_bf16 v[68:71], v[172:175], v[212:215], v[68:71]
	v_mfma_f32_16x16x32_bf16 v[64:67], v[180:183], v[212:215], v[64:67]
	s_barrier
	s_add_i32 s33, s43, s34
	v_lshl_add_u64 v[168:169], s[22:23], 0, v[128:129]
	s_mov_b32 m0, s33
	ds_read_b128 v[184:187], v146 offset:16384
	ds_read_b128 v[188:191], v146 offset:17408
	ds_read_b128 v[192:195], v146 offset:18432
	ds_read_b128 v[196:199], v146 offset:19456
	ds_read_b128 v[200:203], v146 offset:20480
	ds_read_b128 v[204:207], v146 offset:21504
	ds_read_b128 v[208:211], v146 offset:22528
	ds_read_b128 v[212:215], v146 offset:23552
	global_load_lds_dwordx4 v[168:169], off
	s_add_i32 m0, s33, 0x2000
	s_add_u32 s50, s22, 0x160000
	v_lshl_add_u64 v[216:217], s[22:23], 0, v[130:131]
	s_addc_u32 s51, s23, 0
	s_add_i32 s33, s44, s34
	global_load_lds_dwordx4 v[216:217], off
	v_lshl_add_u64 v[218:219], s[50:51], 0, v[128:129]
	s_mov_b32 m0, s33
	v_lshl_add_u64 v[222:223], s[24:25], 0, v[130:131]
	global_load_lds_dwordx4 v[218:219], off
	v_lshl_add_u64 v[218:219], s[50:51], 0, v[130:131]
	s_add_i32 m0, s33, 0x2000
	s_nop 0
	global_load_lds_dwordx4 v[218:219], off
	v_lshl_add_u64 v[218:219], s[24:25], 0, v[128:129]
	s_mov_b32 m0, s35
	s_nop 0
	global_load_lds_dwordx4 v[218:219], off
	s_mov_b32 m0, s37
	s_nop 0
	global_load_lds_dwordx4 v[222:223], off
	s_waitcnt vmcnt(8)
	s_waitcnt lgkmcnt(0)
	s_barrier
	v_mfma_f32_16x16x32_bf16 v[60:63], v[148:151], v[184:187], v[60:63]
	v_mfma_f32_16x16x32_bf16 v[56:59], v[156:159], v[184:187], v[56:59]
	v_mfma_f32_16x16x32_bf16 v[44:47], v[148:151], v[192:195], v[44:47]
	v_mfma_f32_16x16x32_bf16 v[40:43], v[156:159], v[192:195], v[40:43]
	v_mfma_f32_16x16x32_bf16 v[28:31], v[148:151], v[200:203], v[28:31]
	v_mfma_f32_16x16x32_bf16 v[24:27], v[156:159], v[200:203], v[24:27]
	v_mfma_f32_16x16x32_bf16 v[12:15], v[148:151], v[208:211], v[12:15]
	v_mfma_f32_16x16x32_bf16 v[8:11], v[156:159], v[208:211], v[8:11]
	v_mfma_f32_16x16x32_bf16 v[60:63], v[152:155], v[188:191], v[60:63]
	v_mfma_f32_16x16x32_bf16 v[56:59], v[160:163], v[188:191], v[56:59]
	v_mfma_f32_16x16x32_bf16 v[44:47], v[152:155], v[196:199], v[44:47]
	v_mfma_f32_16x16x32_bf16 v[40:43], v[160:163], v[196:199], v[40:43]
	v_mfma_f32_16x16x32_bf16 v[28:31], v[152:155], v[204:207], v[28:31]
	v_mfma_f32_16x16x32_bf16 v[24:27], v[160:163], v[204:207], v[24:27]
	v_mfma_f32_16x16x32_bf16 v[12:15], v[152:155], v[212:215], v[12:15]
	v_mfma_f32_16x16x32_bf16 v[8:11], v[160:163], v[212:215], v[8:11]
	v_mfma_f32_16x16x32_bf16 v[52:55], v[164:167], v[184:187], v[52:55]
	v_mfma_f32_16x16x32_bf16 v[48:51], v[176:179], v[184:187], v[48:51]
	v_mfma_f32_16x16x32_bf16 v[36:39], v[164:167], v[192:195], v[36:39]
	v_mfma_f32_16x16x32_bf16 v[32:35], v[176:179], v[192:195], v[32:35]
	v_mfma_f32_16x16x32_bf16 v[20:23], v[164:167], v[200:203], v[20:23]
	v_mfma_f32_16x16x32_bf16 v[16:19], v[176:179], v[200:203], v[16:19]
	v_mfma_f32_16x16x32_bf16 v[4:7], v[164:167], v[208:211], v[4:7]
	v_mfma_f32_16x16x32_bf16 v[0:3], v[176:179], v[208:211], v[0:3]
	v_mfma_f32_16x16x32_bf16 v[52:55], v[172:175], v[188:191], v[52:55]
	v_mfma_f32_16x16x32_bf16 v[48:51], v[180:183], v[188:191], v[48:51]
	v_mfma_f32_16x16x32_bf16 v[36:39], v[172:175], v[196:199], v[36:39]
	v_mfma_f32_16x16x32_bf16 v[32:35], v[180:183], v[196:199], v[32:35]
	v_mfma_f32_16x16x32_bf16 v[20:23], v[172:175], v[204:207], v[20:23]
	v_mfma_f32_16x16x32_bf16 v[16:19], v[180:183], v[204:207], v[16:19]
	v_mfma_f32_16x16x32_bf16 v[4:7], v[172:175], v[212:215], v[4:7]
	v_mfma_f32_16x16x32_bf16 v[0:3], v[180:183], v[212:215], v[0:3]
	s_barrier
	s_add_i32 s33, 0, 0x18000
	v_add_u32_e32 v147, s33, v145
	s_add_i32 s49, 0, 0x1c000
	ds_read_b128 v[148:151], v147
	ds_read_b128 v[152:155], v147 offset:1024
	ds_read_b128 v[156:159], v147 offset:2048
	ds_read_b128 v[160:163], v147 offset:3072
	v_add_u32_e32 v147, s49, v145
	ds_read_b128 v[164:167], v147
	ds_read_b128 v[172:175], v147 offset:1024
	ds_read_b128 v[176:179], v147 offset:2048
	ds_read_b128 v[180:183], v147 offset:3072
	s_add_u32 s24, s24, 0x160000
	s_addc_u32 s25, s25, 0
	s_mov_b32 m0, s38
	v_lshl_add_u64 v[224:225], s[24:25], 0, v[128:129]
	ds_read_b128 v[184:187], v146 offset:32768
	ds_read_b128 v[188:191], v146 offset:33792
	ds_read_b128 v[192:195], v146 offset:34816
	ds_read_b128 v[196:199], v146 offset:35840
	ds_read_b128 v[200:203], v146 offset:36864
	ds_read_b128 v[204:207], v146 offset:37888
	ds_read_b128 v[208:211], v146 offset:38912
	ds_read_b128 v[212:215], v146 offset:39936
	global_load_lds_dwordx4 v[224:225], off
	v_lshl_add_u64 v[224:225], s[24:25], 0, v[130:131]
	s_mov_b32 m0, s39
	s_nop 0
	global_load_lds_dwordx4 v[224:225], off
	s_waitcnt vmcnt(8)
	s_waitcnt lgkmcnt(0)
	s_barrier
	v_mfma_f32_16x16x32_bf16 v[124:127], v[148:151], v[184:187], v[124:127]
	v_mfma_f32_16x16x32_bf16 v[120:123], v[156:159], v[184:187], v[120:123]
	v_mfma_f32_16x16x32_bf16 v[108:111], v[148:151], v[192:195], v[108:111]
	v_mfma_f32_16x16x32_bf16 v[104:107], v[156:159], v[192:195], v[104:107]
	v_mfma_f32_16x16x32_bf16 v[92:95], v[148:151], v[200:203], v[92:95]
	v_mfma_f32_16x16x32_bf16 v[88:91], v[156:159], v[200:203], v[88:91]
	v_mfma_f32_16x16x32_bf16 v[76:79], v[148:151], v[208:211], v[76:79]
	v_mfma_f32_16x16x32_bf16 v[72:75], v[156:159], v[208:211], v[72:75]
	v_mfma_f32_16x16x32_bf16 v[124:127], v[152:155], v[188:191], v[124:127]
	v_mfma_f32_16x16x32_bf16 v[120:123], v[160:163], v[188:191], v[120:123]
	v_mfma_f32_16x16x32_bf16 v[108:111], v[152:155], v[196:199], v[108:111]
	v_mfma_f32_16x16x32_bf16 v[104:107], v[160:163], v[196:199], v[104:107]
	v_mfma_f32_16x16x32_bf16 v[92:95], v[152:155], v[204:207], v[92:95]
	v_mfma_f32_16x16x32_bf16 v[88:91], v[160:163], v[204:207], v[88:91]
	v_mfma_f32_16x16x32_bf16 v[76:79], v[152:155], v[212:215], v[76:79]
	v_mfma_f32_16x16x32_bf16 v[72:75], v[160:163], v[212:215], v[72:75]
	v_mfma_f32_16x16x32_bf16 v[116:119], v[164:167], v[184:187], v[116:119]
	v_mfma_f32_16x16x32_bf16 v[112:115], v[176:179], v[184:187], v[112:115]
	v_mfma_f32_16x16x32_bf16 v[100:103], v[164:167], v[192:195], v[100:103]
	v_mfma_f32_16x16x32_bf16 v[96:99], v[176:179], v[192:195], v[96:99]
	v_mfma_f32_16x16x32_bf16 v[84:87], v[164:167], v[200:203], v[84:87]
	v_mfma_f32_16x16x32_bf16 v[80:83], v[176:179], v[200:203], v[80:83]
	v_mfma_f32_16x16x32_bf16 v[68:71], v[164:167], v[208:211], v[68:71]
	v_mfma_f32_16x16x32_bf16 v[64:67], v[176:179], v[208:211], v[64:67]
	v_mfma_f32_16x16x32_bf16 v[116:119], v[172:175], v[188:191], v[116:119]
	v_mfma_f32_16x16x32_bf16 v[112:115], v[180:183], v[188:191], v[112:115]
	v_mfma_f32_16x16x32_bf16 v[100:103], v[172:175], v[196:199], v[100:103]
	v_mfma_f32_16x16x32_bf16 v[96:99], v[180:183], v[196:199], v[96:99]
	v_mfma_f32_16x16x32_bf16 v[84:87], v[172:175], v[204:207], v[84:87]
	v_mfma_f32_16x16x32_bf16 v[80:83], v[180:183], v[204:207], v[80:83]
	v_mfma_f32_16x16x32_bf16 v[68:71], v[172:175], v[212:215], v[68:71]
	v_mfma_f32_16x16x32_bf16 v[64:67], v[180:183], v[212:215], v[64:67]
	s_barrier
	s_add_i32 s24, s33, s34
	v_lshl_add_u64 v[168:169], v[168:169], 0, s[14:15]
	s_mov_b32 m0, s24
	ds_read_b128 v[184:187], v146 offset:49152
	ds_read_b128 v[188:191], v146 offset:50176
	ds_read_b128 v[192:195], v146 offset:51200
	ds_read_b128 v[196:199], v146 offset:52224
	ds_read_b128 v[200:203], v146 offset:53248
	ds_read_b128 v[204:207], v146 offset:54272
	ds_read_b128 v[208:211], v146 offset:55296
	ds_read_b128 v[212:215], v146 offset:56320
	global_load_lds_dwordx4 v[168:169], off
	s_add_i32 m0, s24, 0x2000
	s_add_u32 s22, s22, 0x160080
	v_lshl_add_u64 v[168:169], v[216:217], 0, s[14:15]
	s_addc_u32 s23, s23, 0
	s_add_i32 s24, s49, s34
	global_load_lds_dwordx4 v[168:169], off
	v_lshl_add_u64 v[168:169], s[22:23], 0, v[128:129]
	s_mov_b32 m0, s24
	s_nop 0
	global_load_lds_dwordx4 v[168:169], off
	v_lshl_add_u64 v[168:169], s[22:23], 0, v[130:131]
	s_add_i32 m0, s24, 0x2000
	s_nop 0
	global_load_lds_dwordx4 v[168:169], off
	v_lshl_add_u64 v[168:169], v[218:219], 0, s[14:15]
	s_mov_b32 m0, s40
	s_nop 0
	global_load_lds_dwordx4 v[168:169], off
	v_lshl_add_u64 v[168:169], v[222:223], 0, s[14:15]
	s_mov_b32 m0, s41
	s_nop 0
	global_load_lds_dwordx4 v[168:169], off
	s_waitcnt vmcnt(8)
	s_waitcnt lgkmcnt(0)
	s_barrier
	v_mfma_f32_16x16x32_bf16 v[60:63], v[148:151], v[184:187], v[60:63]
	v_mfma_f32_16x16x32_bf16 v[56:59], v[156:159], v[184:187], v[56:59]
	v_mfma_f32_16x16x32_bf16 v[44:47], v[148:151], v[192:195], v[44:47]
	v_mfma_f32_16x16x32_bf16 v[40:43], v[156:159], v[192:195], v[40:43]
	v_mfma_f32_16x16x32_bf16 v[28:31], v[148:151], v[200:203], v[28:31]
	v_mfma_f32_16x16x32_bf16 v[24:27], v[156:159], v[200:203], v[24:27]
	v_mfma_f32_16x16x32_bf16 v[12:15], v[148:151], v[208:211], v[12:15]
	v_mfma_f32_16x16x32_bf16 v[8:11], v[156:159], v[208:211], v[8:11]
	v_mfma_f32_16x16x32_bf16 v[60:63], v[152:155], v[188:191], v[60:63]
	v_mfma_f32_16x16x32_bf16 v[56:59], v[160:163], v[188:191], v[56:59]
	v_mfma_f32_16x16x32_bf16 v[44:47], v[152:155], v[196:199], v[44:47]
	v_mfma_f32_16x16x32_bf16 v[40:43], v[160:163], v[196:199], v[40:43]
	v_mfma_f32_16x16x32_bf16 v[28:31], v[152:155], v[204:207], v[28:31]
	v_mfma_f32_16x16x32_bf16 v[24:27], v[160:163], v[204:207], v[24:27]
	v_mfma_f32_16x16x32_bf16 v[12:15], v[152:155], v[212:215], v[12:15]
	v_mfma_f32_16x16x32_bf16 v[8:11], v[160:163], v[212:215], v[8:11]
	v_mfma_f32_16x16x32_bf16 v[52:55], v[164:167], v[184:187], v[52:55]
	v_mfma_f32_16x16x32_bf16 v[48:51], v[176:179], v[184:187], v[48:51]
	v_mfma_f32_16x16x32_bf16 v[36:39], v[164:167], v[192:195], v[36:39]
	v_mfma_f32_16x16x32_bf16 v[32:35], v[176:179], v[192:195], v[32:35]
	v_mfma_f32_16x16x32_bf16 v[20:23], v[164:167], v[200:203], v[20:23]
	v_mfma_f32_16x16x32_bf16 v[16:19], v[176:179], v[200:203], v[16:19]
	v_mfma_f32_16x16x32_bf16 v[4:7], v[164:167], v[208:211], v[4:7]
	v_mfma_f32_16x16x32_bf16 v[0:3], v[176:179], v[208:211], v[0:3]
	v_mfma_f32_16x16x32_bf16 v[52:55], v[172:175], v[188:191], v[52:55]
	v_mfma_f32_16x16x32_bf16 v[48:51], v[180:183], v[188:191], v[48:51]
	v_mfma_f32_16x16x32_bf16 v[36:39], v[172:175], v[196:199], v[36:39]
	v_mfma_f32_16x16x32_bf16 v[32:35], v[180:183], v[196:199], v[32:35]
	v_mfma_f32_16x16x32_bf16 v[20:23], v[172:175], v[204:207], v[20:23]
	v_mfma_f32_16x16x32_bf16 v[16:19], v[180:183], v[204:207], v[16:19]
	v_mfma_f32_16x16x32_bf16 v[4:7], v[172:175], v[212:215], v[4:7]
	v_mfma_f32_16x16x32_bf16 v[0:3], v[180:183], v[212:215], v[0:3]
	s_barrier
	s_add_i32 s48, s48, 2
	s_add_u32 s20, s20, 0x100
	s_addc_u32 s21, s21, 0
	s_cmpk_gt_u32 s48, 0x55
	s_cbranch_scc0 .LBB0_798
	s_add_u32 s20, s17, 0xffffff00
	s_addc_u32 s21, s47, -1
	s_and_b64 vcc, exec, s[4:5]
	s_cbranch_vccnz .LBB0_801
	v_mov_b32_e32 v0, 0
	s_mov_b32 s29, s45
	s_mov_b32 s26, s46
	s_mov_b64 s[12:13], s[18:19]
	s_mov_b32 s42, s16
	v_mov_b32_e32 v1, v0
	v_mov_b32_e32 v2, v0
	v_mov_b32_e32 v3, v0
	v_mov_b32_e32 v4, v0
	v_mov_b32_e32 v5, v0
	v_mov_b32_e32 v6, v0
	v_mov_b32_e32 v7, v0
	v_mov_b32_e32 v16, v0
	v_mov_b32_e32 v17, v0
	v_mov_b32_e32 v18, v0
	v_mov_b32_e32 v19, v0
	v_mov_b32_e32 v20, v0
	v_mov_b32_e32 v21, v0
	v_mov_b32_e32 v22, v0
	v_mov_b32_e32 v23, v0
	v_mov_b32_e32 v32, v0
	v_mov_b32_e32 v33, v0
	v_mov_b32_e32 v34, v0
	v_mov_b32_e32 v35, v0
	v_mov_b32_e32 v36, v0
	v_mov_b32_e32 v37, v0
	v_mov_b32_e32 v38, v0
	v_mov_b32_e32 v39, v0
	v_mov_b32_e32 v48, v0
	v_mov_b32_e32 v49, v0
	v_mov_b32_e32 v50, v0
	v_mov_b32_e32 v51, v0
	v_mov_b32_e32 v52, v0
	v_mov_b32_e32 v53, v0
	v_mov_b32_e32 v54, v0
	v_mov_b32_e32 v55, v0
	v_mov_b32_e32 v8, v0
	v_mov_b32_e32 v9, v0
	v_mov_b32_e32 v10, v0
	v_mov_b32_e32 v11, v0
	v_mov_b32_e32 v12, v0
	v_mov_b32_e32 v13, v0
	v_mov_b32_e32 v14, v0
	v_mov_b32_e32 v15, v0
	v_mov_b32_e32 v24, v0
	v_mov_b32_e32 v25, v0
	v_mov_b32_e32 v26, v0
	v_mov_b32_e32 v27, v0
	v_mov_b32_e32 v28, v0
	v_mov_b32_e32 v29, v0
	v_mov_b32_e32 v30, v0
	v_mov_b32_e32 v31, v0
	v_mov_b32_e32 v40, v0
	v_mov_b32_e32 v41, v0
	v_mov_b32_e32 v42, v0
	v_mov_b32_e32 v43, v0
	v_mov_b32_e32 v44, v0
	v_mov_b32_e32 v45, v0
	v_mov_b32_e32 v46, v0
	v_mov_b32_e32 v47, v0
	v_mov_b32_e32 v56, v0
	v_mov_b32_e32 v57, v0
	v_mov_b32_e32 v58, v0
	v_mov_b32_e32 v59, v0
	v_mov_b32_e32 v60, v0
	v_mov_b32_e32 v61, v0
	v_mov_b32_e32 v62, v0
	v_mov_b32_e32 v63, v0
	v_mov_b32_e32 v64, v0
	v_mov_b32_e32 v65, v0
	v_mov_b32_e32 v66, v0
	v_mov_b32_e32 v67, v0
	v_mov_b32_e32 v68, v0
	v_mov_b32_e32 v69, v0
	v_mov_b32_e32 v70, v0
	v_mov_b32_e32 v71, v0
	v_mov_b32_e32 v80, v0
	v_mov_b32_e32 v81, v0
	v_mov_b32_e32 v82, v0
	v_mov_b32_e32 v83, v0
	v_mov_b32_e32 v84, v0
	v_mov_b32_e32 v85, v0
	v_mov_b32_e32 v86, v0
	v_mov_b32_e32 v87, v0
	v_mov_b32_e32 v96, v0
	v_mov_b32_e32 v97, v0
	v_mov_b32_e32 v98, v0
	v_mov_b32_e32 v99, v0
	v_mov_b32_e32 v100, v0
	v_mov_b32_e32 v101, v0
	v_mov_b32_e32 v102, v0
	v_mov_b32_e32 v103, v0
	v_mov_b32_e32 v112, v0
	v_mov_b32_e32 v113, v0
	v_mov_b32_e32 v114, v0
	v_mov_b32_e32 v115, v0
	v_mov_b32_e32 v116, v0
	v_mov_b32_e32 v117, v0
	v_mov_b32_e32 v118, v0
	v_mov_b32_e32 v119, v0
	v_mov_b32_e32 v72, v0
	v_mov_b32_e32 v73, v0
	v_mov_b32_e32 v74, v0
	v_mov_b32_e32 v75, v0
	v_mov_b32_e32 v76, v0
	v_mov_b32_e32 v77, v0
	v_mov_b32_e32 v78, v0
	v_mov_b32_e32 v79, v0
	v_mov_b32_e32 v88, v0
	v_mov_b32_e32 v89, v0
	v_mov_b32_e32 v90, v0
	v_mov_b32_e32 v91, v0
	v_mov_b32_e32 v92, v0
	v_mov_b32_e32 v93, v0
	v_mov_b32_e32 v94, v0
	v_mov_b32_e32 v95, v0
	v_mov_b32_e32 v104, v0
	v_mov_b32_e32 v105, v0
	v_mov_b32_e32 v106, v0
	v_mov_b32_e32 v107, v0
	v_mov_b32_e32 v108, v0
	v_mov_b32_e32 v109, v0
	v_mov_b32_e32 v110, v0
	v_mov_b32_e32 v111, v0
	v_mov_b32_e32 v120, v0
	v_mov_b32_e32 v121, v0
	v_mov_b32_e32 v122, v0
	v_mov_b32_e32 v123, v0
	v_mov_b32_e32 v124, v0
	v_mov_b32_e32 v125, v0
	v_mov_b32_e32 v126, v0
	v_mov_b32_e32 v127, v0
	s_andn2_b64 vcc, exec, s[2:3]
	s_cbranch_vccnz .LBB0_802
	s_branch .LBB0_803
